# K-loops: per-segment s_setprio flips replaced by one static priority raise for waves 4-7 per tile
# baseline (speedup 1.0000x reference)
; #define PG8_STAGEA(bufoff, gbase, voff) PG8_STAGE_X(bufoff, gbase, voff, AUXA)
; #define PG8_STAGEB(bufoff, gbase, voff) PG8_STAGE_X(bufoff, gbase, voff, AUXB)
; #define PG8_LDA(dst, b, h) do { _Pragma("unroll") for (int m = 0; m < 4; ++m) _Pragma("unroll") for (int k = 0; k < 2; ++k) dst[m][k] = *(const PG8_LAS bf16x8*)(lds + PG8_SA(b, h) + aoff + m * 2048 + k * 1024); } while (0)
; #define PG8_LDB(dst, b, h) do { _Pragma("unroll") for (int n = 0; n < 2; ++n) _Pragma("unroll") for (int k = 0; k < 2; ++k) dst[n][k] = *(const PG8_LAS bf16x8*)(lds + PG8_SB(b, h) + boff + n * 2048 + k * 1024); } while (0)
; #define PG8_MMA(ai, bj, At, Bt) do { if (GEMM_PRIO_MODE == 0) __builtin_amdgcn_s_setprio(1); PG8_MMA_LOOPS \
;         acc[ai][bj][m][n] = __builtin_amdgcn_mfma_f32_16x16x32_bf16(Bt[n][k], At[m][k], acc[ai][bj][m][n], 0, 0, 0); if (GEMM_PRIO_MODE == 0) __builtin_amdgcn_s_setprio(0); } while (0)
; #define PG8_WAIT_V(n) asm volatile("s_waitcnt vmcnt(" #n ")" ::: "memory")
; #define PG8_WAIT_VR(n, nr, flag) asm volatile("s_cmp_eq_u32 %0, 0\n\ts_cbranch_scc1 .Lpg8s%=\n\ts_waitcnt vmcnt(" #nr ")\n\ts_branch .Lpg8d%=\n.Lpg8s%=:\n\ts_waitcnt vmcnt(" #n ")\n.Lpg8d%=:" :: "s"(flag) : "memory", "scc")
;     ...
;     if (GEMM_PRIO_MODE == 2 && wr == 1) __builtin_amdgcn_s_setprio(1);
;     ...
;         for (int t = t0; t < nt; t += 2) {
;             const bool last = (t == nt - 2);
;             const char* a1 = cA + (size_t)(t + 1) * kstepA;
;             const char* a2 = last ? nA : cA + (size_t)(t + 2) * kstepA; const char* b2 = last ? nB : cB + (size_t)(t + 2) * kstepB;
;             const char* a3 = a2 + kstepA; const char* b3 = b2 + kstepB;
;             if (last && has_next) S.a_ready(nxt);
;             if constexpr (SP2) {
;             PG8_LDB(B0, 0, 0); PG8_LDB(B1, 0, 1); PG8_SCHED; PG8_LDA(At, 0, 0); PG8_STAGEA(PG8_SA(1, 1), a1 + hstepA, voffA);
;     ...
;             const int relax = __builtin_amdgcn_readfirstlane((t == 0 && ui > 0) ? 1 : 0);
;             PG8_WAIT_VR(8, 24, relax); PG8_WAIT_L(0); PG8_BAR; PG8_MMA(0, 0, At, B0); PG8_MMA(0, 1, At, B1); PG8_BAR; PG8_SCHED;
;     ...
;             PG8_WAIT_V(8); PG8_WAIT_L(0); PG8_BAR; PG8_MMA(0, 0, At, B0); PG8_MMA(0, 1, At, B1); PG8_BAR; PG8_SCHED;
;     ...
;             PG8_LDA(At, 0, 1); PG8_STAGEB(PG8_SB(0, 0), b2, voffB); PG8_STAGEB(PG8_SB(0, 1), b2 + hstepB, voffB); PG8_STAGEA(PG8_SA(0, 0), a2, voffA);
.LBB0_128:
	s_ashr_i32 s37, s36, 31
	s_lshl_b64 s[4:5], s[36:37], 21
	s_add_u32 s38, s56, s4
	s_addc_u32 s39, s57, s5
	s_and_b64 s[4:5], s[6:7], exec
	s_cselect_b32 s4, s39, s1
	s_cselect_b32 s5, s38, s0
	s_ashr_i32 s27, s26, 31
	s_lshl_b64 s[8:9], s[26:27], 21
	s_add_u32 s40, s43, s8
	s_addc_u32 s41, s50, s9
	s_and_b64 s[8:9], s[6:7], exec
	s_cselect_b32 s16, s41, s11
	s_cselect_b32 s17, s40, s10
	s_add_u32 s8, s0, 0x100080
	s_addc_u32 s9, s1, 0
	s_add_u32 s0, s10, 0x100
	s_addc_u32 s1, s11, 0
	s_mov_b32 s27, -2
	s_and_b64 vcc, exec, s[24:25]
	s_cbranch_vccnz .Lsprio_g1
	s_setprio 1
.Lsprio_g1:
	s_add_u32 s10, s8, 0xfff00080
	s_addc_u32 s11, s9, -1
	s_add_i32 s18, 0, 0x10000
	s_cmp_eq_u32 s27, 60
	s_cselect_b32 s15, s4, s11
	s_cselect_b32 s14, s5, s10
	v_add_u32_e32 v16, s18, v167
	s_cselect_b32 s11, s16, s1
	s_cselect_b32 s10, s17, s0
	s_add_i32 s20, 0, 0x14000
	s_waitcnt lgkmcnt(0)
	ds_read_b128 v[130:133], v16
	ds_read_b128 v[134:137], v16 offset:1024
	ds_read_b128 v[152:155], v16 offset:2048
	ds_read_b128 v[156:159], v16 offset:3072
	v_add_u32_e32 v16, s20, v167
	ds_read_b128 v[160:163], v16
	ds_read_b128 v[174:177], v16 offset:1024
	ds_read_b128 v[178:181], v16 offset:2048
	ds_read_b128 v[182:185], v16 offset:3072
	v_lshl_add_u64 v[164:165], s[8:9], 0, v[148:149]
	s_add_i32 m0, s51, 0xc000
	ds_read_b128 v[186:189], v172
	ds_read_b128 v[190:193], v172 offset:1024
	ds_read_b128 v[194:197], v172 offset:2048
	ds_read_b128 v[198:201], v172 offset:3072
	ds_read_b128 v[202:205], v172 offset:4096
	ds_read_b128 v[206:209], v172 offset:5120
	ds_read_b128 v[210:213], v172 offset:6144
	ds_read_b128 v[214:217], v172 offset:7168
	global_load_lds_dwordx4 v[164:165], off
	v_lshl_add_u64 v[164:165], s[8:9], 0, v[150:151]
	s_add_i32 m0, s51, 0xe000
	s_nop 0
	global_load_lds_dwordx4 v[164:165], off
	s_waitcnt vmcnt(8)
	s_waitcnt lgkmcnt(0)
	s_barrier
	v_mfma_f32_16x16x32_bf16 v[126:129], v[130:133], v[186:189], 0
	v_mfma_f32_16x16x32_bf16 v[122:125], v[152:155], v[186:189], 0
	v_mfma_f32_16x16x32_bf16 v[110:113], v[130:133], v[194:197], 0
	v_mfma_f32_16x16x32_bf16 v[106:109], v[152:155], v[194:197], 0
	v_mfma_f32_16x16x32_bf16 v[94:97], v[130:133], v[202:205], 0
	v_mfma_f32_16x16x32_bf16 v[90:93], v[152:155], v[202:205], 0
	v_mfma_f32_16x16x32_bf16 v[78:81], v[130:133], v[210:213], 0
	v_mfma_f32_16x16x32_bf16 v[74:77], v[152:155], v[210:213], 0
	v_mfma_f32_16x16x32_bf16 v[126:129], v[134:137], v[190:193], v[126:129]
	v_mfma_f32_16x16x32_bf16 v[122:125], v[156:159], v[190:193], v[122:125]
	v_mfma_f32_16x16x32_bf16 v[110:113], v[134:137], v[198:201], v[110:113]
	v_mfma_f32_16x16x32_bf16 v[106:109], v[156:159], v[198:201], v[106:109]
	v_mfma_f32_16x16x32_bf16 v[94:97], v[134:137], v[206:209], v[94:97]
	v_mfma_f32_16x16x32_bf16 v[90:93], v[156:159], v[206:209], v[90:93]
	v_mfma_f32_16x16x32_bf16 v[78:81], v[134:137], v[214:217], v[78:81]
	v_mfma_f32_16x16x32_bf16 v[74:77], v[156:159], v[214:217], v[74:77]
	v_mfma_f32_16x16x32_bf16 v[118:121], v[160:163], v[186:189], 0
	v_mfma_f32_16x16x32_bf16 v[114:117], v[178:181], v[186:189], 0
	v_mfma_f32_16x16x32_bf16 v[102:105], v[160:163], v[194:197], 0
	v_mfma_f32_16x16x32_bf16 v[98:101], v[178:181], v[194:197], 0
	v_mfma_f32_16x16x32_bf16 v[86:89], v[160:163], v[202:205], 0
	v_mfma_f32_16x16x32_bf16 v[82:85], v[178:181], v[202:205], 0
	v_mfma_f32_16x16x32_bf16 v[70:73], v[160:163], v[210:213], 0
	v_mfma_f32_16x16x32_bf16 v[66:69], v[178:181], v[210:213], 0
	v_mfma_f32_16x16x32_bf16 v[118:121], v[174:177], v[190:193], v[118:121]
	v_mfma_f32_16x16x32_bf16 v[114:117], v[182:185], v[190:193], v[114:117]
	v_mfma_f32_16x16x32_bf16 v[102:105], v[174:177], v[198:201], v[102:105]
	v_mfma_f32_16x16x32_bf16 v[98:101], v[182:185], v[198:201], v[98:101]
	v_mfma_f32_16x16x32_bf16 v[86:89], v[174:177], v[206:209], v[86:89]
	v_mfma_f32_16x16x32_bf16 v[82:85], v[182:185], v[206:209], v[82:85]
	v_mfma_f32_16x16x32_bf16 v[70:73], v[174:177], v[214:217], v[70:73]
	v_mfma_f32_16x16x32_bf16 v[66:69], v[182:185], v[214:217], v[66:69]
	s_barrier
	s_add_i32 s18, s18, s42
	v_lshl_add_u64 v[164:165], s[10:11], 0, v[142:143]
	s_mov_b32 m0, s18
	ds_read_b128 v[186:189], v172 offset:16384
	ds_read_b128 v[190:193], v172 offset:17408
	ds_read_b128 v[194:197], v172 offset:18432
	ds_read_b128 v[198:201], v172 offset:19456
	ds_read_b128 v[202:205], v172 offset:20480
	ds_read_b128 v[206:209], v172 offset:21504
	ds_read_b128 v[210:213], v172 offset:22528
	ds_read_b128 v[214:217], v172 offset:23552
	global_load_lds_dwordx4 v[164:165], off
	s_add_i32 m0, s18, 0x2000
	s_add_u32 s18, s10, 0x100000
	v_lshl_add_u64 v[218:219], s[10:11], 0, v[138:139]
	s_addc_u32 s19, s11, 0
	s_add_i32 s20, s20, s42
	global_load_lds_dwordx4 v[218:219], off
	v_lshl_add_u64 v[220:221], s[18:19], 0, v[142:143]
	s_mov_b32 m0, s20
	v_lshl_add_u64 v[222:223], s[14:15], 0, v[140:141]
	global_load_lds_dwordx4 v[220:221], off
	v_lshl_add_u64 v[220:221], s[18:19], 0, v[138:139]
	s_add_i32 m0, s20, 0x2000
	s_nop 0
	global_load_lds_dwordx4 v[220:221], off
	v_lshl_add_u64 v[220:221], s[14:15], 0, v[144:145]
	s_mov_b32 m0, s51
	s_nop 0
	global_load_lds_dwordx4 v[220:221], off
	s_mov_b32 m0, s68
	s_nop 0
	global_load_lds_dwordx4 v[222:223], off
	s_waitcnt vmcnt(8)
	s_waitcnt lgkmcnt(0)
	s_barrier
; #define PG8_STAGEA(bufoff, gbase, voff) PG8_STAGE_X(bufoff, gbase, voff, AUXA)
; #define PG8_STAGEB(bufoff, gbase, voff) PG8_STAGE_X(bufoff, gbase, voff, AUXB)
; #define PG8_LDA(dst, b, h) do { _Pragma("unroll") for (int m = 0; m < 4; ++m) _Pragma("unroll") for (int k = 0; k < 2; ++k) dst[m][k] = *(const PG8_LAS bf16x8*)(lds + PG8_SA(b, h) + aoff + m * 2048 + k * 1024); } while (0)
; #define PG8_LDB(dst, b, h) do { _Pragma("unroll") for (int n = 0; n < 2; ++n) _Pragma("unroll") for (int k = 0; k < 2; ++k) dst[n][k] = *(const PG8_LAS bf16x8*)(lds + PG8_SB(b, h) + boff + n * 2048 + k * 1024); } while (0)
; #define PG8_MMA(ai, bj, At, Bt) do { if (GEMM_PRIO_MODE == 0) __builtin_amdgcn_s_setprio(1); PG8_MMA_LOOPS \
;         acc[ai][bj][m][n] = __builtin_amdgcn_mfma_f32_16x16x32_bf16(Bt[n][k], At[m][k], acc[ai][bj][m][n], 0, 0, 0); if (GEMM_PRIO_MODE == 0) __builtin_amdgcn_s_setprio(0); } while (0)
; #define PG8_WAIT_V(n) asm volatile("s_waitcnt vmcnt(" #n ")" ::: "memory")
; #define PG8_WAIT_VR(n, nr, flag) asm volatile("s_cmp_eq_u32 %0, 0\n\ts_cbranch_scc1 .Lpg8s%=\n\ts_waitcnt vmcnt(" #nr ")\n\ts_branch .Lpg8d%=\n.Lpg8s%=:\n\ts_waitcnt vmcnt(" #n ")\n.Lpg8d%=:" :: "s"(flag) : "memory", "scc")
; #define PG8_WAIT_L(n) asm volatile("s_waitcnt lgkmcnt(" #n ")" ::: "memory")
; #define PG8_BAR __builtin_amdgcn_s_barrier()
; #define PG8_SCHED __builtin_amdgcn_sched_barrier(0)
;     ...
;             PG8_LDA(At, 0, 1); PG8_STAGEB(PG8_SB(0, 0), b2, voffB); PG8_STAGEB(PG8_SB(0, 1), b2 + hstepB, voffB); PG8_STAGEA(PG8_SA(0, 0), a2, voffA);
;     ...
;             PG8_WAIT_VR(8, 24, relax); PG8_WAIT_L(0); PG8_BAR; PG8_MMA(1, 0, At, B0); PG8_MMA(1, 1, At, B1); PG8_BAR; PG8_SCHED;
;     ...
;             PG8_WAIT_V(8); PG8_WAIT_L(0); PG8_BAR; PG8_MMA(1, 0, At, B0); PG8_MMA(1, 1, At, B1); PG8_BAR; PG8_SCHED;
;     ...
;             PG8_LDB(B0, 1, 0); PG8_LDB(B1, 1, 1); PG8_SCHED; PG8_LDA(At, 1, 0); PG8_STAGEA(PG8_SA(0, 1), a2 + hstepA, voffA);
;             PG8_WAIT_V(8); PG8_WAIT_L(0); PG8_BAR; PG8_MMA(0, 0, At, B0); PG8_MMA(0, 1, At, B1); PG8_BAR; PG8_SCHED;
	v_mfma_f32_16x16x32_bf16 v[62:65], v[130:133], v[186:189], 0
	v_mfma_f32_16x16x32_bf16 v[58:61], v[152:155], v[186:189], 0
	v_mfma_f32_16x16x32_bf16 v[46:49], v[130:133], v[194:197], 0
	v_mfma_f32_16x16x32_bf16 v[42:45], v[152:155], v[194:197], 0
	v_mfma_f32_16x16x32_bf16 v[30:33], v[130:133], v[202:205], 0
	v_mfma_f32_16x16x32_bf16 v[26:29], v[152:155], v[202:205], 0
	v_mfma_f32_16x16x32_bf16 v[12:15], v[130:133], v[210:213], 0
	v_mfma_f32_16x16x32_bf16 v[8:11], v[152:155], v[210:213], 0
	v_mfma_f32_16x16x32_bf16 v[62:65], v[134:137], v[190:193], v[62:65]
	v_mfma_f32_16x16x32_bf16 v[58:61], v[156:159], v[190:193], v[58:61]
	v_mfma_f32_16x16x32_bf16 v[46:49], v[134:137], v[198:201], v[46:49]
	v_mfma_f32_16x16x32_bf16 v[42:45], v[156:159], v[198:201], v[42:45]
	v_mfma_f32_16x16x32_bf16 v[30:33], v[134:137], v[206:209], v[30:33]
	v_mfma_f32_16x16x32_bf16 v[26:29], v[156:159], v[206:209], v[26:29]
	v_mfma_f32_16x16x32_bf16 v[12:15], v[134:137], v[214:217], v[12:15]
	v_mfma_f32_16x16x32_bf16 v[8:11], v[156:159], v[214:217], v[8:11]
	v_mfma_f32_16x16x32_bf16 v[54:57], v[160:163], v[186:189], 0
	v_mfma_f32_16x16x32_bf16 v[50:53], v[178:181], v[186:189], 0
	v_mfma_f32_16x16x32_bf16 v[38:41], v[160:163], v[194:197], 0
	v_mfma_f32_16x16x32_bf16 v[34:37], v[178:181], v[194:197], 0
	v_mfma_f32_16x16x32_bf16 v[22:25], v[160:163], v[202:205], 0
	v_mfma_f32_16x16x32_bf16 v[18:21], v[178:181], v[202:205], 0
	v_mfma_f32_16x16x32_bf16 v[4:7], v[160:163], v[210:213], 0
	v_mfma_f32_16x16x32_bf16 v[0:3], v[178:181], v[210:213], 0
	v_mfma_f32_16x16x32_bf16 v[54:57], v[174:177], v[190:193], v[54:57]
	v_mfma_f32_16x16x32_bf16 v[50:53], v[182:185], v[190:193], v[50:53]
	v_mfma_f32_16x16x32_bf16 v[38:41], v[174:177], v[198:201], v[38:41]
	v_mfma_f32_16x16x32_bf16 v[34:37], v[182:185], v[198:201], v[34:37]
	v_mfma_f32_16x16x32_bf16 v[22:25], v[174:177], v[206:209], v[22:25]
	v_mfma_f32_16x16x32_bf16 v[18:21], v[182:185], v[206:209], v[18:21]
	v_mfma_f32_16x16x32_bf16 v[4:7], v[174:177], v[214:217], v[4:7]
	v_mfma_f32_16x16x32_bf16 v[0:3], v[182:185], v[214:217], v[0:3]
	s_barrier
	s_add_i32 s18, 0, 0x18000
	v_add_u32_e32 v16, s18, v167
	s_add_i32 s19, 0, 0x1c000
	ds_read_b128 v[130:133], v16
	ds_read_b128 v[134:137], v16 offset:1024
	ds_read_b128 v[152:155], v16 offset:2048
	ds_read_b128 v[156:159], v16 offset:3072
	v_add_u32_e32 v16, s19, v167
	ds_read_b128 v[160:163], v16
	ds_read_b128 v[174:177], v16 offset:1024
	ds_read_b128 v[178:181], v16 offset:2048
	ds_read_b128 v[182:185], v16 offset:3072
	s_add_u32 s14, s14, 0x100000
	s_addc_u32 s15, s15, 0
	s_mov_b32 m0, s69
	v_lshl_add_u64 v[224:225], s[14:15], 0, v[144:145]
	ds_read_b128 v[186:189], v172 offset:32768
	ds_read_b128 v[190:193], v172 offset:33792
	ds_read_b128 v[194:197], v172 offset:34816
	ds_read_b128 v[198:201], v172 offset:35840
	ds_read_b128 v[202:205], v172 offset:36864
	ds_read_b128 v[206:209], v172 offset:37888
	ds_read_b128 v[210:213], v172 offset:38912
	ds_read_b128 v[214:217], v172 offset:39936
	global_load_lds_dwordx4 v[224:225], off
	v_lshl_add_u64 v[224:225], s[14:15], 0, v[140:141]
	s_mov_b32 m0, s72
	s_nop 0
	global_load_lds_dwordx4 v[224:225], off
	s_waitcnt vmcnt(8)
	s_waitcnt lgkmcnt(0)
	s_barrier
	v_mfma_f32_16x16x32_bf16 v[126:129], v[130:133], v[186:189], v[126:129]
	v_mfma_f32_16x16x32_bf16 v[122:125], v[152:155], v[186:189], v[122:125]
	v_mfma_f32_16x16x32_bf16 v[110:113], v[130:133], v[194:197], v[110:113]
	v_mfma_f32_16x16x32_bf16 v[106:109], v[152:155], v[194:197], v[106:109]
	v_mfma_f32_16x16x32_bf16 v[94:97], v[130:133], v[202:205], v[94:97]
	v_mfma_f32_16x16x32_bf16 v[90:93], v[152:155], v[202:205], v[90:93]
	v_mfma_f32_16x16x32_bf16 v[78:81], v[130:133], v[210:213], v[78:81]
	v_mfma_f32_16x16x32_bf16 v[74:77], v[152:155], v[210:213], v[74:77]
	v_mfma_f32_16x16x32_bf16 v[126:129], v[134:137], v[190:193], v[126:129]
	v_mfma_f32_16x16x32_bf16 v[122:125], v[156:159], v[190:193], v[122:125]
	v_mfma_f32_16x16x32_bf16 v[110:113], v[134:137], v[198:201], v[110:113]
	v_mfma_f32_16x16x32_bf16 v[106:109], v[156:159], v[198:201], v[106:109]
	v_mfma_f32_16x16x32_bf16 v[94:97], v[134:137], v[206:209], v[94:97]
	v_mfma_f32_16x16x32_bf16 v[90:93], v[156:159], v[206:209], v[90:93]
	v_mfma_f32_16x16x32_bf16 v[78:81], v[134:137], v[214:217], v[78:81]
	v_mfma_f32_16x16x32_bf16 v[74:77], v[156:159], v[214:217], v[74:77]
	v_mfma_f32_16x16x32_bf16 v[118:121], v[160:163], v[186:189], v[118:121]
	v_mfma_f32_16x16x32_bf16 v[114:117], v[178:181], v[186:189], v[114:117]
	v_mfma_f32_16x16x32_bf16 v[102:105], v[160:163], v[194:197], v[102:105]
	v_mfma_f32_16x16x32_bf16 v[98:101], v[178:181], v[194:197], v[98:101]
	v_mfma_f32_16x16x32_bf16 v[86:89], v[160:163], v[202:205], v[86:89]
	v_mfma_f32_16x16x32_bf16 v[82:85], v[178:181], v[202:205], v[82:85]
	v_mfma_f32_16x16x32_bf16 v[70:73], v[160:163], v[210:213], v[70:73]
	v_mfma_f32_16x16x32_bf16 v[66:69], v[178:181], v[210:213], v[66:69]
	v_mfma_f32_16x16x32_bf16 v[118:121], v[174:177], v[190:193], v[118:121]
	v_mfma_f32_16x16x32_bf16 v[114:117], v[182:185], v[190:193], v[114:117]
	v_mfma_f32_16x16x32_bf16 v[102:105], v[174:177], v[198:201], v[102:105]
	v_mfma_f32_16x16x32_bf16 v[98:101], v[182:185], v[198:201], v[98:101]
	v_mfma_f32_16x16x32_bf16 v[86:89], v[174:177], v[206:209], v[86:89]
	v_mfma_f32_16x16x32_bf16 v[82:85], v[182:185], v[206:209], v[82:85]
	v_mfma_f32_16x16x32_bf16 v[70:73], v[174:177], v[214:217], v[70:73]
	v_mfma_f32_16x16x32_bf16 v[66:69], v[182:185], v[214:217], v[66:69]
	s_barrier
; #define PG8_STAGEA(bufoff, gbase, voff) PG8_STAGE_X(bufoff, gbase, voff, AUXA)
; #define PG8_STAGEB(bufoff, gbase, voff) PG8_STAGE_X(bufoff, gbase, voff, AUXB)
; #define PG8_LDA(dst, b, h) do { _Pragma("unroll") for (int m = 0; m < 4; ++m) _Pragma("unroll") for (int k = 0; k < 2; ++k) dst[m][k] = *(const PG8_LAS bf16x8*)(lds + PG8_SA(b, h) + aoff + m * 2048 + k * 1024); } while (0)
; #define PG8_LDB(dst, b, h) do { _Pragma("unroll") for (int n = 0; n < 2; ++n) _Pragma("unroll") for (int k = 0; k < 2; ++k) dst[n][k] = *(const PG8_LAS bf16x8*)(lds + PG8_SB(b, h) + boff + n * 2048 + k * 1024); } while (0)
; #define PG8_MMA(ai, bj, At, Bt) do { if (GEMM_PRIO_MODE == 0) __builtin_amdgcn_s_setprio(1); PG8_MMA_LOOPS \
;         acc[ai][bj][m][n] = __builtin_amdgcn_mfma_f32_16x16x32_bf16(Bt[n][k], At[m][k], acc[ai][bj][m][n], 0, 0, 0); if (GEMM_PRIO_MODE == 0) __builtin_amdgcn_s_setprio(0); } while (0)
; #define PG8_BAR __builtin_amdgcn_s_barrier()
;     ...
;         for (int t = t0; t < nt; t += 2) {
;             const bool last = (t == nt - 2);
;             const char* a1 = cA + (size_t)(t + 1) * kstepA;
;             const char* a2 = last ? nA : cA + (size_t)(t + 2) * kstepA; const char* b2 = last ? nB : cB + (size_t)(t + 2) * kstepB;
;             const char* a3 = a2 + kstepA; const char* b3 = b2 + kstepB;
;             if (last && has_next) S.a_ready(nxt);
;             if constexpr (SP2) {
;             PG8_LDB(B0, 0, 0); PG8_LDB(B1, 0, 1); PG8_SCHED; PG8_LDA(At, 0, 0); PG8_STAGEA(PG8_SA(1, 1), a1 + hstepA, voffA);
;     ...
;             const int relax = __builtin_amdgcn_readfirstlane((t == 0 && ui > 0) ? 1 : 0);
;             PG8_WAIT_VR(8, 24, relax); PG8_WAIT_L(0); PG8_BAR; PG8_MMA(0, 0, At, B0); PG8_MMA(0, 1, At, B1); PG8_BAR; PG8_SCHED;
;     ...
;             PG8_WAIT_V(8); PG8_WAIT_L(0); PG8_BAR; PG8_MMA(0, 0, At, B0); PG8_MMA(0, 1, At, B1); PG8_BAR; PG8_SCHED;
;     ...
;             PG8_LDB(B0, 1, 0); PG8_LDB(B1, 1, 1); PG8_SCHED; PG8_LDA(At, 1, 0); PG8_STAGEA(PG8_SA(0, 1), a2 + hstepA, voffA);
;             PG8_WAIT_V(8); PG8_WAIT_L(0); PG8_BAR; PG8_MMA(0, 0, At, B0); PG8_MMA(0, 1, At, B1); PG8_BAR; PG8_SCHED;
;             PG8_LDA(At, 1, 1); PG8_STAGEB(PG8_SB(1, 0), b3, voffB); PG8_STAGEB(PG8_SB(1, 1), b3 + hstepB, voffB); PG8_STAGEA(PG8_SA(1, 0), a3, voffA);
;             PG8_WAIT_V(8); PG8_WAIT_L(0); PG8_BAR; PG8_MMA(1, 0, At, B0); PG8_MMA(1, 1, At, B1); PG8_BAR; PG8_SCHED;
	s_add_i32 s14, s18, s42
	v_lshl_add_u64 v[164:165], v[164:165], 0, s[86:87]
	s_mov_b32 m0, s14
	ds_read_b128 v[186:189], v172 offset:49152
	ds_read_b128 v[190:193], v172 offset:50176
	ds_read_b128 v[194:197], v172 offset:51200
	ds_read_b128 v[198:201], v172 offset:52224
	ds_read_b128 v[202:205], v172 offset:53248
	ds_read_b128 v[206:209], v172 offset:54272
	ds_read_b128 v[210:213], v172 offset:55296
	ds_read_b128 v[214:217], v172 offset:56320
	global_load_lds_dwordx4 v[164:165], off
	s_add_i32 m0, s14, 0x2000
	s_add_u32 s10, s10, 0x100080
	v_lshl_add_u64 v[164:165], v[218:219], 0, s[86:87]
	s_addc_u32 s11, s11, 0
	s_add_i32 s14, s19, s42
	global_load_lds_dwordx4 v[164:165], off
	v_lshl_add_u64 v[164:165], s[10:11], 0, v[142:143]
	s_mov_b32 m0, s14
	s_nop 0
	global_load_lds_dwordx4 v[164:165], off
	v_lshl_add_u64 v[164:165], s[10:11], 0, v[138:139]
	s_add_i32 m0, s14, 0x2000
	s_nop 0
	global_load_lds_dwordx4 v[164:165], off
	v_lshl_add_u64 v[164:165], v[220:221], 0, s[86:87]
	s_mov_b32 m0, s73
	s_nop 0
	global_load_lds_dwordx4 v[164:165], off
	v_lshl_add_u64 v[164:165], v[222:223], 0, s[86:87]
	s_mov_b32 m0, s82
	s_nop 0
	global_load_lds_dwordx4 v[164:165], off
	s_waitcnt vmcnt(8)
	s_waitcnt lgkmcnt(0)
	s_barrier
	v_mfma_f32_16x16x32_bf16 v[62:65], v[130:133], v[186:189], v[62:65]
	v_mfma_f32_16x16x32_bf16 v[58:61], v[152:155], v[186:189], v[58:61]
	v_mfma_f32_16x16x32_bf16 v[46:49], v[130:133], v[194:197], v[46:49]
	v_mfma_f32_16x16x32_bf16 v[42:45], v[152:155], v[194:197], v[42:45]
	v_mfma_f32_16x16x32_bf16 v[30:33], v[130:133], v[202:205], v[30:33]
	v_mfma_f32_16x16x32_bf16 v[26:29], v[152:155], v[202:205], v[26:29]
	v_mfma_f32_16x16x32_bf16 v[12:15], v[130:133], v[210:213], v[12:15]
	v_mfma_f32_16x16x32_bf16 v[8:11], v[152:155], v[210:213], v[8:11]
	v_mfma_f32_16x16x32_bf16 v[62:65], v[134:137], v[190:193], v[62:65]
	v_mfma_f32_16x16x32_bf16 v[58:61], v[156:159], v[190:193], v[58:61]
	v_mfma_f32_16x16x32_bf16 v[46:49], v[134:137], v[198:201], v[46:49]
	v_mfma_f32_16x16x32_bf16 v[42:45], v[156:159], v[198:201], v[42:45]
	v_mfma_f32_16x16x32_bf16 v[30:33], v[134:137], v[206:209], v[30:33]
	v_mfma_f32_16x16x32_bf16 v[26:29], v[156:159], v[206:209], v[26:29]
	v_mfma_f32_16x16x32_bf16 v[12:15], v[134:137], v[214:217], v[12:15]
	v_mfma_f32_16x16x32_bf16 v[8:11], v[156:159], v[214:217], v[8:11]
	v_mfma_f32_16x16x32_bf16 v[54:57], v[160:163], v[186:189], v[54:57]
	v_mfma_f32_16x16x32_bf16 v[50:53], v[178:181], v[186:189], v[50:53]
	v_mfma_f32_16x16x32_bf16 v[38:41], v[160:163], v[194:197], v[38:41]
	v_mfma_f32_16x16x32_bf16 v[34:37], v[178:181], v[194:197], v[34:37]
	v_mfma_f32_16x16x32_bf16 v[22:25], v[160:163], v[202:205], v[22:25]
	v_mfma_f32_16x16x32_bf16 v[18:21], v[178:181], v[202:205], v[18:21]
	v_mfma_f32_16x16x32_bf16 v[4:7], v[160:163], v[210:213], v[4:7]
	v_mfma_f32_16x16x32_bf16 v[0:3], v[178:181], v[210:213], v[0:3]
	v_mfma_f32_16x16x32_bf16 v[54:57], v[174:177], v[190:193], v[54:57]
	v_mfma_f32_16x16x32_bf16 v[50:53], v[182:185], v[190:193], v[50:53]
	v_mfma_f32_16x16x32_bf16 v[38:41], v[174:177], v[198:201], v[38:41]
	v_mfma_f32_16x16x32_bf16 v[34:37], v[182:185], v[198:201], v[34:37]
	v_mfma_f32_16x16x32_bf16 v[22:25], v[174:177], v[206:209], v[22:25]
	v_mfma_f32_16x16x32_bf16 v[18:21], v[182:185], v[206:209], v[18:21]
	v_mfma_f32_16x16x32_bf16 v[4:7], v[174:177], v[214:217], v[4:7]
	v_mfma_f32_16x16x32_bf16 v[0:3], v[182:185], v[214:217], v[0:3]
	s_barrier
	s_add_i32 s27, s27, 2
	s_add_u32 s8, s8, 0x100
	s_addc_u32 s9, s9, 0
	s_add_u32 s0, s0, 0x100
	s_addc_u32 s1, s1, 0
.LBB0_129:
	s_add_u32 s10, s8, 0xfff00080
	s_addc_u32 s11, s9, -1
	s_add_i32 s18, 0, 0x10000
	s_cmp_eq_u32 s27, 60
	s_cselect_b32 s15, s4, s11
	s_cselect_b32 s14, s5, s10
	v_add_u32_e32 v16, s18, v167
	s_cselect_b32 s11, s16, s1
	s_cselect_b32 s10, s17, s0
	s_add_i32 s20, 0, 0x14000
	s_waitcnt lgkmcnt(0)
	ds_read_b128 v[130:133], v16
	ds_read_b128 v[134:137], v16 offset:1024
	ds_read_b128 v[152:155], v16 offset:2048
	ds_read_b128 v[156:159], v16 offset:3072
	v_add_u32_e32 v16, s20, v167
	ds_read_b128 v[160:163], v16
	ds_read_b128 v[174:177], v16 offset:1024
	ds_read_b128 v[178:181], v16 offset:2048
	ds_read_b128 v[182:185], v16 offset:3072
	v_lshl_add_u64 v[164:165], s[8:9], 0, v[148:149]
	s_add_i32 m0, s51, 0xc000
	ds_read_b128 v[186:189], v172
	ds_read_b128 v[190:193], v172 offset:1024
	ds_read_b128 v[194:197], v172 offset:2048
	ds_read_b128 v[198:201], v172 offset:3072
	ds_read_b128 v[202:205], v172 offset:4096
	ds_read_b128 v[206:209], v172 offset:5120
	ds_read_b128 v[210:213], v172 offset:6144
	ds_read_b128 v[214:217], v172 offset:7168
	global_load_lds_dwordx4 v[164:165], off
	v_lshl_add_u64 v[164:165], s[8:9], 0, v[150:151]
	s_add_i32 m0, s51, 0xe000
	s_nop 0
	global_load_lds_dwordx4 v[164:165], off
	s_waitcnt vmcnt(8)
	s_waitcnt lgkmcnt(0)
	s_barrier
; #define PG8_STAGEA(bufoff, gbase, voff) PG8_STAGE_X(bufoff, gbase, voff, AUXA)
; #define PG8_STAGEB(bufoff, gbase, voff) PG8_STAGE_X(bufoff, gbase, voff, AUXB)
; #define PG8_LDA(dst, b, h) do { _Pragma("unroll") for (int m = 0; m < 4; ++m) _Pragma("unroll") for (int k = 0; k < 2; ++k) dst[m][k] = *(const PG8_LAS bf16x8*)(lds + PG8_SA(b, h) + aoff + m * 2048 + k * 1024); } while (0)
; #define PG8_LDB(dst, b, h) do { _Pragma("unroll") for (int n = 0; n < 2; ++n) _Pragma("unroll") for (int k = 0; k < 2; ++k) dst[n][k] = *(const PG8_LAS bf16x8*)(lds + PG8_SB(b, h) + boff + n * 2048 + k * 1024); } while (0)
; #define PG8_MMA(ai, bj, At, Bt) do { if (GEMM_PRIO_MODE == 0) __builtin_amdgcn_s_setprio(1); PG8_MMA_LOOPS \
;         acc[ai][bj][m][n] = __builtin_amdgcn_mfma_f32_16x16x32_bf16(Bt[n][k], At[m][k], acc[ai][bj][m][n], 0, 0, 0); if (GEMM_PRIO_MODE == 0) __builtin_amdgcn_s_setprio(0); } while (0)
; #define PG8_WAIT_V(n) asm volatile("s_waitcnt vmcnt(" #n ")" ::: "memory")
; #define PG8_WAIT_VR(n, nr, flag) asm volatile("s_cmp_eq_u32 %0, 0\n\ts_cbranch_scc1 .Lpg8s%=\n\ts_waitcnt vmcnt(" #nr ")\n\ts_branch .Lpg8d%=\n.Lpg8s%=:\n\ts_waitcnt vmcnt(" #n ")\n.Lpg8d%=:" :: "s"(flag) : "memory", "scc")
; #define PG8_WAIT_L(n) asm volatile("s_waitcnt lgkmcnt(" #n ")" ::: "memory")
; #define PG8_BAR __builtin_amdgcn_s_barrier()
; #define PG8_SCHED __builtin_amdgcn_sched_barrier(0)
;     ...
;             PG8_WAIT_V(8); PG8_WAIT_L(0); PG8_BAR; PG8_MMA(0, 0, At, B0); PG8_MMA(0, 1, At, B1); PG8_BAR; PG8_SCHED;
;     ...
;             PG8_LDA(At, 0, 1); PG8_STAGEB(PG8_SB(0, 0), b2, voffB); PG8_STAGEB(PG8_SB(0, 1), b2 + hstepB, voffB); PG8_STAGEA(PG8_SA(0, 0), a2, voffA);
;     ...
;             PG8_WAIT_VR(8, 24, relax); PG8_WAIT_L(0); PG8_BAR; PG8_MMA(1, 0, At, B0); PG8_MMA(1, 1, At, B1); PG8_BAR; PG8_SCHED;
;     ...
;             PG8_WAIT_V(8); PG8_WAIT_L(0); PG8_BAR; PG8_MMA(1, 0, At, B0); PG8_MMA(1, 1, At, B1); PG8_BAR; PG8_SCHED;
;     ...
;             PG8_LDB(B0, 1, 0); PG8_LDB(B1, 1, 1); PG8_SCHED; PG8_LDA(At, 1, 0); PG8_STAGEA(PG8_SA(0, 1), a2 + hstepA, voffA);
;             PG8_WAIT_V(8); PG8_WAIT_L(0); PG8_BAR; PG8_MMA(0, 0, At, B0); PG8_MMA(0, 1, At, B1); PG8_BAR; PG8_SCHED;
	v_mfma_f32_16x16x32_bf16 v[126:129], v[130:133], v[186:189], v[126:129]
	v_mfma_f32_16x16x32_bf16 v[122:125], v[152:155], v[186:189], v[122:125]
	v_mfma_f32_16x16x32_bf16 v[110:113], v[130:133], v[194:197], v[110:113]
	v_mfma_f32_16x16x32_bf16 v[106:109], v[152:155], v[194:197], v[106:109]
	v_mfma_f32_16x16x32_bf16 v[94:97], v[130:133], v[202:205], v[94:97]
	v_mfma_f32_16x16x32_bf16 v[90:93], v[152:155], v[202:205], v[90:93]
	v_mfma_f32_16x16x32_bf16 v[78:81], v[130:133], v[210:213], v[78:81]
	v_mfma_f32_16x16x32_bf16 v[74:77], v[152:155], v[210:213], v[74:77]
	v_mfma_f32_16x16x32_bf16 v[126:129], v[134:137], v[190:193], v[126:129]
	v_mfma_f32_16x16x32_bf16 v[122:125], v[156:159], v[190:193], v[122:125]
	v_mfma_f32_16x16x32_bf16 v[110:113], v[134:137], v[198:201], v[110:113]
	v_mfma_f32_16x16x32_bf16 v[106:109], v[156:159], v[198:201], v[106:109]
	v_mfma_f32_16x16x32_bf16 v[94:97], v[134:137], v[206:209], v[94:97]
	v_mfma_f32_16x16x32_bf16 v[90:93], v[156:159], v[206:209], v[90:93]
	v_mfma_f32_16x16x32_bf16 v[78:81], v[134:137], v[214:217], v[78:81]
	v_mfma_f32_16x16x32_bf16 v[74:77], v[156:159], v[214:217], v[74:77]
	v_mfma_f32_16x16x32_bf16 v[118:121], v[160:163], v[186:189], v[118:121]
	v_mfma_f32_16x16x32_bf16 v[114:117], v[178:181], v[186:189], v[114:117]
	v_mfma_f32_16x16x32_bf16 v[102:105], v[160:163], v[194:197], v[102:105]
	v_mfma_f32_16x16x32_bf16 v[98:101], v[178:181], v[194:197], v[98:101]
	v_mfma_f32_16x16x32_bf16 v[86:89], v[160:163], v[202:205], v[86:89]
	v_mfma_f32_16x16x32_bf16 v[82:85], v[178:181], v[202:205], v[82:85]
	v_mfma_f32_16x16x32_bf16 v[70:73], v[160:163], v[210:213], v[70:73]
	v_mfma_f32_16x16x32_bf16 v[66:69], v[178:181], v[210:213], v[66:69]
	v_mfma_f32_16x16x32_bf16 v[118:121], v[174:177], v[190:193], v[118:121]
	v_mfma_f32_16x16x32_bf16 v[114:117], v[182:185], v[190:193], v[114:117]
	v_mfma_f32_16x16x32_bf16 v[102:105], v[174:177], v[198:201], v[102:105]
	v_mfma_f32_16x16x32_bf16 v[98:101], v[182:185], v[198:201], v[98:101]
	v_mfma_f32_16x16x32_bf16 v[86:89], v[174:177], v[206:209], v[86:89]
	v_mfma_f32_16x16x32_bf16 v[82:85], v[182:185], v[206:209], v[82:85]
	v_mfma_f32_16x16x32_bf16 v[70:73], v[174:177], v[214:217], v[70:73]
	v_mfma_f32_16x16x32_bf16 v[66:69], v[182:185], v[214:217], v[66:69]
	s_barrier
	s_add_i32 s18, s18, s42
	v_lshl_add_u64 v[164:165], s[10:11], 0, v[142:143]
	s_mov_b32 m0, s18
	ds_read_b128 v[186:189], v172 offset:16384
	ds_read_b128 v[190:193], v172 offset:17408
	ds_read_b128 v[194:197], v172 offset:18432
	ds_read_b128 v[198:201], v172 offset:19456
	ds_read_b128 v[202:205], v172 offset:20480
	ds_read_b128 v[206:209], v172 offset:21504
	ds_read_b128 v[210:213], v172 offset:22528
	ds_read_b128 v[214:217], v172 offset:23552
	global_load_lds_dwordx4 v[164:165], off
	s_add_i32 m0, s18, 0x2000
	s_add_u32 s18, s10, 0x100000
	v_lshl_add_u64 v[218:219], s[10:11], 0, v[138:139]
	s_addc_u32 s19, s11, 0
	s_add_i32 s20, s20, s42
	global_load_lds_dwordx4 v[218:219], off
	v_lshl_add_u64 v[220:221], s[18:19], 0, v[142:143]
	s_mov_b32 m0, s20
	v_lshl_add_u64 v[222:223], s[14:15], 0, v[140:141]
	global_load_lds_dwordx4 v[220:221], off
	v_lshl_add_u64 v[220:221], s[18:19], 0, v[138:139]
	s_add_i32 m0, s20, 0x2000
	s_nop 0
	global_load_lds_dwordx4 v[220:221], off
	v_lshl_add_u64 v[220:221], s[14:15], 0, v[144:145]
	s_mov_b32 m0, s51
	s_nop 0
	global_load_lds_dwordx4 v[220:221], off
	s_mov_b32 m0, s68
	s_nop 0
	global_load_lds_dwordx4 v[222:223], off
	s_waitcnt vmcnt(8)
	s_waitcnt lgkmcnt(0)
	s_barrier
	v_mfma_f32_16x16x32_bf16 v[62:65], v[130:133], v[186:189], v[62:65]
	v_mfma_f32_16x16x32_bf16 v[58:61], v[152:155], v[186:189], v[58:61]
	v_mfma_f32_16x16x32_bf16 v[46:49], v[130:133], v[194:197], v[46:49]
	v_mfma_f32_16x16x32_bf16 v[42:45], v[152:155], v[194:197], v[42:45]
	v_mfma_f32_16x16x32_bf16 v[30:33], v[130:133], v[202:205], v[30:33]
	v_mfma_f32_16x16x32_bf16 v[26:29], v[152:155], v[202:205], v[26:29]
	v_mfma_f32_16x16x32_bf16 v[12:15], v[130:133], v[210:213], v[12:15]
	v_mfma_f32_16x16x32_bf16 v[8:11], v[152:155], v[210:213], v[8:11]
	v_mfma_f32_16x16x32_bf16 v[62:65], v[134:137], v[190:193], v[62:65]
	v_mfma_f32_16x16x32_bf16 v[58:61], v[156:159], v[190:193], v[58:61]
	v_mfma_f32_16x16x32_bf16 v[46:49], v[134:137], v[198:201], v[46:49]
	v_mfma_f32_16x16x32_bf16 v[42:45], v[156:159], v[198:201], v[42:45]
	v_mfma_f32_16x16x32_bf16 v[30:33], v[134:137], v[206:209], v[30:33]
	v_mfma_f32_16x16x32_bf16 v[26:29], v[156:159], v[206:209], v[26:29]
	v_mfma_f32_16x16x32_bf16 v[12:15], v[134:137], v[214:217], v[12:15]
	v_mfma_f32_16x16x32_bf16 v[8:11], v[156:159], v[214:217], v[8:11]
	v_mfma_f32_16x16x32_bf16 v[54:57], v[160:163], v[186:189], v[54:57]
	v_mfma_f32_16x16x32_bf16 v[50:53], v[178:181], v[186:189], v[50:53]
	v_mfma_f32_16x16x32_bf16 v[38:41], v[160:163], v[194:197], v[38:41]
	v_mfma_f32_16x16x32_bf16 v[34:37], v[178:181], v[194:197], v[34:37]
	v_mfma_f32_16x16x32_bf16 v[22:25], v[160:163], v[202:205], v[22:25]
	v_mfma_f32_16x16x32_bf16 v[18:21], v[178:181], v[202:205], v[18:21]
	v_mfma_f32_16x16x32_bf16 v[4:7], v[160:163], v[210:213], v[4:7]
	v_mfma_f32_16x16x32_bf16 v[0:3], v[178:181], v[210:213], v[0:3]
	v_mfma_f32_16x16x32_bf16 v[54:57], v[174:177], v[190:193], v[54:57]
	v_mfma_f32_16x16x32_bf16 v[50:53], v[182:185], v[190:193], v[50:53]
	v_mfma_f32_16x16x32_bf16 v[38:41], v[174:177], v[198:201], v[38:41]
	v_mfma_f32_16x16x32_bf16 v[34:37], v[182:185], v[198:201], v[34:37]
	v_mfma_f32_16x16x32_bf16 v[22:25], v[174:177], v[206:209], v[22:25]
	v_mfma_f32_16x16x32_bf16 v[18:21], v[182:185], v[206:209], v[18:21]
	v_mfma_f32_16x16x32_bf16 v[4:7], v[174:177], v[214:217], v[4:7]
	v_mfma_f32_16x16x32_bf16 v[0:3], v[182:185], v[214:217], v[0:3]
	s_barrier
; #define PG8_STAGEA(bufoff, gbase, voff) PG8_STAGE_X(bufoff, gbase, voff, AUXA)
; #define PG8_LDA(dst, b, h) do { _Pragma("unroll") for (int m = 0; m < 4; ++m) _Pragma("unroll") for (int k = 0; k < 2; ++k) dst[m][k] = *(const PG8_LAS bf16x8*)(lds + PG8_SA(b, h) + aoff + m * 2048 + k * 1024); } while (0)
; #define PG8_LDB(dst, b, h) do { _Pragma("unroll") for (int n = 0; n < 2; ++n) _Pragma("unroll") for (int k = 0; k < 2; ++k) dst[n][k] = *(const PG8_LAS bf16x8*)(lds + PG8_SB(b, h) + boff + n * 2048 + k * 1024); } while (0)
; #define PG8_MMA(ai, bj, At, Bt) do { if (GEMM_PRIO_MODE == 0) __builtin_amdgcn_s_setprio(1); PG8_MMA_LOOPS \
;         acc[ai][bj][m][n] = __builtin_amdgcn_mfma_f32_16x16x32_bf16(Bt[n][k], At[m][k], acc[ai][bj][m][n], 0, 0, 0); if (GEMM_PRIO_MODE == 0) __builtin_amdgcn_s_setprio(0); } while (0)
; #define PG8_WAIT_V(n) asm volatile("s_waitcnt vmcnt(" #n ")" ::: "memory")
; #define PG8_WAIT_L(n) asm volatile("s_waitcnt lgkmcnt(" #n ")" ::: "memory")
; #define PG8_BAR __builtin_amdgcn_s_barrier()
; #define PG8_SCHED __builtin_amdgcn_sched_barrier(0)
;     ...
;             PG8_LDB(B0, 1, 0); PG8_LDB(B1, 1, 1); PG8_SCHED; PG8_LDA(At, 1, 0); PG8_STAGEA(PG8_SA(0, 1), a2 + hstepA, voffA);
;             PG8_WAIT_V(8); PG8_WAIT_L(0); PG8_BAR; PG8_MMA(0, 0, At, B0); PG8_MMA(0, 1, At, B1); PG8_BAR; PG8_SCHED;
	s_add_i32 s18, 0, 0x18000
	v_add_u32_e32 v16, s18, v167
	s_add_i32 s19, 0, 0x1c000
	ds_read_b128 v[130:133], v16
	ds_read_b128 v[134:137], v16 offset:1024
	ds_read_b128 v[152:155], v16 offset:2048
	ds_read_b128 v[156:159], v16 offset:3072
	v_add_u32_e32 v16, s19, v167
	ds_read_b128 v[160:163], v16
	ds_read_b128 v[174:177], v16 offset:1024
	ds_read_b128 v[178:181], v16 offset:2048
	ds_read_b128 v[182:185], v16 offset:3072
	s_add_u32 s14, s14, 0x100000
	s_addc_u32 s15, s15, 0
	s_mov_b32 m0, s69
	v_lshl_add_u64 v[224:225], s[14:15], 0, v[144:145]
	ds_read_b128 v[186:189], v172 offset:32768
	ds_read_b128 v[190:193], v172 offset:33792
	ds_read_b128 v[194:197], v172 offset:34816
	ds_read_b128 v[198:201], v172 offset:35840
	ds_read_b128 v[202:205], v172 offset:36864
	ds_read_b128 v[206:209], v172 offset:37888
	ds_read_b128 v[210:213], v172 offset:38912
	ds_read_b128 v[214:217], v172 offset:39936
	global_load_lds_dwordx4 v[224:225], off
	v_lshl_add_u64 v[224:225], s[14:15], 0, v[140:141]
	s_mov_b32 m0, s72
	s_nop 0
	global_load_lds_dwordx4 v[224:225], off
	s_waitcnt vmcnt(8)
	s_waitcnt lgkmcnt(0)
	s_barrier
	v_mfma_f32_16x16x32_bf16 v[126:129], v[130:133], v[186:189], v[126:129]
	v_mfma_f32_16x16x32_bf16 v[122:125], v[152:155], v[186:189], v[122:125]
	v_mfma_f32_16x16x32_bf16 v[110:113], v[130:133], v[194:197], v[110:113]
	v_mfma_f32_16x16x32_bf16 v[106:109], v[152:155], v[194:197], v[106:109]
	v_mfma_f32_16x16x32_bf16 v[94:97], v[130:133], v[202:205], v[94:97]
	v_mfma_f32_16x16x32_bf16 v[90:93], v[152:155], v[202:205], v[90:93]
	v_mfma_f32_16x16x32_bf16 v[78:81], v[130:133], v[210:213], v[78:81]
	v_mfma_f32_16x16x32_bf16 v[74:77], v[152:155], v[210:213], v[74:77]
	v_mfma_f32_16x16x32_bf16 v[126:129], v[134:137], v[190:193], v[126:129]
	v_mfma_f32_16x16x32_bf16 v[122:125], v[156:159], v[190:193], v[122:125]
	v_mfma_f32_16x16x32_bf16 v[110:113], v[134:137], v[198:201], v[110:113]
	v_mfma_f32_16x16x32_bf16 v[106:109], v[156:159], v[198:201], v[106:109]
	v_mfma_f32_16x16x32_bf16 v[94:97], v[134:137], v[206:209], v[94:97]
	v_mfma_f32_16x16x32_bf16 v[90:93], v[156:159], v[206:209], v[90:93]
	v_mfma_f32_16x16x32_bf16 v[78:81], v[134:137], v[214:217], v[78:81]
	v_mfma_f32_16x16x32_bf16 v[74:77], v[156:159], v[214:217], v[74:77]
	v_mfma_f32_16x16x32_bf16 v[118:121], v[160:163], v[186:189], v[118:121]
	v_mfma_f32_16x16x32_bf16 v[114:117], v[178:181], v[186:189], v[114:117]
	v_mfma_f32_16x16x32_bf16 v[102:105], v[160:163], v[194:197], v[102:105]
	v_mfma_f32_16x16x32_bf16 v[98:101], v[178:181], v[194:197], v[98:101]
	v_mfma_f32_16x16x32_bf16 v[86:89], v[160:163], v[202:205], v[86:89]
	v_mfma_f32_16x16x32_bf16 v[82:85], v[178:181], v[202:205], v[82:85]
	v_mfma_f32_16x16x32_bf16 v[70:73], v[160:163], v[210:213], v[70:73]
	v_mfma_f32_16x16x32_bf16 v[66:69], v[178:181], v[210:213], v[66:69]
	v_mfma_f32_16x16x32_bf16 v[118:121], v[174:177], v[190:193], v[118:121]
	v_mfma_f32_16x16x32_bf16 v[114:117], v[182:185], v[190:193], v[114:117]
	v_mfma_f32_16x16x32_bf16 v[102:105], v[174:177], v[198:201], v[102:105]
	v_mfma_f32_16x16x32_bf16 v[98:101], v[182:185], v[198:201], v[98:101]
	v_mfma_f32_16x16x32_bf16 v[86:89], v[174:177], v[206:209], v[86:89]
	v_mfma_f32_16x16x32_bf16 v[82:85], v[182:185], v[206:209], v[82:85]
	v_mfma_f32_16x16x32_bf16 v[70:73], v[174:177], v[214:217], v[70:73]
	v_mfma_f32_16x16x32_bf16 v[66:69], v[182:185], v[214:217], v[66:69]
	s_barrier
; #define PG8_STAGEA(bufoff, gbase, voff) PG8_STAGE_X(bufoff, gbase, voff, AUXA)
; #define PG8_STAGEB(bufoff, gbase, voff) PG8_STAGE_X(bufoff, gbase, voff, AUXB)
; #define PG8_LDA(dst, b, h) do { _Pragma("unroll") for (int m = 0; m < 4; ++m) _Pragma("unroll") for (int k = 0; k < 2; ++k) dst[m][k] = *(const PG8_LAS bf16x8*)(lds + PG8_SA(b, h) + aoff + m * 2048 + k * 1024); } while (0)
; #define PG8_MMA(ai, bj, At, Bt) do { if (GEMM_PRIO_MODE == 0) __builtin_amdgcn_s_setprio(1); PG8_MMA_LOOPS \
;         acc[ai][bj][m][n] = __builtin_amdgcn_mfma_f32_16x16x32_bf16(Bt[n][k], At[m][k], acc[ai][bj][m][n], 0, 0, 0); if (GEMM_PRIO_MODE == 0) __builtin_amdgcn_s_setprio(0); } while (0)
; #define PG8_WAIT_V(n) asm volatile("s_waitcnt vmcnt(" #n ")" ::: "memory")
; #define PG8_WAIT_L(n) asm volatile("s_waitcnt lgkmcnt(" #n ")" ::: "memory")
; #define PG8_BAR __builtin_amdgcn_s_barrier()
; #define PG8_SCHED __builtin_amdgcn_sched_barrier(0)
;     ...
;             PG8_LDA(At, 1, 1); PG8_STAGEB(PG8_SB(1, 0), b3, voffB); PG8_STAGEB(PG8_SB(1, 1), b3 + hstepB, voffB); PG8_STAGEA(PG8_SA(1, 0), a3, voffA);
;             PG8_WAIT_V(8); PG8_WAIT_L(0); PG8_BAR; PG8_MMA(1, 0, At, B0); PG8_MMA(1, 1, At, B1); PG8_BAR; PG8_SCHED;
;     ...
;         if constexpr (ALIGN_EPI) { if (wr == 0) PG8_BAR; }
;         if constexpr (!Epi::AFTER_DRAIN) { E(acc, cur, wr, wc, fr, fq); S.done(cur); }
;         if (!has_next) break;
; #pragma unroll
;         for (int a = 0; a < 2; ++a)
; #pragma unroll
;             for (int b = 0; b < 2; ++b)
; #pragma unroll
;                 for (int m = 0; m < 4; ++m)
; #pragma unroll
;                     for (int n = 0; n < 2; ++n) acc[a][b][m][n] = (f32x4){0.f, 0.f, 0.f, 0.f};
;         cur = nxt; cA = nA; cB = nB; ++ui;
;         if constexpr (ALIGN_EPI) { if (wr == 1) PG8_BAR; }
;     }
;     PG8_WAIT_V(0);
;     if constexpr (!ALIGN_EPI) { if (wr == 0) PG8_BAR; }
;     PG8_BAR;
;     if (GEMM_PRIO_MODE == 2) __builtin_amdgcn_s_setprio(0);
	s_add_i32 s14, s18, s42
	v_lshl_add_u64 v[164:165], v[164:165], 0, s[86:87]
	s_mov_b32 m0, s14
	ds_read_b128 v[186:189], v172 offset:49152
	ds_read_b128 v[190:193], v172 offset:50176
	ds_read_b128 v[194:197], v172 offset:51200
	ds_read_b128 v[198:201], v172 offset:52224
	ds_read_b128 v[202:205], v172 offset:53248
	ds_read_b128 v[206:209], v172 offset:54272
	ds_read_b128 v[210:213], v172 offset:55296
	ds_read_b128 v[214:217], v172 offset:56320
	global_load_lds_dwordx4 v[164:165], off
	s_add_i32 m0, s14, 0x2000
	s_add_u32 s10, s10, 0x100080
	v_lshl_add_u64 v[164:165], v[218:219], 0, s[86:87]
	s_addc_u32 s11, s11, 0
	s_add_i32 s14, s19, s42
	global_load_lds_dwordx4 v[164:165], off
	v_lshl_add_u64 v[164:165], s[10:11], 0, v[142:143]
	s_mov_b32 m0, s14
	s_nop 0
	global_load_lds_dwordx4 v[164:165], off
	v_lshl_add_u64 v[164:165], s[10:11], 0, v[138:139]
	s_add_i32 m0, s14, 0x2000
	s_nop 0
	global_load_lds_dwordx4 v[164:165], off
	v_lshl_add_u64 v[164:165], v[220:221], 0, s[86:87]
	s_mov_b32 m0, s73
	s_nop 0
	global_load_lds_dwordx4 v[164:165], off
	v_lshl_add_u64 v[164:165], v[222:223], 0, s[86:87]
	s_mov_b32 m0, s82
	s_nop 0
	global_load_lds_dwordx4 v[164:165], off
	s_waitcnt vmcnt(8)
	s_waitcnt lgkmcnt(0)
	s_barrier
	v_mfma_f32_16x16x32_bf16 v[62:65], v[130:133], v[186:189], v[62:65]
	v_mfma_f32_16x16x32_bf16 v[58:61], v[152:155], v[186:189], v[58:61]
	v_mfma_f32_16x16x32_bf16 v[46:49], v[130:133], v[194:197], v[46:49]
	v_mfma_f32_16x16x32_bf16 v[42:45], v[152:155], v[194:197], v[42:45]
	v_mfma_f32_16x16x32_bf16 v[30:33], v[130:133], v[202:205], v[30:33]
	v_mfma_f32_16x16x32_bf16 v[26:29], v[152:155], v[202:205], v[26:29]
	v_mfma_f32_16x16x32_bf16 v[12:15], v[130:133], v[210:213], v[12:15]
	v_mfma_f32_16x16x32_bf16 v[8:11], v[152:155], v[210:213], v[8:11]
	v_mfma_f32_16x16x32_bf16 v[62:65], v[134:137], v[190:193], v[62:65]
	v_mfma_f32_16x16x32_bf16 v[58:61], v[156:159], v[190:193], v[58:61]
	v_mfma_f32_16x16x32_bf16 v[46:49], v[134:137], v[198:201], v[46:49]
	v_mfma_f32_16x16x32_bf16 v[42:45], v[156:159], v[198:201], v[42:45]
	v_mfma_f32_16x16x32_bf16 v[30:33], v[134:137], v[206:209], v[30:33]
	v_mfma_f32_16x16x32_bf16 v[26:29], v[156:159], v[206:209], v[26:29]
	v_mfma_f32_16x16x32_bf16 v[12:15], v[134:137], v[214:217], v[12:15]
	v_mfma_f32_16x16x32_bf16 v[8:11], v[156:159], v[214:217], v[8:11]
	v_mfma_f32_16x16x32_bf16 v[54:57], v[160:163], v[186:189], v[54:57]
	v_mfma_f32_16x16x32_bf16 v[50:53], v[178:181], v[186:189], v[50:53]
	v_mfma_f32_16x16x32_bf16 v[38:41], v[160:163], v[194:197], v[38:41]
	v_mfma_f32_16x16x32_bf16 v[34:37], v[178:181], v[194:197], v[34:37]
	v_mfma_f32_16x16x32_bf16 v[22:25], v[160:163], v[202:205], v[22:25]
	v_mfma_f32_16x16x32_bf16 v[18:21], v[178:181], v[202:205], v[18:21]
	v_mfma_f32_16x16x32_bf16 v[4:7], v[160:163], v[210:213], v[4:7]
	v_mfma_f32_16x16x32_bf16 v[0:3], v[178:181], v[210:213], v[0:3]
	v_mfma_f32_16x16x32_bf16 v[54:57], v[174:177], v[190:193], v[54:57]
	v_mfma_f32_16x16x32_bf16 v[50:53], v[182:185], v[190:193], v[50:53]
	v_mfma_f32_16x16x32_bf16 v[38:41], v[174:177], v[198:201], v[38:41]
	v_mfma_f32_16x16x32_bf16 v[34:37], v[182:185], v[198:201], v[34:37]
	v_mfma_f32_16x16x32_bf16 v[22:25], v[174:177], v[206:209], v[22:25]
	v_mfma_f32_16x16x32_bf16 v[18:21], v[182:185], v[206:209], v[18:21]
	v_mfma_f32_16x16x32_bf16 v[4:7], v[174:177], v[214:217], v[4:7]
	v_mfma_f32_16x16x32_bf16 v[0:3], v[182:185], v[214:217], v[0:3]
	s_barrier
	s_add_i32 s27, s27, 2
	s_add_u32 s8, s8, 0x100
	s_addc_u32 s9, s9, 0
	s_add_u32 s0, s0, 0x100
	s_addc_u32 s1, s1, 0
	s_cmp_gt_u32 s27, 61
	s_cbranch_scc0 .LBB0_129
	s_setprio 0
	s_and_b64 vcc, exec, s[24:25]
	s_cbranch_vccz .LBB0_132
	s_barrier

; #define PG8_STAGEA(bufoff, gbase, voff) PG8_STAGE_X(bufoff, gbase, voff, AUXA)
; #define PG8_STAGEB(bufoff, gbase, voff) PG8_STAGE_X(bufoff, gbase, voff, AUXB)
; #define PG8_LDA(dst, b, h) do { _Pragma("unroll") for (int m = 0; m < 4; ++m) _Pragma("unroll") for (int k = 0; k < 2; ++k) dst[m][k] = *(const PG8_LAS bf16x8*)(lds + PG8_SA(b, h) + aoff + m * 2048 + k * 1024); } while (0)
; #define PG8_LDB(dst, b, h) do { _Pragma("unroll") for (int n = 0; n < 2; ++n) _Pragma("unroll") for (int k = 0; k < 2; ++k) dst[n][k] = *(const PG8_LAS bf16x8*)(lds + PG8_SB(b, h) + boff + n * 2048 + k * 1024); } while (0)
; #define PG8_MMA(ai, bj, At, Bt) do { if (GEMM_PRIO_MODE == 0) __builtin_amdgcn_s_setprio(1); PG8_MMA_LOOPS \
;         acc[ai][bj][m][n] = __builtin_amdgcn_mfma_f32_16x16x32_bf16(Bt[n][k], At[m][k], acc[ai][bj][m][n], 0, 0, 0); if (GEMM_PRIO_MODE == 0) __builtin_amdgcn_s_setprio(0); } while (0)
; #define PG8_WAIT_V(n) asm volatile("s_waitcnt vmcnt(" #n ")" ::: "memory")
; #define PG8_WAIT_VR(n, nr, flag) asm volatile("s_cmp_eq_u32 %0, 0\n\ts_cbranch_scc1 .Lpg8s%=\n\ts_waitcnt vmcnt(" #nr ")\n\ts_branch .Lpg8d%=\n.Lpg8s%=:\n\ts_waitcnt vmcnt(" #n ")\n.Lpg8d%=:" :: "s"(flag) : "memory", "scc")
;     ...
;     if (GEMM_PRIO_MODE == 2 && wr == 1) __builtin_amdgcn_s_setprio(1);
;     ...
;         for (int t = t0; t < nt; t += 2) {
;             const bool last = (t == nt - 2);
;             const char* a1 = cA + (size_t)(t + 1) * kstepA;
;             const char* a2 = last ? nA : cA + (size_t)(t + 2) * kstepA; const char* b2 = last ? nB : cB + (size_t)(t + 2) * kstepB;
;             const char* a3 = a2 + kstepA; const char* b3 = b2 + kstepB;
;             if (last && has_next) S.a_ready(nxt);
;             if constexpr (SP2) {
;             PG8_LDB(B0, 0, 0); PG8_LDB(B1, 0, 1); PG8_SCHED; PG8_LDA(At, 0, 0); PG8_STAGEA(PG8_SA(1, 1), a1 + hstepA, voffA);
;     ...
;             const int relax = __builtin_amdgcn_readfirstlane((t == 0 && ui > 0) ? 1 : 0);
;             PG8_WAIT_VR(8, 24, relax); PG8_WAIT_L(0); PG8_BAR; PG8_MMA(0, 0, At, B0); PG8_MMA(0, 1, At, B1); PG8_BAR; PG8_SCHED;
;     ...
;             PG8_WAIT_V(8); PG8_WAIT_L(0); PG8_BAR; PG8_MMA(0, 0, At, B0); PG8_MMA(0, 1, At, B1); PG8_BAR; PG8_SCHED;
;     ...
;             PG8_LDA(At, 0, 1); PG8_STAGEB(PG8_SB(0, 0), b2, voffB); PG8_STAGEB(PG8_SB(0, 1), b2 + hstepB, voffB); PG8_STAGEA(PG8_SA(0, 0), a2, voffA);
.LBB0_557:
	s_ashr_i32 s21, s20, 31
	s_lshl_b64 s[6:7], s[20:21], 21
	s_add_u32 s24, s60, s6
	s_addc_u32 s25, s61, s7
	s_and_b64 s[6:7], s[26:27], exec
	s_cselect_b32 s21, s25, s1
	s_cselect_b32 s82, s24, s0
	s_ashr_i32 s23, s22, 31
	s_lshl_b64 s[6:7], s[22:23], 21
	s_add_u32 s36, s4, s6
	s_addc_u32 s37, s5, s7
	s_and_b64 s[6:7], s[26:27], exec
	s_cselect_b32 s23, s37, s41
	s_cselect_b32 s83, s36, s40
	s_add_u32 s38, s0, 0x100080
	s_addc_u32 s39, s1, 0
	s_add_u32 s0, s40, 0x100
	s_addc_u32 s1, s41, 0
	s_mov_b32 s90, -2
	s_waitcnt lgkmcnt(0)
	s_waitcnt vmcnt(0)
	s_and_b64 vcc, exec, s[18:19]
	s_cbranch_vccnz .Lsprio_g2
	s_setprio 1
.Lsprio_g2:
	s_add_u32 s6, s38, 0xfff00080
	s_addc_u32 s7, s39, -1
	s_add_i32 s91, 0, 0x10000
	s_cmp_eq_u32 s90, 60
	s_cselect_b32 s41, s21, s7
	s_cselect_b32 s40, s82, s6
	s_cselect_b32 s17, s23, s1
	s_cselect_b32 s16, s83, s0
	s_add_i32 s94, 0, 0x14000
	v_add_u32_e32 v152, s91, v157
	v_add_u32_e32 v174, s94, v157
	ds_read_b128 v[130:133], v152
	ds_read_b128 v[134:137], v152 offset:1024
	ds_read_b128 v[148:151], v152 offset:2048
	ds_read_b128 v[152:155], v152 offset:3072
	ds_read_b128 v[162:165], v174
	ds_read_b128 v[166:169], v174 offset:1024
	ds_read_b128 v[170:173], v174 offset:2048
	ds_read_b128 v[174:177], v174 offset:3072
	v_lshl_add_u64 v[210:211], s[38:39], 0, v[144:145]
	s_add_i32 m0, s13, 0xc000
	ds_read_b128 v[178:181], v161
	ds_read_b128 v[182:185], v161 offset:1024
	ds_read_b128 v[186:189], v161 offset:2048
	ds_read_b128 v[190:193], v161 offset:3072
	ds_read_b128 v[194:197], v161 offset:4096
	ds_read_b128 v[198:201], v161 offset:5120
	ds_read_b128 v[202:205], v161 offset:6144
	ds_read_b128 v[206:209], v161 offset:7168
	global_load_lds_dwordx4 v[210:211], off
	v_lshl_add_u64 v[210:211], s[38:39], 0, v[146:147]
	s_add_i32 m0, s13, 0xe000
	s_nop 0
	global_load_lds_dwordx4 v[210:211], off
	s_waitcnt vmcnt(8)
	s_waitcnt lgkmcnt(0)
	s_barrier
	v_mfma_f32_16x16x32_bf16 v[126:129], v[130:133], v[178:181], 0
	v_mfma_f32_16x16x32_bf16 v[122:125], v[148:151], v[178:181], 0
	v_mfma_f32_16x16x32_bf16 v[110:113], v[130:133], v[186:189], 0
	v_mfma_f32_16x16x32_bf16 v[106:109], v[148:151], v[186:189], 0
	v_mfma_f32_16x16x32_bf16 v[94:97], v[130:133], v[194:197], 0
	v_mfma_f32_16x16x32_bf16 v[90:93], v[148:151], v[194:197], 0
	v_mfma_f32_16x16x32_bf16 v[78:81], v[130:133], v[202:205], 0
	v_mfma_f32_16x16x32_bf16 v[74:77], v[148:151], v[202:205], 0
	v_mfma_f32_16x16x32_bf16 v[126:129], v[134:137], v[182:185], v[126:129]
	v_mfma_f32_16x16x32_bf16 v[122:125], v[152:155], v[182:185], v[122:125]
	v_mfma_f32_16x16x32_bf16 v[110:113], v[134:137], v[190:193], v[110:113]
	v_mfma_f32_16x16x32_bf16 v[106:109], v[152:155], v[190:193], v[106:109]
	v_mfma_f32_16x16x32_bf16 v[94:97], v[134:137], v[198:201], v[94:97]
	v_mfma_f32_16x16x32_bf16 v[90:93], v[152:155], v[198:201], v[90:93]
	v_mfma_f32_16x16x32_bf16 v[78:81], v[134:137], v[206:209], v[78:81]
	v_mfma_f32_16x16x32_bf16 v[74:77], v[152:155], v[206:209], v[74:77]
	v_mfma_f32_16x16x32_bf16 v[118:121], v[162:165], v[178:181], 0
	v_mfma_f32_16x16x32_bf16 v[114:117], v[170:173], v[178:181], 0
	v_mfma_f32_16x16x32_bf16 v[102:105], v[162:165], v[186:189], 0
	v_mfma_f32_16x16x32_bf16 v[98:101], v[170:173], v[186:189], 0
	v_mfma_f32_16x16x32_bf16 v[86:89], v[162:165], v[194:197], 0
	v_mfma_f32_16x16x32_bf16 v[82:85], v[170:173], v[194:197], 0
	v_mfma_f32_16x16x32_bf16 v[70:73], v[162:165], v[202:205], 0
	v_mfma_f32_16x16x32_bf16 v[66:69], v[170:173], v[202:205], 0
	v_mfma_f32_16x16x32_bf16 v[118:121], v[166:169], v[182:185], v[118:121]
	v_mfma_f32_16x16x32_bf16 v[114:117], v[174:177], v[182:185], v[114:117]
	v_mfma_f32_16x16x32_bf16 v[102:105], v[166:169], v[190:193], v[102:105]
	v_mfma_f32_16x16x32_bf16 v[98:101], v[174:177], v[190:193], v[98:101]
	v_mfma_f32_16x16x32_bf16 v[86:89], v[166:169], v[198:201], v[86:89]
	v_mfma_f32_16x16x32_bf16 v[82:85], v[174:177], v[198:201], v[82:85]
	v_mfma_f32_16x16x32_bf16 v[70:73], v[166:169], v[206:209], v[70:73]
	v_mfma_f32_16x16x32_bf16 v[66:69], v[174:177], v[206:209], v[66:69]
	s_barrier
	s_add_i32 s6, s91, s12
	v_lshl_add_u64 v[210:211], s[16:17], 0, v[16:17]
	s_mov_b32 m0, s6
	ds_read_b128 v[178:181], v161 offset:16384
	ds_read_b128 v[182:185], v161 offset:17408
	ds_read_b128 v[186:189], v161 offset:18432
	ds_read_b128 v[190:193], v161 offset:19456
	ds_read_b128 v[194:197], v161 offset:20480
	ds_read_b128 v[198:201], v161 offset:21504
	ds_read_b128 v[202:205], v161 offset:22528
	ds_read_b128 v[206:209], v161 offset:23552
	global_load_lds_dwordx4 v[210:211], off
	s_add_i32 m0, s6, 0x2000
	s_add_u32 s6, s16, 0x100000
	v_lshl_add_u64 v[212:213], s[16:17], 0, v[138:139]
	s_addc_u32 s7, s17, 0
	s_add_i32 s91, s94, s12
	global_load_lds_dwordx4 v[212:213], off
	v_lshl_add_u64 v[214:215], s[6:7], 0, v[16:17]
	s_mov_b32 m0, s91
	v_lshl_add_u64 v[216:217], s[40:41], 0, v[140:141]
	global_load_lds_dwordx4 v[214:215], off
	v_lshl_add_u64 v[214:215], s[6:7], 0, v[138:139]
	s_add_i32 m0, s91, 0x2000
	s_nop 0
	global_load_lds_dwordx4 v[214:215], off
	v_lshl_add_u64 v[214:215], s[40:41], 0, v[142:143]
	s_mov_b32 m0, s13
	s_nop 0
	global_load_lds_dwordx4 v[214:215], off
	s_mov_b32 m0, s42
	s_nop 0
	global_load_lds_dwordx4 v[216:217], off
	s_waitcnt vmcnt(8)
	s_waitcnt lgkmcnt(0)
	s_barrier
; #define PG8_STAGEA(bufoff, gbase, voff) PG8_STAGE_X(bufoff, gbase, voff, AUXA)
; #define PG8_STAGEB(bufoff, gbase, voff) PG8_STAGE_X(bufoff, gbase, voff, AUXB)
; #define PG8_LDA(dst, b, h) do { _Pragma("unroll") for (int m = 0; m < 4; ++m) _Pragma("unroll") for (int k = 0; k < 2; ++k) dst[m][k] = *(const PG8_LAS bf16x8*)(lds + PG8_SA(b, h) + aoff + m * 2048 + k * 1024); } while (0)
; #define PG8_LDB(dst, b, h) do { _Pragma("unroll") for (int n = 0; n < 2; ++n) _Pragma("unroll") for (int k = 0; k < 2; ++k) dst[n][k] = *(const PG8_LAS bf16x8*)(lds + PG8_SB(b, h) + boff + n * 2048 + k * 1024); } while (0)
; #define PG8_MMA(ai, bj, At, Bt) do { if (GEMM_PRIO_MODE == 0) __builtin_amdgcn_s_setprio(1); PG8_MMA_LOOPS \
;         acc[ai][bj][m][n] = __builtin_amdgcn_mfma_f32_16x16x32_bf16(Bt[n][k], At[m][k], acc[ai][bj][m][n], 0, 0, 0); if (GEMM_PRIO_MODE == 0) __builtin_amdgcn_s_setprio(0); } while (0)
; #define PG8_WAIT_V(n) asm volatile("s_waitcnt vmcnt(" #n ")" ::: "memory")
;     ...
;             PG8_LDB(B0, 0, 0); PG8_LDB(B1, 0, 1); PG8_SCHED; PG8_LDA(At, 0, 0); PG8_STAGEA(PG8_SA(1, 1), a1 + hstepA, voffA);
;     ...
;             const int relax = __builtin_amdgcn_readfirstlane((t == 0 && ui > 0) ? 1 : 0);
;             PG8_WAIT_VR(8, 24, relax); PG8_WAIT_L(0); PG8_BAR; PG8_MMA(0, 0, At, B0); PG8_MMA(0, 1, At, B1); PG8_BAR; PG8_SCHED;
;     ...
;             PG8_WAIT_V(8); PG8_WAIT_L(0); PG8_BAR; PG8_MMA(0, 0, At, B0); PG8_MMA(0, 1, At, B1); PG8_BAR; PG8_SCHED;
;     ...
;             PG8_LDA(At, 0, 1); PG8_STAGEB(PG8_SB(0, 0), b2, voffB); PG8_STAGEB(PG8_SB(0, 1), b2 + hstepB, voffB); PG8_STAGEA(PG8_SA(0, 0), a2, voffA);
;     ...
;             PG8_WAIT_VR(8, 24, relax); PG8_WAIT_L(0); PG8_BAR; PG8_MMA(1, 0, At, B0); PG8_MMA(1, 1, At, B1); PG8_BAR; PG8_SCHED;
;     ...
;             PG8_WAIT_V(8); PG8_WAIT_L(0); PG8_BAR; PG8_MMA(1, 0, At, B0); PG8_MMA(1, 1, At, B1); PG8_BAR; PG8_SCHED;
;     ...
;             PG8_LDB(B0, 1, 0); PG8_LDB(B1, 1, 1); PG8_SCHED; PG8_LDA(At, 1, 0); PG8_STAGEA(PG8_SA(0, 1), a2 + hstepA, voffA);
;             PG8_WAIT_V(8); PG8_WAIT_L(0); PG8_BAR; PG8_MMA(0, 0, At, B0); PG8_MMA(0, 1, At, B1); PG8_BAR; PG8_SCHED;
;             PG8_LDA(At, 1, 1); PG8_STAGEB(PG8_SB(1, 0), b3, voffB); PG8_STAGEB(PG8_SB(1, 1), b3 + hstepB, voffB); PG8_STAGEA(PG8_SA(1, 0), a3, voffA);
;             PG8_WAIT_V(8); PG8_WAIT_L(0); PG8_BAR; PG8_MMA(1, 0, At, B0); PG8_MMA(1, 1, At, B1); PG8_BAR; PG8_SCHED;
	v_mfma_f32_16x16x32_bf16 v[62:65], v[130:133], v[178:181], 0
	v_mfma_f32_16x16x32_bf16 v[58:61], v[148:151], v[178:181], 0
	v_mfma_f32_16x16x32_bf16 v[46:49], v[130:133], v[186:189], 0
	v_mfma_f32_16x16x32_bf16 v[42:45], v[148:151], v[186:189], 0
	v_mfma_f32_16x16x32_bf16 v[30:33], v[130:133], v[194:197], 0
	v_mfma_f32_16x16x32_bf16 v[26:29], v[148:151], v[194:197], 0
	v_mfma_f32_16x16x32_bf16 v[12:15], v[130:133], v[202:205], 0
	v_mfma_f32_16x16x32_bf16 v[8:11], v[148:151], v[202:205], 0
	v_mfma_f32_16x16x32_bf16 v[62:65], v[134:137], v[182:185], v[62:65]
	v_mfma_f32_16x16x32_bf16 v[58:61], v[152:155], v[182:185], v[58:61]
	v_mfma_f32_16x16x32_bf16 v[46:49], v[134:137], v[190:193], v[46:49]
	v_mfma_f32_16x16x32_bf16 v[42:45], v[152:155], v[190:193], v[42:45]
	v_mfma_f32_16x16x32_bf16 v[30:33], v[134:137], v[198:201], v[30:33]
	v_mfma_f32_16x16x32_bf16 v[26:29], v[152:155], v[198:201], v[26:29]
	v_mfma_f32_16x16x32_bf16 v[12:15], v[134:137], v[206:209], v[12:15]
	v_mfma_f32_16x16x32_bf16 v[8:11], v[152:155], v[206:209], v[8:11]
	v_mfma_f32_16x16x32_bf16 v[54:57], v[162:165], v[178:181], 0
	v_mfma_f32_16x16x32_bf16 v[50:53], v[170:173], v[178:181], 0
	v_mfma_f32_16x16x32_bf16 v[38:41], v[162:165], v[186:189], 0
	v_mfma_f32_16x16x32_bf16 v[34:37], v[170:173], v[186:189], 0
	v_mfma_f32_16x16x32_bf16 v[22:25], v[162:165], v[194:197], 0
	v_mfma_f32_16x16x32_bf16 v[18:21], v[170:173], v[194:197], 0
	v_mfma_f32_16x16x32_bf16 v[4:7], v[162:165], v[202:205], 0
	v_mfma_f32_16x16x32_bf16 v[0:3], v[170:173], v[202:205], 0
	v_mfma_f32_16x16x32_bf16 v[54:57], v[166:169], v[182:185], v[54:57]
	v_mfma_f32_16x16x32_bf16 v[50:53], v[174:177], v[182:185], v[50:53]
	v_mfma_f32_16x16x32_bf16 v[38:41], v[166:169], v[190:193], v[38:41]
	v_mfma_f32_16x16x32_bf16 v[34:37], v[174:177], v[190:193], v[34:37]
	v_mfma_f32_16x16x32_bf16 v[22:25], v[166:169], v[198:201], v[22:25]
	v_mfma_f32_16x16x32_bf16 v[18:21], v[174:177], v[198:201], v[18:21]
	v_mfma_f32_16x16x32_bf16 v[4:7], v[166:169], v[206:209], v[4:7]
	v_mfma_f32_16x16x32_bf16 v[0:3], v[174:177], v[206:209], v[0:3]
	s_barrier
	s_add_i32 s91, 0, 0x18000
	s_add_i32 s94, 0, 0x1c000
	v_add_u32_e32 v152, s91, v157
	v_add_u32_e32 v174, s94, v157
	ds_read_b128 v[130:133], v152
	ds_read_b128 v[134:137], v152 offset:1024
	ds_read_b128 v[148:151], v152 offset:2048
	ds_read_b128 v[152:155], v152 offset:3072
	ds_read_b128 v[162:165], v174
	ds_read_b128 v[166:169], v174 offset:1024
	ds_read_b128 v[170:173], v174 offset:2048
	ds_read_b128 v[174:177], v174 offset:3072
	s_add_u32 s6, s40, 0x100000
	s_addc_u32 s7, s41, 0
	s_mov_b32 m0, s43
	v_lshl_add_u64 v[218:219], s[6:7], 0, v[142:143]
	ds_read_b128 v[178:181], v161 offset:32768
	ds_read_b128 v[182:185], v161 offset:33792
	ds_read_b128 v[186:189], v161 offset:34816
	ds_read_b128 v[190:193], v161 offset:35840
	ds_read_b128 v[194:197], v161 offset:36864
	ds_read_b128 v[198:201], v161 offset:37888
	ds_read_b128 v[202:205], v161 offset:38912
	ds_read_b128 v[206:209], v161 offset:39936
	global_load_lds_dwordx4 v[218:219], off
	v_lshl_add_u64 v[218:219], s[6:7], 0, v[140:141]
	s_mov_b32 m0, s50
	s_nop 0
	global_load_lds_dwordx4 v[218:219], off
	s_waitcnt vmcnt(8)
	s_waitcnt lgkmcnt(0)
	s_barrier
	v_mfma_f32_16x16x32_bf16 v[126:129], v[130:133], v[178:181], v[126:129]
	v_mfma_f32_16x16x32_bf16 v[122:125], v[148:151], v[178:181], v[122:125]
	v_mfma_f32_16x16x32_bf16 v[110:113], v[130:133], v[186:189], v[110:113]
	v_mfma_f32_16x16x32_bf16 v[106:109], v[148:151], v[186:189], v[106:109]
	v_mfma_f32_16x16x32_bf16 v[94:97], v[130:133], v[194:197], v[94:97]
	v_mfma_f32_16x16x32_bf16 v[90:93], v[148:151], v[194:197], v[90:93]
	v_mfma_f32_16x16x32_bf16 v[78:81], v[130:133], v[202:205], v[78:81]
	v_mfma_f32_16x16x32_bf16 v[74:77], v[148:151], v[202:205], v[74:77]
	v_mfma_f32_16x16x32_bf16 v[126:129], v[134:137], v[182:185], v[126:129]
	v_mfma_f32_16x16x32_bf16 v[122:125], v[152:155], v[182:185], v[122:125]
	v_mfma_f32_16x16x32_bf16 v[110:113], v[134:137], v[190:193], v[110:113]
	v_mfma_f32_16x16x32_bf16 v[106:109], v[152:155], v[190:193], v[106:109]
	v_mfma_f32_16x16x32_bf16 v[94:97], v[134:137], v[198:201], v[94:97]
	v_mfma_f32_16x16x32_bf16 v[90:93], v[152:155], v[198:201], v[90:93]
	v_mfma_f32_16x16x32_bf16 v[78:81], v[134:137], v[206:209], v[78:81]
	v_mfma_f32_16x16x32_bf16 v[74:77], v[152:155], v[206:209], v[74:77]
	v_mfma_f32_16x16x32_bf16 v[118:121], v[162:165], v[178:181], v[118:121]
	v_mfma_f32_16x16x32_bf16 v[114:117], v[170:173], v[178:181], v[114:117]
	v_mfma_f32_16x16x32_bf16 v[102:105], v[162:165], v[186:189], v[102:105]
	v_mfma_f32_16x16x32_bf16 v[98:101], v[170:173], v[186:189], v[98:101]
	v_mfma_f32_16x16x32_bf16 v[86:89], v[162:165], v[194:197], v[86:89]
	v_mfma_f32_16x16x32_bf16 v[82:85], v[170:173], v[194:197], v[82:85]
	v_mfma_f32_16x16x32_bf16 v[70:73], v[162:165], v[202:205], v[70:73]
	v_mfma_f32_16x16x32_bf16 v[66:69], v[170:173], v[202:205], v[66:69]
	v_mfma_f32_16x16x32_bf16 v[118:121], v[166:169], v[182:185], v[118:121]
	v_mfma_f32_16x16x32_bf16 v[114:117], v[174:177], v[182:185], v[114:117]
	v_mfma_f32_16x16x32_bf16 v[102:105], v[166:169], v[190:193], v[102:105]
	v_mfma_f32_16x16x32_bf16 v[98:101], v[174:177], v[190:193], v[98:101]
	v_mfma_f32_16x16x32_bf16 v[86:89], v[166:169], v[198:201], v[86:89]
	v_mfma_f32_16x16x32_bf16 v[82:85], v[174:177], v[198:201], v[82:85]
	v_mfma_f32_16x16x32_bf16 v[70:73], v[166:169], v[206:209], v[70:73]
	v_mfma_f32_16x16x32_bf16 v[66:69], v[174:177], v[206:209], v[66:69]
	s_barrier
; #define PG8_STAGEA(bufoff, gbase, voff) PG8_STAGE_X(bufoff, gbase, voff, AUXA)
; #define PG8_STAGEB(bufoff, gbase, voff) PG8_STAGE_X(bufoff, gbase, voff, AUXB)
; #define PG8_LDA(dst, b, h) do { _Pragma("unroll") for (int m = 0; m < 4; ++m) _Pragma("unroll") for (int k = 0; k < 2; ++k) dst[m][k] = *(const PG8_LAS bf16x8*)(lds + PG8_SA(b, h) + aoff + m * 2048 + k * 1024); } while (0)
; #define PG8_WAIT_V(n) asm volatile("s_waitcnt vmcnt(" #n ")" ::: "memory")
; #define PG8_WAIT_L(n) asm volatile("s_waitcnt lgkmcnt(" #n ")" ::: "memory")
;     ...
;         for (int t = t0; t < nt; t += 2) {
;             const bool last = (t == nt - 2);
;             const char* a1 = cA + (size_t)(t + 1) * kstepA;
;             const char* a2 = last ? nA : cA + (size_t)(t + 2) * kstepA; const char* b2 = last ? nB : cB + (size_t)(t + 2) * kstepB;
;             const char* a3 = a2 + kstepA; const char* b3 = b2 + kstepB;
;             if (last && has_next) S.a_ready(nxt);
;             if constexpr (SP2) {
;             PG8_LDB(B0, 0, 0); PG8_LDB(B1, 0, 1); PG8_SCHED; PG8_LDA(At, 0, 0); PG8_STAGEA(PG8_SA(1, 1), a1 + hstepA, voffA);
;     ...
;             const int relax = __builtin_amdgcn_readfirstlane((t == 0 && ui > 0) ? 1 : 0);
;             PG8_WAIT_VR(8, 24, relax); PG8_WAIT_L(0); PG8_BAR; PG8_MMA(0, 0, At, B0); PG8_MMA(0, 1, At, B1); PG8_BAR; PG8_SCHED;
;     ...
;             PG8_WAIT_V(8); PG8_WAIT_L(0); PG8_BAR; PG8_MMA(0, 0, At, B0); PG8_MMA(0, 1, At, B1); PG8_BAR; PG8_SCHED;
;     ...
;             PG8_LDA(At, 0, 1); PG8_STAGEB(PG8_SB(0, 0), b2, voffB); PG8_STAGEB(PG8_SB(0, 1), b2 + hstepB, voffB); PG8_STAGEA(PG8_SA(0, 0), a2, voffA);
;     ...
;             PG8_WAIT_VR(8, 24, relax); PG8_WAIT_L(0); PG8_BAR; PG8_MMA(1, 0, At, B0); PG8_MMA(1, 1, At, B1); PG8_BAR; PG8_SCHED;
;     ...
;             PG8_WAIT_V(8); PG8_WAIT_L(0); PG8_BAR; PG8_MMA(1, 0, At, B0); PG8_MMA(1, 1, At, B1); PG8_BAR; PG8_SCHED;
;     ...
;             PG8_LDB(B0, 1, 0); PG8_LDB(B1, 1, 1); PG8_SCHED; PG8_LDA(At, 1, 0); PG8_STAGEA(PG8_SA(0, 1), a2 + hstepA, voffA);
;             PG8_WAIT_V(8); PG8_WAIT_L(0); PG8_BAR; PG8_MMA(0, 0, At, B0); PG8_MMA(0, 1, At, B1); PG8_BAR; PG8_SCHED;
;             PG8_LDA(At, 1, 1); PG8_STAGEB(PG8_SB(1, 0), b3, voffB); PG8_STAGEB(PG8_SB(1, 1), b3 + hstepB, voffB); PG8_STAGEA(PG8_SA(1, 0), a3, voffA);
;             PG8_WAIT_V(8); PG8_WAIT_L(0); PG8_BAR; PG8_MMA(1, 0, At, B0); PG8_MMA(1, 1, At, B1); PG8_BAR; PG8_SCHED;
	s_add_i32 s6, s91, s12
	v_lshl_add_u64 v[210:211], v[210:211], 0, s[86:87]
	s_mov_b32 m0, s6
	ds_read_b128 v[178:181], v161 offset:49152
	ds_read_b128 v[182:185], v161 offset:50176
	ds_read_b128 v[186:189], v161 offset:51200
	ds_read_b128 v[190:193], v161 offset:52224
	ds_read_b128 v[194:197], v161 offset:53248
	ds_read_b128 v[198:201], v161 offset:54272
	ds_read_b128 v[202:205], v161 offset:55296
	ds_read_b128 v[206:209], v161 offset:56320
	global_load_lds_dwordx4 v[210:211], off
	s_add_i32 m0, s6, 0x2000
	s_add_u32 s6, s16, 0x100080
	v_lshl_add_u64 v[210:211], v[212:213], 0, s[86:87]
	s_addc_u32 s7, s17, 0
	s_add_i32 s16, s94, s12
	global_load_lds_dwordx4 v[210:211], off
	v_lshl_add_u64 v[210:211], s[6:7], 0, v[16:17]
	s_mov_b32 m0, s16
	s_nop 0
	global_load_lds_dwordx4 v[210:211], off
	v_lshl_add_u64 v[210:211], s[6:7], 0, v[138:139]
	s_add_i32 m0, s16, 0x2000
	s_nop 0
	global_load_lds_dwordx4 v[210:211], off
	v_lshl_add_u64 v[210:211], v[214:215], 0, s[86:87]
	s_mov_b32 m0, s68
	s_nop 0
	global_load_lds_dwordx4 v[210:211], off
	v_lshl_add_u64 v[210:211], v[216:217], 0, s[86:87]
	s_mov_b32 m0, s69
	s_nop 0
	global_load_lds_dwordx4 v[210:211], off
	s_waitcnt vmcnt(8)
	s_waitcnt lgkmcnt(0)
	s_barrier
	v_mfma_f32_16x16x32_bf16 v[62:65], v[130:133], v[178:181], v[62:65]
	v_mfma_f32_16x16x32_bf16 v[58:61], v[148:151], v[178:181], v[58:61]
	v_mfma_f32_16x16x32_bf16 v[46:49], v[130:133], v[186:189], v[46:49]
	v_mfma_f32_16x16x32_bf16 v[42:45], v[148:151], v[186:189], v[42:45]
	v_mfma_f32_16x16x32_bf16 v[30:33], v[130:133], v[194:197], v[30:33]
	v_mfma_f32_16x16x32_bf16 v[26:29], v[148:151], v[194:197], v[26:29]
	v_mfma_f32_16x16x32_bf16 v[12:15], v[130:133], v[202:205], v[12:15]
	v_mfma_f32_16x16x32_bf16 v[8:11], v[148:151], v[202:205], v[8:11]
	v_mfma_f32_16x16x32_bf16 v[62:65], v[134:137], v[182:185], v[62:65]
	v_mfma_f32_16x16x32_bf16 v[58:61], v[152:155], v[182:185], v[58:61]
	v_mfma_f32_16x16x32_bf16 v[46:49], v[134:137], v[190:193], v[46:49]
	v_mfma_f32_16x16x32_bf16 v[42:45], v[152:155], v[190:193], v[42:45]
	v_mfma_f32_16x16x32_bf16 v[30:33], v[134:137], v[198:201], v[30:33]
	v_mfma_f32_16x16x32_bf16 v[26:29], v[152:155], v[198:201], v[26:29]
	v_mfma_f32_16x16x32_bf16 v[12:15], v[134:137], v[206:209], v[12:15]
	v_mfma_f32_16x16x32_bf16 v[8:11], v[152:155], v[206:209], v[8:11]
	v_mfma_f32_16x16x32_bf16 v[54:57], v[162:165], v[178:181], v[54:57]
	v_mfma_f32_16x16x32_bf16 v[50:53], v[170:173], v[178:181], v[50:53]
	v_mfma_f32_16x16x32_bf16 v[38:41], v[162:165], v[186:189], v[38:41]
	v_mfma_f32_16x16x32_bf16 v[34:37], v[170:173], v[186:189], v[34:37]
	v_mfma_f32_16x16x32_bf16 v[22:25], v[162:165], v[194:197], v[22:25]
	v_mfma_f32_16x16x32_bf16 v[18:21], v[170:173], v[194:197], v[18:21]
	v_mfma_f32_16x16x32_bf16 v[4:7], v[162:165], v[202:205], v[4:7]
	v_mfma_f32_16x16x32_bf16 v[0:3], v[170:173], v[202:205], v[0:3]
	v_mfma_f32_16x16x32_bf16 v[54:57], v[166:169], v[182:185], v[54:57]
	v_mfma_f32_16x16x32_bf16 v[50:53], v[174:177], v[182:185], v[50:53]
	v_mfma_f32_16x16x32_bf16 v[38:41], v[166:169], v[190:193], v[38:41]
	v_mfma_f32_16x16x32_bf16 v[34:37], v[174:177], v[190:193], v[34:37]
	v_mfma_f32_16x16x32_bf16 v[22:25], v[166:169], v[198:201], v[22:25]
	v_mfma_f32_16x16x32_bf16 v[18:21], v[174:177], v[198:201], v[18:21]
	v_mfma_f32_16x16x32_bf16 v[4:7], v[166:169], v[206:209], v[4:7]
	v_mfma_f32_16x16x32_bf16 v[0:3], v[174:177], v[206:209], v[0:3]
	s_barrier
	s_add_i32 s90, s90, 2
	s_add_u32 s38, s38, 0x100
	s_addc_u32 s39, s39, 0
	s_add_u32 s0, s0, 0x100
	s_addc_u32 s1, s1, 0
.LBB0_558:
	s_add_u32 s6, s38, 0xfff00080
	s_addc_u32 s7, s39, -1
	s_add_i32 s91, 0, 0x10000
	s_cmp_eq_u32 s90, 60
	s_cselect_b32 s41, s21, s7
	s_cselect_b32 s40, s82, s6
	s_cselect_b32 s17, s23, s1
	s_cselect_b32 s16, s83, s0
	s_add_i32 s94, 0, 0x14000
	v_add_u32_e32 v152, s91, v157
	v_add_u32_e32 v174, s94, v157
	ds_read_b128 v[130:133], v152
	ds_read_b128 v[134:137], v152 offset:1024
	ds_read_b128 v[148:151], v152 offset:2048
	ds_read_b128 v[152:155], v152 offset:3072
	ds_read_b128 v[162:165], v174
	ds_read_b128 v[166:169], v174 offset:1024
	ds_read_b128 v[170:173], v174 offset:2048
	ds_read_b128 v[174:177], v174 offset:3072
	v_lshl_add_u64 v[210:211], s[38:39], 0, v[144:145]
	s_add_i32 m0, s13, 0xc000
	ds_read_b128 v[178:181], v161
	ds_read_b128 v[182:185], v161 offset:1024
	ds_read_b128 v[186:189], v161 offset:2048
	ds_read_b128 v[190:193], v161 offset:3072
	ds_read_b128 v[194:197], v161 offset:4096
	ds_read_b128 v[198:201], v161 offset:5120
	ds_read_b128 v[202:205], v161 offset:6144
	ds_read_b128 v[206:209], v161 offset:7168
	global_load_lds_dwordx4 v[210:211], off
	v_lshl_add_u64 v[210:211], s[38:39], 0, v[146:147]
	s_add_i32 m0, s13, 0xe000
	s_nop 0
	global_load_lds_dwordx4 v[210:211], off
	s_waitcnt vmcnt(8)
	s_waitcnt lgkmcnt(0)
	s_barrier
; #define PG8_STAGEA(bufoff, gbase, voff) PG8_STAGE_X(bufoff, gbase, voff, AUXA)
; #define PG8_STAGEB(bufoff, gbase, voff) PG8_STAGE_X(bufoff, gbase, voff, AUXB)
; #define PG8_LDA(dst, b, h) do { _Pragma("unroll") for (int m = 0; m < 4; ++m) _Pragma("unroll") for (int k = 0; k < 2; ++k) dst[m][k] = *(const PG8_LAS bf16x8*)(lds + PG8_SA(b, h) + aoff + m * 2048 + k * 1024); } while (0)
; #define PG8_LDB(dst, b, h) do { _Pragma("unroll") for (int n = 0; n < 2; ++n) _Pragma("unroll") for (int k = 0; k < 2; ++k) dst[n][k] = *(const PG8_LAS bf16x8*)(lds + PG8_SB(b, h) + boff + n * 2048 + k * 1024); } while (0)
; #define PG8_MMA(ai, bj, At, Bt) do { if (GEMM_PRIO_MODE == 0) __builtin_amdgcn_s_setprio(1); PG8_MMA_LOOPS \
;         acc[ai][bj][m][n] = __builtin_amdgcn_mfma_f32_16x16x32_bf16(Bt[n][k], At[m][k], acc[ai][bj][m][n], 0, 0, 0); if (GEMM_PRIO_MODE == 0) __builtin_amdgcn_s_setprio(0); } while (0)
; #define PG8_WAIT_V(n) asm volatile("s_waitcnt vmcnt(" #n ")" ::: "memory")
;     ...
;             PG8_LDB(B0, 0, 0); PG8_LDB(B1, 0, 1); PG8_SCHED; PG8_LDA(At, 0, 0); PG8_STAGEA(PG8_SA(1, 1), a1 + hstepA, voffA);
;     ...
;             const int relax = __builtin_amdgcn_readfirstlane((t == 0 && ui > 0) ? 1 : 0);
;             PG8_WAIT_VR(8, 24, relax); PG8_WAIT_L(0); PG8_BAR; PG8_MMA(0, 0, At, B0); PG8_MMA(0, 1, At, B1); PG8_BAR; PG8_SCHED;
;     ...
;             PG8_WAIT_V(8); PG8_WAIT_L(0); PG8_BAR; PG8_MMA(0, 0, At, B0); PG8_MMA(0, 1, At, B1); PG8_BAR; PG8_SCHED;
;     ...
;             PG8_LDA(At, 0, 1); PG8_STAGEB(PG8_SB(0, 0), b2, voffB); PG8_STAGEB(PG8_SB(0, 1), b2 + hstepB, voffB); PG8_STAGEA(PG8_SA(0, 0), a2, voffA);
;     ...
;             PG8_WAIT_VR(8, 24, relax); PG8_WAIT_L(0); PG8_BAR; PG8_MMA(1, 0, At, B0); PG8_MMA(1, 1, At, B1); PG8_BAR; PG8_SCHED;
;     ...
;             PG8_WAIT_V(8); PG8_WAIT_L(0); PG8_BAR; PG8_MMA(1, 0, At, B0); PG8_MMA(1, 1, At, B1); PG8_BAR; PG8_SCHED;
;     ...
;             PG8_LDB(B0, 1, 0); PG8_LDB(B1, 1, 1); PG8_SCHED; PG8_LDA(At, 1, 0); PG8_STAGEA(PG8_SA(0, 1), a2 + hstepA, voffA);
;             PG8_WAIT_V(8); PG8_WAIT_L(0); PG8_BAR; PG8_MMA(0, 0, At, B0); PG8_MMA(0, 1, At, B1); PG8_BAR; PG8_SCHED;
;             PG8_LDA(At, 1, 1); PG8_STAGEB(PG8_SB(1, 0), b3, voffB); PG8_STAGEB(PG8_SB(1, 1), b3 + hstepB, voffB); PG8_STAGEA(PG8_SA(1, 0), a3, voffA);
;             PG8_WAIT_V(8); PG8_WAIT_L(0); PG8_BAR; PG8_MMA(1, 0, At, B0); PG8_MMA(1, 1, At, B1); PG8_BAR; PG8_SCHED;
	v_mfma_f32_16x16x32_bf16 v[126:129], v[130:133], v[178:181], v[126:129]
	v_mfma_f32_16x16x32_bf16 v[122:125], v[148:151], v[178:181], v[122:125]
	v_mfma_f32_16x16x32_bf16 v[110:113], v[130:133], v[186:189], v[110:113]
	v_mfma_f32_16x16x32_bf16 v[106:109], v[148:151], v[186:189], v[106:109]
	v_mfma_f32_16x16x32_bf16 v[94:97], v[130:133], v[194:197], v[94:97]
	v_mfma_f32_16x16x32_bf16 v[90:93], v[148:151], v[194:197], v[90:93]
	v_mfma_f32_16x16x32_bf16 v[78:81], v[130:133], v[202:205], v[78:81]
	v_mfma_f32_16x16x32_bf16 v[74:77], v[148:151], v[202:205], v[74:77]
	v_mfma_f32_16x16x32_bf16 v[126:129], v[134:137], v[182:185], v[126:129]
	v_mfma_f32_16x16x32_bf16 v[122:125], v[152:155], v[182:185], v[122:125]
	v_mfma_f32_16x16x32_bf16 v[110:113], v[134:137], v[190:193], v[110:113]
	v_mfma_f32_16x16x32_bf16 v[106:109], v[152:155], v[190:193], v[106:109]
	v_mfma_f32_16x16x32_bf16 v[94:97], v[134:137], v[198:201], v[94:97]
	v_mfma_f32_16x16x32_bf16 v[90:93], v[152:155], v[198:201], v[90:93]
	v_mfma_f32_16x16x32_bf16 v[78:81], v[134:137], v[206:209], v[78:81]
	v_mfma_f32_16x16x32_bf16 v[74:77], v[152:155], v[206:209], v[74:77]
	v_mfma_f32_16x16x32_bf16 v[118:121], v[162:165], v[178:181], v[118:121]
	v_mfma_f32_16x16x32_bf16 v[114:117], v[170:173], v[178:181], v[114:117]
	v_mfma_f32_16x16x32_bf16 v[102:105], v[162:165], v[186:189], v[102:105]
	v_mfma_f32_16x16x32_bf16 v[98:101], v[170:173], v[186:189], v[98:101]
	v_mfma_f32_16x16x32_bf16 v[86:89], v[162:165], v[194:197], v[86:89]
	v_mfma_f32_16x16x32_bf16 v[82:85], v[170:173], v[194:197], v[82:85]
	v_mfma_f32_16x16x32_bf16 v[70:73], v[162:165], v[202:205], v[70:73]
	v_mfma_f32_16x16x32_bf16 v[66:69], v[170:173], v[202:205], v[66:69]
	v_mfma_f32_16x16x32_bf16 v[118:121], v[166:169], v[182:185], v[118:121]
	v_mfma_f32_16x16x32_bf16 v[114:117], v[174:177], v[182:185], v[114:117]
	v_mfma_f32_16x16x32_bf16 v[102:105], v[166:169], v[190:193], v[102:105]
	v_mfma_f32_16x16x32_bf16 v[98:101], v[174:177], v[190:193], v[98:101]
	v_mfma_f32_16x16x32_bf16 v[86:89], v[166:169], v[198:201], v[86:89]
	v_mfma_f32_16x16x32_bf16 v[82:85], v[174:177], v[198:201], v[82:85]
	v_mfma_f32_16x16x32_bf16 v[70:73], v[166:169], v[206:209], v[70:73]
	v_mfma_f32_16x16x32_bf16 v[66:69], v[174:177], v[206:209], v[66:69]
	s_barrier
	s_add_i32 s6, s91, s12
	v_lshl_add_u64 v[210:211], s[16:17], 0, v[16:17]
	s_mov_b32 m0, s6
	ds_read_b128 v[178:181], v161 offset:16384
	ds_read_b128 v[182:185], v161 offset:17408
	ds_read_b128 v[186:189], v161 offset:18432
	ds_read_b128 v[190:193], v161 offset:19456
	ds_read_b128 v[194:197], v161 offset:20480
	ds_read_b128 v[198:201], v161 offset:21504
	ds_read_b128 v[202:205], v161 offset:22528
	ds_read_b128 v[206:209], v161 offset:23552
	global_load_lds_dwordx4 v[210:211], off
	s_add_i32 m0, s6, 0x2000
	s_add_u32 s6, s16, 0x100000
	v_lshl_add_u64 v[212:213], s[16:17], 0, v[138:139]
	s_addc_u32 s7, s17, 0
	s_add_i32 s91, s94, s12
	global_load_lds_dwordx4 v[212:213], off
	v_lshl_add_u64 v[214:215], s[6:7], 0, v[16:17]
	s_mov_b32 m0, s91
	v_lshl_add_u64 v[216:217], s[40:41], 0, v[140:141]
	global_load_lds_dwordx4 v[214:215], off
	v_lshl_add_u64 v[214:215], s[6:7], 0, v[138:139]
	s_add_i32 m0, s91, 0x2000
	s_nop 0
	global_load_lds_dwordx4 v[214:215], off
	v_lshl_add_u64 v[214:215], s[40:41], 0, v[142:143]
	s_mov_b32 m0, s13
	s_nop 0
	global_load_lds_dwordx4 v[214:215], off
	s_mov_b32 m0, s42
	s_nop 0
	global_load_lds_dwordx4 v[216:217], off
	s_waitcnt vmcnt(8)
	s_waitcnt lgkmcnt(0)
	s_barrier
	v_mfma_f32_16x16x32_bf16 v[62:65], v[130:133], v[178:181], v[62:65]
	v_mfma_f32_16x16x32_bf16 v[58:61], v[148:151], v[178:181], v[58:61]
	v_mfma_f32_16x16x32_bf16 v[46:49], v[130:133], v[186:189], v[46:49]
	v_mfma_f32_16x16x32_bf16 v[42:45], v[148:151], v[186:189], v[42:45]
	v_mfma_f32_16x16x32_bf16 v[30:33], v[130:133], v[194:197], v[30:33]
	v_mfma_f32_16x16x32_bf16 v[26:29], v[148:151], v[194:197], v[26:29]
	v_mfma_f32_16x16x32_bf16 v[12:15], v[130:133], v[202:205], v[12:15]
	v_mfma_f32_16x16x32_bf16 v[8:11], v[148:151], v[202:205], v[8:11]
	v_mfma_f32_16x16x32_bf16 v[62:65], v[134:137], v[182:185], v[62:65]
	v_mfma_f32_16x16x32_bf16 v[58:61], v[152:155], v[182:185], v[58:61]
	v_mfma_f32_16x16x32_bf16 v[46:49], v[134:137], v[190:193], v[46:49]
	v_mfma_f32_16x16x32_bf16 v[42:45], v[152:155], v[190:193], v[42:45]
	v_mfma_f32_16x16x32_bf16 v[30:33], v[134:137], v[198:201], v[30:33]
	v_mfma_f32_16x16x32_bf16 v[26:29], v[152:155], v[198:201], v[26:29]
	v_mfma_f32_16x16x32_bf16 v[12:15], v[134:137], v[206:209], v[12:15]
	v_mfma_f32_16x16x32_bf16 v[8:11], v[152:155], v[206:209], v[8:11]
	v_mfma_f32_16x16x32_bf16 v[54:57], v[162:165], v[178:181], v[54:57]
	v_mfma_f32_16x16x32_bf16 v[50:53], v[170:173], v[178:181], v[50:53]
	v_mfma_f32_16x16x32_bf16 v[38:41], v[162:165], v[186:189], v[38:41]
	v_mfma_f32_16x16x32_bf16 v[34:37], v[170:173], v[186:189], v[34:37]
	v_mfma_f32_16x16x32_bf16 v[22:25], v[162:165], v[194:197], v[22:25]
	v_mfma_f32_16x16x32_bf16 v[18:21], v[170:173], v[194:197], v[18:21]
	v_mfma_f32_16x16x32_bf16 v[4:7], v[162:165], v[202:205], v[4:7]
	v_mfma_f32_16x16x32_bf16 v[0:3], v[170:173], v[202:205], v[0:3]
	v_mfma_f32_16x16x32_bf16 v[54:57], v[166:169], v[182:185], v[54:57]
	v_mfma_f32_16x16x32_bf16 v[50:53], v[174:177], v[182:185], v[50:53]
	v_mfma_f32_16x16x32_bf16 v[38:41], v[166:169], v[190:193], v[38:41]
	v_mfma_f32_16x16x32_bf16 v[34:37], v[174:177], v[190:193], v[34:37]
	v_mfma_f32_16x16x32_bf16 v[22:25], v[166:169], v[198:201], v[22:25]
	v_mfma_f32_16x16x32_bf16 v[18:21], v[174:177], v[198:201], v[18:21]
	v_mfma_f32_16x16x32_bf16 v[4:7], v[166:169], v[206:209], v[4:7]
	v_mfma_f32_16x16x32_bf16 v[0:3], v[174:177], v[206:209], v[0:3]
	s_barrier
; #define PG8_STAGEA(bufoff, gbase, voff) PG8_STAGE_X(bufoff, gbase, voff, AUXA)
; #define PG8_STAGEB(bufoff, gbase, voff) PG8_STAGE_X(bufoff, gbase, voff, AUXB)
; #define PG8_LDA(dst, b, h) do { _Pragma("unroll") for (int m = 0; m < 4; ++m) _Pragma("unroll") for (int k = 0; k < 2; ++k) dst[m][k] = *(const PG8_LAS bf16x8*)(lds + PG8_SA(b, h) + aoff + m * 2048 + k * 1024); } while (0)
; #define PG8_LDB(dst, b, h) do { _Pragma("unroll") for (int n = 0; n < 2; ++n) _Pragma("unroll") for (int k = 0; k < 2; ++k) dst[n][k] = *(const PG8_LAS bf16x8*)(lds + PG8_SB(b, h) + boff + n * 2048 + k * 1024); } while (0)
; #define PG8_MMA(ai, bj, At, Bt) do { if (GEMM_PRIO_MODE == 0) __builtin_amdgcn_s_setprio(1); PG8_MMA_LOOPS \
;         acc[ai][bj][m][n] = __builtin_amdgcn_mfma_f32_16x16x32_bf16(Bt[n][k], At[m][k], acc[ai][bj][m][n], 0, 0, 0); if (GEMM_PRIO_MODE == 0) __builtin_amdgcn_s_setprio(0); } while (0)
; #define PG8_WAIT_V(n) asm volatile("s_waitcnt vmcnt(" #n ")" ::: "memory")
; #define PG8_WAIT_VR(n, nr, flag) asm volatile("s_cmp_eq_u32 %0, 0\n\ts_cbranch_scc1 .Lpg8s%=\n\ts_waitcnt vmcnt(" #nr ")\n\ts_branch .Lpg8d%=\n.Lpg8s%=:\n\ts_waitcnt vmcnt(" #n ")\n.Lpg8d%=:" :: "s"(flag) : "memory", "scc")
; #define PG8_WAIT_L(n) asm volatile("s_waitcnt lgkmcnt(" #n ")" ::: "memory")
; #define PG8_BAR __builtin_amdgcn_s_barrier()
; #define PG8_SCHED __builtin_amdgcn_sched_barrier(0)
;     ...
;             PG8_LDA(At, 0, 1); PG8_STAGEB(PG8_SB(0, 0), b2, voffB); PG8_STAGEB(PG8_SB(0, 1), b2 + hstepB, voffB); PG8_STAGEA(PG8_SA(0, 0), a2, voffA);
;     ...
;             PG8_WAIT_VR(8, 24, relax); PG8_WAIT_L(0); PG8_BAR; PG8_MMA(1, 0, At, B0); PG8_MMA(1, 1, At, B1); PG8_BAR; PG8_SCHED;
;     ...
;             PG8_WAIT_V(8); PG8_WAIT_L(0); PG8_BAR; PG8_MMA(1, 0, At, B0); PG8_MMA(1, 1, At, B1); PG8_BAR; PG8_SCHED;
;     ...
;             PG8_LDB(B0, 1, 0); PG8_LDB(B1, 1, 1); PG8_SCHED; PG8_LDA(At, 1, 0); PG8_STAGEA(PG8_SA(0, 1), a2 + hstepA, voffA);
;             PG8_WAIT_V(8); PG8_WAIT_L(0); PG8_BAR; PG8_MMA(0, 0, At, B0); PG8_MMA(0, 1, At, B1); PG8_BAR; PG8_SCHED;
;             PG8_LDA(At, 1, 1); PG8_STAGEB(PG8_SB(1, 0), b3, voffB); PG8_STAGEB(PG8_SB(1, 1), b3 + hstepB, voffB); PG8_STAGEA(PG8_SA(1, 0), a3, voffA);
;             PG8_WAIT_V(8); PG8_WAIT_L(0); PG8_BAR; PG8_MMA(1, 0, At, B0); PG8_MMA(1, 1, At, B1); PG8_BAR; PG8_SCHED;
	s_add_i32 s91, 0, 0x18000
	s_add_i32 s94, 0, 0x1c000
	v_add_u32_e32 v152, s91, v157
	v_add_u32_e32 v174, s94, v157
	ds_read_b128 v[130:133], v152
	ds_read_b128 v[134:137], v152 offset:1024
	ds_read_b128 v[148:151], v152 offset:2048
	ds_read_b128 v[152:155], v152 offset:3072
	ds_read_b128 v[162:165], v174
	ds_read_b128 v[166:169], v174 offset:1024
	ds_read_b128 v[170:173], v174 offset:2048
	ds_read_b128 v[174:177], v174 offset:3072
	s_add_u32 s6, s40, 0x100000
	s_addc_u32 s7, s41, 0
	s_mov_b32 m0, s43
	v_lshl_add_u64 v[218:219], s[6:7], 0, v[142:143]
	ds_read_b128 v[178:181], v161 offset:32768
	ds_read_b128 v[182:185], v161 offset:33792
	ds_read_b128 v[186:189], v161 offset:34816
	ds_read_b128 v[190:193], v161 offset:35840
	ds_read_b128 v[194:197], v161 offset:36864
	ds_read_b128 v[198:201], v161 offset:37888
	ds_read_b128 v[202:205], v161 offset:38912
	ds_read_b128 v[206:209], v161 offset:39936
	global_load_lds_dwordx4 v[218:219], off
	v_lshl_add_u64 v[218:219], s[6:7], 0, v[140:141]
	s_mov_b32 m0, s50
	s_nop 0
	global_load_lds_dwordx4 v[218:219], off
	s_waitcnt vmcnt(8)
	s_waitcnt lgkmcnt(0)
	s_barrier
	v_mfma_f32_16x16x32_bf16 v[126:129], v[130:133], v[178:181], v[126:129]
	v_mfma_f32_16x16x32_bf16 v[122:125], v[148:151], v[178:181], v[122:125]
	v_mfma_f32_16x16x32_bf16 v[110:113], v[130:133], v[186:189], v[110:113]
	v_mfma_f32_16x16x32_bf16 v[106:109], v[148:151], v[186:189], v[106:109]
	v_mfma_f32_16x16x32_bf16 v[94:97], v[130:133], v[194:197], v[94:97]
	v_mfma_f32_16x16x32_bf16 v[90:93], v[148:151], v[194:197], v[90:93]
	v_mfma_f32_16x16x32_bf16 v[78:81], v[130:133], v[202:205], v[78:81]
	v_mfma_f32_16x16x32_bf16 v[74:77], v[148:151], v[202:205], v[74:77]
	v_mfma_f32_16x16x32_bf16 v[126:129], v[134:137], v[182:185], v[126:129]
	v_mfma_f32_16x16x32_bf16 v[122:125], v[152:155], v[182:185], v[122:125]
	v_mfma_f32_16x16x32_bf16 v[110:113], v[134:137], v[190:193], v[110:113]
	v_mfma_f32_16x16x32_bf16 v[106:109], v[152:155], v[190:193], v[106:109]
	v_mfma_f32_16x16x32_bf16 v[94:97], v[134:137], v[198:201], v[94:97]
	v_mfma_f32_16x16x32_bf16 v[90:93], v[152:155], v[198:201], v[90:93]
	v_mfma_f32_16x16x32_bf16 v[78:81], v[134:137], v[206:209], v[78:81]
	v_mfma_f32_16x16x32_bf16 v[74:77], v[152:155], v[206:209], v[74:77]
	v_mfma_f32_16x16x32_bf16 v[118:121], v[162:165], v[178:181], v[118:121]
	v_mfma_f32_16x16x32_bf16 v[114:117], v[170:173], v[178:181], v[114:117]
	v_mfma_f32_16x16x32_bf16 v[102:105], v[162:165], v[186:189], v[102:105]
	v_mfma_f32_16x16x32_bf16 v[98:101], v[170:173], v[186:189], v[98:101]
	v_mfma_f32_16x16x32_bf16 v[86:89], v[162:165], v[194:197], v[86:89]
	v_mfma_f32_16x16x32_bf16 v[82:85], v[170:173], v[194:197], v[82:85]
	v_mfma_f32_16x16x32_bf16 v[70:73], v[162:165], v[202:205], v[70:73]
	v_mfma_f32_16x16x32_bf16 v[66:69], v[170:173], v[202:205], v[66:69]
	v_mfma_f32_16x16x32_bf16 v[118:121], v[166:169], v[182:185], v[118:121]
	v_mfma_f32_16x16x32_bf16 v[114:117], v[174:177], v[182:185], v[114:117]
	v_mfma_f32_16x16x32_bf16 v[102:105], v[166:169], v[190:193], v[102:105]
	v_mfma_f32_16x16x32_bf16 v[98:101], v[174:177], v[190:193], v[98:101]
	v_mfma_f32_16x16x32_bf16 v[86:89], v[166:169], v[198:201], v[86:89]
	v_mfma_f32_16x16x32_bf16 v[82:85], v[174:177], v[198:201], v[82:85]
	v_mfma_f32_16x16x32_bf16 v[70:73], v[166:169], v[206:209], v[70:73]
	v_mfma_f32_16x16x32_bf16 v[66:69], v[174:177], v[206:209], v[66:69]
	s_barrier
; #define PG8_STAGEA(bufoff, gbase, voff) PG8_STAGE_X(bufoff, gbase, voff, AUXA)
; #define PG8_STAGEB(bufoff, gbase, voff) PG8_STAGE_X(bufoff, gbase, voff, AUXB)
; #define PG8_LDA(dst, b, h) do { _Pragma("unroll") for (int m = 0; m < 4; ++m) _Pragma("unroll") for (int k = 0; k < 2; ++k) dst[m][k] = *(const PG8_LAS bf16x8*)(lds + PG8_SA(b, h) + aoff + m * 2048 + k * 1024); } while (0)
; #define PG8_WAIT_V(n) asm volatile("s_waitcnt vmcnt(" #n ")" ::: "memory")
; #define PG8_BAR __builtin_amdgcn_s_barrier()
;     ...
;             PG8_LDB(B0, 1, 0); PG8_LDB(B1, 1, 1); PG8_SCHED; PG8_LDA(At, 1, 0); PG8_STAGEA(PG8_SA(0, 1), a2 + hstepA, voffA);
;             PG8_WAIT_V(8); PG8_WAIT_L(0); PG8_BAR; PG8_MMA(0, 0, At, B0); PG8_MMA(0, 1, At, B1); PG8_BAR; PG8_SCHED;
;             PG8_LDA(At, 1, 1); PG8_STAGEB(PG8_SB(1, 0), b3, voffB); PG8_STAGEB(PG8_SB(1, 1), b3 + hstepB, voffB); PG8_STAGEA(PG8_SA(1, 0), a3, voffA);
;             PG8_WAIT_V(8); PG8_WAIT_L(0); PG8_BAR; PG8_MMA(1, 0, At, B0); PG8_MMA(1, 1, At, B1); PG8_BAR; PG8_SCHED;
;             } else {
;             PG8_LDB(B0, 0, 0); PG8_SCHED; PG8_LDA(At, 0, 0); PG8_STAGEA(PG8_SA(1, 1), a1 + hstepA, voffA);
;             PG8_WAIT_L(8); PG8_BAR; PG8_WAIT_L(0); PG8_MMA(0, 0, At, B0); PG8_BAR; PG8_SCHED;
;             PG8_LDB(B1, 0, 1); PG8_STAGEB(PG8_SB(0, 0), b2, voffB);
;             PG8_BAR; PG8_WAIT_L(0); PG8_MMA(0, 1, At, B1); PG8_BAR;
;             PG8_LDA(At, 0, 1); PG8_STAGEA(PG8_SA(0, 0), a2, voffA);
;             PG8_BAR; PG8_WAIT_L(0); PG8_MMA(1, 0, At, B0); PG8_BAR; PG8_SCHED;
;             PG8_STAGEB(PG8_SB(0, 1), b2 + hstepB, voffB);
;             PG8_WAIT_V(6); PG8_BAR; PG8_MMA(1, 1, At, B1); PG8_BAR;
;             PG8_LDB(B0, 1, 0); PG8_SCHED; PG8_LDA(At, 1, 0); PG8_STAGEA(PG8_SA(0, 1), a2 + hstepA, voffA);
;             PG8_WAIT_L(8); PG8_BAR; PG8_WAIT_L(0); PG8_MMA(0, 0, At, B0); PG8_BAR; PG8_SCHED;
;             PG8_LDB(B1, 1, 1); PG8_STAGEB(PG8_SB(1, 0), b3, voffB);
;             PG8_BAR; PG8_WAIT_L(0); PG8_MMA(0, 1, At, B1); PG8_BAR;
;             PG8_LDA(At, 1, 1); PG8_STAGEA(PG8_SA(1, 0), a3, voffA);
;             PG8_BAR; PG8_WAIT_L(0); PG8_MMA(1, 0, At, B0); PG8_BAR; PG8_SCHED;
;             PG8_STAGEB(PG8_SB(1, 1), b3 + hstepB, voffB);
;             PG8_WAIT_V(6); PG8_BAR; PG8_MMA(1, 1, At, B1); PG8_BAR;
;             }
;         }
;         if constexpr (ALIGN_EPI) { if (wr == 0) PG8_BAR; }
	s_add_i32 s6, s91, s12
	v_lshl_add_u64 v[210:211], v[210:211], 0, s[86:87]
	s_mov_b32 m0, s6
	ds_read_b128 v[178:181], v161 offset:49152
	ds_read_b128 v[182:185], v161 offset:50176
	ds_read_b128 v[186:189], v161 offset:51200
	ds_read_b128 v[190:193], v161 offset:52224
	ds_read_b128 v[194:197], v161 offset:53248
	ds_read_b128 v[198:201], v161 offset:54272
	ds_read_b128 v[202:205], v161 offset:55296
	ds_read_b128 v[206:209], v161 offset:56320
	global_load_lds_dwordx4 v[210:211], off
	s_add_i32 m0, s6, 0x2000
	s_add_u32 s6, s16, 0x100080
	v_lshl_add_u64 v[210:211], v[212:213], 0, s[86:87]
	s_addc_u32 s7, s17, 0
	s_add_i32 s16, s94, s12
	global_load_lds_dwordx4 v[210:211], off
	v_lshl_add_u64 v[210:211], s[6:7], 0, v[16:17]
	s_mov_b32 m0, s16
	s_nop 0
	global_load_lds_dwordx4 v[210:211], off
	v_lshl_add_u64 v[210:211], s[6:7], 0, v[138:139]
	s_add_i32 m0, s16, 0x2000
	s_nop 0
	global_load_lds_dwordx4 v[210:211], off
	v_lshl_add_u64 v[210:211], v[214:215], 0, s[86:87]
	s_mov_b32 m0, s68
	s_nop 0
	global_load_lds_dwordx4 v[210:211], off
	v_lshl_add_u64 v[210:211], v[216:217], 0, s[86:87]
	s_mov_b32 m0, s69
	s_nop 0
	global_load_lds_dwordx4 v[210:211], off
	s_waitcnt vmcnt(8)
	s_waitcnt lgkmcnt(0)
	s_barrier
	v_mfma_f32_16x16x32_bf16 v[62:65], v[130:133], v[178:181], v[62:65]
	v_mfma_f32_16x16x32_bf16 v[58:61], v[148:151], v[178:181], v[58:61]
	v_mfma_f32_16x16x32_bf16 v[46:49], v[130:133], v[186:189], v[46:49]
	v_mfma_f32_16x16x32_bf16 v[42:45], v[148:151], v[186:189], v[42:45]
	v_mfma_f32_16x16x32_bf16 v[30:33], v[130:133], v[194:197], v[30:33]
	v_mfma_f32_16x16x32_bf16 v[26:29], v[148:151], v[194:197], v[26:29]
	v_mfma_f32_16x16x32_bf16 v[12:15], v[130:133], v[202:205], v[12:15]
	v_mfma_f32_16x16x32_bf16 v[8:11], v[148:151], v[202:205], v[8:11]
	v_mfma_f32_16x16x32_bf16 v[62:65], v[134:137], v[182:185], v[62:65]
	v_mfma_f32_16x16x32_bf16 v[58:61], v[152:155], v[182:185], v[58:61]
	v_mfma_f32_16x16x32_bf16 v[46:49], v[134:137], v[190:193], v[46:49]
	v_mfma_f32_16x16x32_bf16 v[42:45], v[152:155], v[190:193], v[42:45]
	v_mfma_f32_16x16x32_bf16 v[30:33], v[134:137], v[198:201], v[30:33]
	v_mfma_f32_16x16x32_bf16 v[26:29], v[152:155], v[198:201], v[26:29]
	v_mfma_f32_16x16x32_bf16 v[12:15], v[134:137], v[206:209], v[12:15]
	v_mfma_f32_16x16x32_bf16 v[8:11], v[152:155], v[206:209], v[8:11]
	v_mfma_f32_16x16x32_bf16 v[54:57], v[162:165], v[178:181], v[54:57]
	v_mfma_f32_16x16x32_bf16 v[50:53], v[170:173], v[178:181], v[50:53]
	v_mfma_f32_16x16x32_bf16 v[38:41], v[162:165], v[186:189], v[38:41]
	v_mfma_f32_16x16x32_bf16 v[34:37], v[170:173], v[186:189], v[34:37]
	v_mfma_f32_16x16x32_bf16 v[22:25], v[162:165], v[194:197], v[22:25]
	v_mfma_f32_16x16x32_bf16 v[18:21], v[170:173], v[194:197], v[18:21]
	v_mfma_f32_16x16x32_bf16 v[4:7], v[162:165], v[202:205], v[4:7]
	v_mfma_f32_16x16x32_bf16 v[0:3], v[170:173], v[202:205], v[0:3]
	v_mfma_f32_16x16x32_bf16 v[54:57], v[166:169], v[182:185], v[54:57]
	v_mfma_f32_16x16x32_bf16 v[50:53], v[174:177], v[182:185], v[50:53]
	v_mfma_f32_16x16x32_bf16 v[38:41], v[166:169], v[190:193], v[38:41]
	v_mfma_f32_16x16x32_bf16 v[34:37], v[174:177], v[190:193], v[34:37]
	v_mfma_f32_16x16x32_bf16 v[22:25], v[166:169], v[198:201], v[22:25]
	v_mfma_f32_16x16x32_bf16 v[18:21], v[174:177], v[198:201], v[18:21]
	v_mfma_f32_16x16x32_bf16 v[4:7], v[166:169], v[206:209], v[4:7]
	v_mfma_f32_16x16x32_bf16 v[0:3], v[174:177], v[206:209], v[0:3]
	s_barrier
	s_add_i32 s90, s90, 2
	s_add_u32 s38, s38, 0x100
	s_addc_u32 s39, s39, 0
	s_add_u32 s0, s0, 0x100
	s_addc_u32 s1, s1, 0
	s_cmp_gt_u32 s90, 61
	s_cbranch_scc0 .LBB0_558
	s_setprio 0
	s_and_b64 vcc, exec, s[18:19]
	s_cbranch_vccz .LBB0_561
	s_barrier

; #define PG8_STR(x) PG8_STR2(x)
;     ...
;         const char* nA = has_next ? (const char*)g.A + (size_t)nxt.pm * tstepA : cA; const char* nB = has_next ? (const char*)g.Bt + (size_t)nxt.pn * tstepB : cB;
;         int t0 = 0;
;         if constexpr (SP2 && GEMM_RELAX == 1) { if (ui > 0) {
;             const char* a1 = cA + kstepA; const char* a2 = cA + 2 * kstepA; const char* b2 = cB + 2 * kstepB; const char* a3 = a2 + kstepA; const char* b3 = b2 + kstepB;
;             PG8_LDB(B0, 0, 0); PG8_LDB(B1, 0, 1); PG8_SCHED; PG8_LDA(At, 0, 0); PG8_STAGEA(PG8_SA(1, 1), a1 + hstepA, voffA);
;             PG8_WAIT_V(24); PG8_WAIT_L(0); PG8_BAR; PG8_MMA(0, 0, At, B0); PG8_MMA(0, 1, At, B1); PG8_BAR; PG8_SCHED;
;             PG8_LDA(At, 0, 1); PG8_STAGEB(PG8_SB(0, 0), b2, voffB); PG8_STAGEB(PG8_SB(0, 1), b2 + hstepB, voffB); PG8_STAGEA(PG8_SA(0, 0), a2, voffA);
;             PG8_WAIT_V(24); PG8_WAIT_L(0); PG8_BAR; PG8_MMA(1, 0, At, B0); PG8_MMA(1, 1, At, B1); PG8_BAR; PG8_SCHED;
;             PG8_LDB(B0, 1, 0); PG8_LDB(B1, 1, 1); PG8_SCHED; PG8_LDA(At, 1, 0); PG8_STAGEA(PG8_SA(0, 1), a2 + hstepA, voffA);
;             PG8_WAIT_V(8); PG8_WAIT_L(0); PG8_BAR; PG8_MMA(0, 0, At, B0); PG8_MMA(0, 1, At, B1); PG8_BAR; PG8_SCHED;
;             PG8_LDA(At, 1, 1); PG8_STAGEB(PG8_SB(1, 0), b3, voffB); PG8_STAGEB(PG8_SB(1, 1), b3 + hstepB, voffB); PG8_STAGEA(PG8_SA(1, 0), a3, voffA);
;             PG8_WAIT_V(8); PG8_WAIT_L(0); PG8_BAR; PG8_MMA(1, 0, At, B0); PG8_MMA(1, 1, At, B1); PG8_BAR; PG8_SCHED;
;             t0 = 2; } }
;     ...
;         asm volatile(".p2align " PG8_STR(GEMM_LOOP_ALIGN) ::: "memory");
;     ...
;         for (int t = t0; t < nt; t += 2) {
;             const bool last = (t == nt - 2);
;             const char* a1 = cA + (size_t)(t + 1) * kstepA;
;             const char* a2 = last ? nA : cA + (size_t)(t + 2) * kstepA; const char* b2 = last ? nB : cB + (size_t)(t + 2) * kstepB;
;             const char* a3 = a2 + kstepA; const char* b3 = b2 + kstepB;
;             if (last && has_next) S.a_ready(nxt);
;             if constexpr (SP2) {
;             PG8_LDB(B0, 0, 0); PG8_LDB(B1, 0, 1); PG8_SCHED; PG8_LDA(At, 0, 0); PG8_STAGEA(PG8_SA(1, 1), a1 + hstepA, voffA);
;     ...
;             const int relax = __builtin_amdgcn_readfirstlane((t == 0 && ui > 0) ? 1 : 0);
;             PG8_WAIT_VR(8, 24, relax); PG8_WAIT_L(0); PG8_BAR; PG8_MMA(0, 0, At, B0); PG8_MMA(0, 1, At, B1); PG8_BAR; PG8_SCHED;
.LBB0_711:
	s_ashr_i32 s25, s24, 31
	s_lshl_b64 s[0:1], s[24:25], 21
	s_add_u32 s26, s56, s0
	s_addc_u32 s27, s57, s1
	s_and_b64 s[0:1], s[10:11], exec
	s_cselect_b32 s0, s27, s13
	s_cselect_b32 s1, s26, s12
	s_ashr_i32 s23, s22, 31
	s_lshl_b64 s[6:7], s[22:23], 21
	s_add_u32 s36, s51, s6
	s_addc_u32 s37, s68, s7
	s_and_b64 s[6:7], s[10:11], exec
	s_cselect_b32 s23, s37, s43
	s_cselect_b32 s25, s36, s42
	s_add_u32 s40, s12, 0x100080
	s_addc_u32 s41, s13, 0
	s_add_u32 s12, s42, 0x100
	s_addc_u32 s13, s43, 0
	s_mov_b32 s39, -2
	s_and_b64 vcc, exec, s[18:19]
	s_cbranch_vccnz .Lsprio_g3
	s_setprio 1
.Lsprio_g3:
	s_add_u32 s6, s40, 0xfff00080
	s_addc_u32 s7, s41, -1
	s_add_i32 s95, 0, 0x10000
	s_cmp_eq_u32 s39, 60
	s_cselect_b32 s43, s0, s7
	s_cselect_b32 s42, s1, s6
	v_add_u32_e32 v144, s95, v146
	s_cselect_b32 s17, s23, s13
	s_cselect_b32 s16, s25, s12
	s_add_i32 vcc_lo, 0, 0x14000
	ds_read_b128 v[150:153], v144
	ds_read_b128 v[154:157], v144 offset:1024
	ds_read_b128 v[158:161], v144 offset:2048
	ds_read_b128 v[162:165], v144 offset:3072
	v_add_u32_e32 v144, vcc_lo, v146
	ds_read_b128 v[166:169], v144
	ds_read_b128 v[170:173], v144 offset:1024
	ds_read_b128 v[174:177], v144 offset:2048
	ds_read_b128 v[178:181], v144 offset:3072
	v_lshl_add_u64 v[144:145], s[40:41], 0, v[140:141]
	s_add_i32 m0, s69, 0xc000
	ds_read_b128 v[182:185], v148
	ds_read_b128 v[186:189], v148 offset:1024
	ds_read_b128 v[190:193], v148 offset:2048
	ds_read_b128 v[194:197], v148 offset:3072
	ds_read_b128 v[198:201], v148 offset:4096
	ds_read_b128 v[202:205], v148 offset:5120
	ds_read_b128 v[206:209], v148 offset:6144
	ds_read_b128 v[210:213], v148 offset:7168
	global_load_lds_dwordx4 v[144:145], off
	v_lshl_add_u64 v[144:145], s[40:41], 0, v[142:143]
	s_add_i32 m0, s69, 0xe000
	s_nop 0
	global_load_lds_dwordx4 v[144:145], off
	s_waitcnt vmcnt(8)
	s_waitcnt lgkmcnt(0)
	s_barrier
	v_mfma_f32_16x16x32_bf16 v[126:129], v[150:153], v[182:185], 0
	v_mfma_f32_16x16x32_bf16 v[122:125], v[158:161], v[182:185], 0
	v_mfma_f32_16x16x32_bf16 v[110:113], v[150:153], v[190:193], 0
	v_mfma_f32_16x16x32_bf16 v[106:109], v[158:161], v[190:193], 0
	v_mfma_f32_16x16x32_bf16 v[94:97], v[150:153], v[198:201], 0
	v_mfma_f32_16x16x32_bf16 v[90:93], v[158:161], v[198:201], 0
	v_mfma_f32_16x16x32_bf16 v[78:81], v[150:153], v[206:209], 0
	v_mfma_f32_16x16x32_bf16 v[74:77], v[158:161], v[206:209], 0
	v_mfma_f32_16x16x32_bf16 v[126:129], v[154:157], v[186:189], v[126:129]
	v_mfma_f32_16x16x32_bf16 v[122:125], v[162:165], v[186:189], v[122:125]
	v_mfma_f32_16x16x32_bf16 v[110:113], v[154:157], v[194:197], v[110:113]
	v_mfma_f32_16x16x32_bf16 v[106:109], v[162:165], v[194:197], v[106:109]
	v_mfma_f32_16x16x32_bf16 v[94:97], v[154:157], v[202:205], v[94:97]
	v_mfma_f32_16x16x32_bf16 v[90:93], v[162:165], v[202:205], v[90:93]
	v_mfma_f32_16x16x32_bf16 v[78:81], v[154:157], v[210:213], v[78:81]
	v_mfma_f32_16x16x32_bf16 v[74:77], v[162:165], v[210:213], v[74:77]
	v_mfma_f32_16x16x32_bf16 v[118:121], v[166:169], v[182:185], 0
	v_mfma_f32_16x16x32_bf16 v[114:117], v[174:177], v[182:185], 0
	v_mfma_f32_16x16x32_bf16 v[102:105], v[166:169], v[190:193], 0
	v_mfma_f32_16x16x32_bf16 v[98:101], v[174:177], v[190:193], 0
	v_mfma_f32_16x16x32_bf16 v[86:89], v[166:169], v[198:201], 0
	v_mfma_f32_16x16x32_bf16 v[82:85], v[174:177], v[198:201], 0
	v_mfma_f32_16x16x32_bf16 v[70:73], v[166:169], v[206:209], 0
	v_mfma_f32_16x16x32_bf16 v[66:69], v[174:177], v[206:209], 0
	v_mfma_f32_16x16x32_bf16 v[118:121], v[170:173], v[186:189], v[118:121]
	v_mfma_f32_16x16x32_bf16 v[114:117], v[178:181], v[186:189], v[114:117]
	v_mfma_f32_16x16x32_bf16 v[102:105], v[170:173], v[194:197], v[102:105]
	v_mfma_f32_16x16x32_bf16 v[98:101], v[178:181], v[194:197], v[98:101]
	v_mfma_f32_16x16x32_bf16 v[86:89], v[170:173], v[202:205], v[86:89]
	v_mfma_f32_16x16x32_bf16 v[82:85], v[178:181], v[202:205], v[82:85]
	v_mfma_f32_16x16x32_bf16 v[70:73], v[170:173], v[210:213], v[70:73]
	v_mfma_f32_16x16x32_bf16 v[66:69], v[178:181], v[210:213], v[66:69]
	s_barrier
	s_add_i32 s6, s95, s50
	v_lshl_add_u64 v[144:145], s[16:17], 0, v[134:135]
	s_mov_b32 m0, s6
	ds_read_b128 v[182:185], v148 offset:16384
	ds_read_b128 v[186:189], v148 offset:17408
	ds_read_b128 v[190:193], v148 offset:18432
	ds_read_b128 v[194:197], v148 offset:19456
	ds_read_b128 v[198:201], v148 offset:20480
	ds_read_b128 v[202:205], v148 offset:21504
	ds_read_b128 v[206:209], v148 offset:22528
	ds_read_b128 v[210:213], v148 offset:23552
	global_load_lds_dwordx4 v[144:145], off
	s_add_i32 m0, s6, 0x2000
	s_add_u32 s6, s16, 0x100000
	v_lshl_add_u64 v[214:215], s[16:17], 0, v[130:131]
	s_addc_u32 s7, s17, 0
	s_add_i32 s95, vcc_lo, s50
	global_load_lds_dwordx4 v[214:215], off
	v_lshl_add_u64 v[216:217], s[6:7], 0, v[134:135]
	s_mov_b32 m0, s95
	v_lshl_add_u64 v[218:219], s[42:43], 0, v[132:133]
	global_load_lds_dwordx4 v[216:217], off
	v_lshl_add_u64 v[216:217], s[6:7], 0, v[130:131]
	s_add_i32 m0, s95, 0x2000
	s_nop 0
	global_load_lds_dwordx4 v[216:217], off
	v_lshl_add_u64 v[216:217], s[42:43], 0, v[136:137]
	s_mov_b32 m0, s69
	s_nop 0
	global_load_lds_dwordx4 v[216:217], off
	s_mov_b32 m0, s72
	s_nop 0
	global_load_lds_dwordx4 v[218:219], off
	s_waitcnt vmcnt(8)
	s_waitcnt lgkmcnt(0)
	s_barrier
; #define PG8_STAGEA(bufoff, gbase, voff) PG8_STAGE_X(bufoff, gbase, voff, AUXA)
; #define PG8_STAGEB(bufoff, gbase, voff) PG8_STAGE_X(bufoff, gbase, voff, AUXB)
; #define PG8_LDA(dst, b, h) do { _Pragma("unroll") for (int m = 0; m < 4; ++m) _Pragma("unroll") for (int k = 0; k < 2; ++k) dst[m][k] = *(const PG8_LAS bf16x8*)(lds + PG8_SA(b, h) + aoff + m * 2048 + k * 1024); } while (0)
; #define PG8_LDB(dst, b, h) do { _Pragma("unroll") for (int n = 0; n < 2; ++n) _Pragma("unroll") for (int k = 0; k < 2; ++k) dst[n][k] = *(const PG8_LAS bf16x8*)(lds + PG8_SB(b, h) + boff + n * 2048 + k * 1024); } while (0)
; #define PG8_MMA(ai, bj, At, Bt) do { if (GEMM_PRIO_MODE == 0) __builtin_amdgcn_s_setprio(1); PG8_MMA_LOOPS \
;         acc[ai][bj][m][n] = __builtin_amdgcn_mfma_f32_16x16x32_bf16(Bt[n][k], At[m][k], acc[ai][bj][m][n], 0, 0, 0); if (GEMM_PRIO_MODE == 0) __builtin_amdgcn_s_setprio(0); } while (0)
; #define PG8_WAIT_V(n) asm volatile("s_waitcnt vmcnt(" #n ")" ::: "memory")
; #define PG8_WAIT_VR(n, nr, flag) asm volatile("s_cmp_eq_u32 %0, 0\n\ts_cbranch_scc1 .Lpg8s%=\n\ts_waitcnt vmcnt(" #nr ")\n\ts_branch .Lpg8d%=\n.Lpg8s%=:\n\ts_waitcnt vmcnt(" #n ")\n.Lpg8d%=:" :: "s"(flag) : "memory", "scc")
; #define PG8_WAIT_L(n) asm volatile("s_waitcnt lgkmcnt(" #n ")" ::: "memory")
; #define PG8_BAR __builtin_amdgcn_s_barrier()
; #define PG8_SCHED __builtin_amdgcn_sched_barrier(0)
;     ...
;             PG8_LDA(At, 0, 1); PG8_STAGEB(PG8_SB(0, 0), b2, voffB); PG8_STAGEB(PG8_SB(0, 1), b2 + hstepB, voffB); PG8_STAGEA(PG8_SA(0, 0), a2, voffA);
;     ...
;             PG8_WAIT_VR(8, 24, relax); PG8_WAIT_L(0); PG8_BAR; PG8_MMA(1, 0, At, B0); PG8_MMA(1, 1, At, B1); PG8_BAR; PG8_SCHED;
;     ...
;             PG8_WAIT_V(8); PG8_WAIT_L(0); PG8_BAR; PG8_MMA(1, 0, At, B0); PG8_MMA(1, 1, At, B1); PG8_BAR; PG8_SCHED;
;     ...
;             PG8_LDB(B0, 1, 0); PG8_LDB(B1, 1, 1); PG8_SCHED; PG8_LDA(At, 1, 0); PG8_STAGEA(PG8_SA(0, 1), a2 + hstepA, voffA);
;             PG8_WAIT_V(8); PG8_WAIT_L(0); PG8_BAR; PG8_MMA(0, 0, At, B0); PG8_MMA(0, 1, At, B1); PG8_BAR; PG8_SCHED;
;             PG8_LDA(At, 1, 1); PG8_STAGEB(PG8_SB(1, 0), b3, voffB); PG8_STAGEB(PG8_SB(1, 1), b3 + hstepB, voffB); PG8_STAGEA(PG8_SA(1, 0), a3, voffA);
;             PG8_WAIT_V(8); PG8_WAIT_L(0); PG8_BAR; PG8_MMA(1, 0, At, B0); PG8_MMA(1, 1, At, B1); PG8_BAR; PG8_SCHED;
	v_mfma_f32_16x16x32_bf16 v[62:65], v[150:153], v[182:185], 0
	v_mfma_f32_16x16x32_bf16 v[58:61], v[158:161], v[182:185], 0
	v_mfma_f32_16x16x32_bf16 v[46:49], v[150:153], v[190:193], 0
	v_mfma_f32_16x16x32_bf16 v[42:45], v[158:161], v[190:193], 0
	v_mfma_f32_16x16x32_bf16 v[30:33], v[150:153], v[198:201], 0
	v_mfma_f32_16x16x32_bf16 v[26:29], v[158:161], v[198:201], 0
	v_mfma_f32_16x16x32_bf16 v[12:15], v[150:153], v[206:209], 0
	v_mfma_f32_16x16x32_bf16 v[8:11], v[158:161], v[206:209], 0
	v_mfma_f32_16x16x32_bf16 v[62:65], v[154:157], v[186:189], v[62:65]
	v_mfma_f32_16x16x32_bf16 v[58:61], v[162:165], v[186:189], v[58:61]
	v_mfma_f32_16x16x32_bf16 v[46:49], v[154:157], v[194:197], v[46:49]
	v_mfma_f32_16x16x32_bf16 v[42:45], v[162:165], v[194:197], v[42:45]
	v_mfma_f32_16x16x32_bf16 v[30:33], v[154:157], v[202:205], v[30:33]
	v_mfma_f32_16x16x32_bf16 v[26:29], v[162:165], v[202:205], v[26:29]
	v_mfma_f32_16x16x32_bf16 v[12:15], v[154:157], v[210:213], v[12:15]
	v_mfma_f32_16x16x32_bf16 v[8:11], v[162:165], v[210:213], v[8:11]
	v_mfma_f32_16x16x32_bf16 v[54:57], v[166:169], v[182:185], 0
	v_mfma_f32_16x16x32_bf16 v[50:53], v[174:177], v[182:185], 0
	v_mfma_f32_16x16x32_bf16 v[38:41], v[166:169], v[190:193], 0
	v_mfma_f32_16x16x32_bf16 v[34:37], v[174:177], v[190:193], 0
	v_mfma_f32_16x16x32_bf16 v[22:25], v[166:169], v[198:201], 0
	v_mfma_f32_16x16x32_bf16 v[18:21], v[174:177], v[198:201], 0
	v_mfma_f32_16x16x32_bf16 v[4:7], v[166:169], v[206:209], 0
	v_mfma_f32_16x16x32_bf16 v[0:3], v[174:177], v[206:209], 0
	v_mfma_f32_16x16x32_bf16 v[54:57], v[170:173], v[186:189], v[54:57]
	v_mfma_f32_16x16x32_bf16 v[50:53], v[178:181], v[186:189], v[50:53]
	v_mfma_f32_16x16x32_bf16 v[38:41], v[170:173], v[194:197], v[38:41]
	v_mfma_f32_16x16x32_bf16 v[34:37], v[178:181], v[194:197], v[34:37]
	v_mfma_f32_16x16x32_bf16 v[22:25], v[170:173], v[202:205], v[22:25]
	v_mfma_f32_16x16x32_bf16 v[18:21], v[178:181], v[202:205], v[18:21]
	v_mfma_f32_16x16x32_bf16 v[4:7], v[170:173], v[210:213], v[4:7]
	v_mfma_f32_16x16x32_bf16 v[0:3], v[178:181], v[210:213], v[0:3]
	s_barrier
	s_add_i32 s95, 0, 0x18000
	v_add_u32_e32 v149, s95, v146
	s_add_i32 vcc_lo, 0, 0x1c000
	ds_read_b128 v[150:153], v149
	ds_read_b128 v[154:157], v149 offset:1024
	ds_read_b128 v[158:161], v149 offset:2048
	ds_read_b128 v[162:165], v149 offset:3072
	v_add_u32_e32 v149, vcc_lo, v146
	ds_read_b128 v[166:169], v149
	ds_read_b128 v[170:173], v149 offset:1024
	ds_read_b128 v[174:177], v149 offset:2048
	ds_read_b128 v[178:181], v149 offset:3072
	s_add_u32 s6, s42, 0x100000
	s_addc_u32 s7, s43, 0
	s_mov_b32 m0, s73
	v_lshl_add_u64 v[220:221], s[6:7], 0, v[136:137]
	ds_read_b128 v[182:185], v148 offset:32768
	ds_read_b128 v[186:189], v148 offset:33792
	ds_read_b128 v[190:193], v148 offset:34816
	ds_read_b128 v[194:197], v148 offset:35840
	ds_read_b128 v[198:201], v148 offset:36864
	ds_read_b128 v[202:205], v148 offset:37888
	ds_read_b128 v[206:209], v148 offset:38912
	ds_read_b128 v[210:213], v148 offset:39936
	global_load_lds_dwordx4 v[220:221], off
	v_lshl_add_u64 v[220:221], s[6:7], 0, v[132:133]
	s_mov_b32 m0, s82
	s_nop 0
	global_load_lds_dwordx4 v[220:221], off
	s_waitcnt vmcnt(8)
	s_waitcnt lgkmcnt(0)
	s_barrier
	v_mfma_f32_16x16x32_bf16 v[126:129], v[150:153], v[182:185], v[126:129]
	v_mfma_f32_16x16x32_bf16 v[122:125], v[158:161], v[182:185], v[122:125]
	v_mfma_f32_16x16x32_bf16 v[110:113], v[150:153], v[190:193], v[110:113]
	v_mfma_f32_16x16x32_bf16 v[106:109], v[158:161], v[190:193], v[106:109]
	v_mfma_f32_16x16x32_bf16 v[94:97], v[150:153], v[198:201], v[94:97]
	v_mfma_f32_16x16x32_bf16 v[90:93], v[158:161], v[198:201], v[90:93]
	v_mfma_f32_16x16x32_bf16 v[78:81], v[150:153], v[206:209], v[78:81]
	v_mfma_f32_16x16x32_bf16 v[74:77], v[158:161], v[206:209], v[74:77]
	v_mfma_f32_16x16x32_bf16 v[126:129], v[154:157], v[186:189], v[126:129]
	v_mfma_f32_16x16x32_bf16 v[122:125], v[162:165], v[186:189], v[122:125]
	v_mfma_f32_16x16x32_bf16 v[110:113], v[154:157], v[194:197], v[110:113]
	v_mfma_f32_16x16x32_bf16 v[106:109], v[162:165], v[194:197], v[106:109]
	v_mfma_f32_16x16x32_bf16 v[94:97], v[154:157], v[202:205], v[94:97]
	v_mfma_f32_16x16x32_bf16 v[90:93], v[162:165], v[202:205], v[90:93]
	v_mfma_f32_16x16x32_bf16 v[78:81], v[154:157], v[210:213], v[78:81]
	v_mfma_f32_16x16x32_bf16 v[74:77], v[162:165], v[210:213], v[74:77]
	v_mfma_f32_16x16x32_bf16 v[118:121], v[166:169], v[182:185], v[118:121]
	v_mfma_f32_16x16x32_bf16 v[114:117], v[174:177], v[182:185], v[114:117]
	v_mfma_f32_16x16x32_bf16 v[102:105], v[166:169], v[190:193], v[102:105]
	v_mfma_f32_16x16x32_bf16 v[98:101], v[174:177], v[190:193], v[98:101]
	v_mfma_f32_16x16x32_bf16 v[86:89], v[166:169], v[198:201], v[86:89]
	v_mfma_f32_16x16x32_bf16 v[82:85], v[174:177], v[198:201], v[82:85]
	v_mfma_f32_16x16x32_bf16 v[70:73], v[166:169], v[206:209], v[70:73]
	v_mfma_f32_16x16x32_bf16 v[66:69], v[174:177], v[206:209], v[66:69]
	v_mfma_f32_16x16x32_bf16 v[118:121], v[170:173], v[186:189], v[118:121]
	v_mfma_f32_16x16x32_bf16 v[114:117], v[178:181], v[186:189], v[114:117]
	v_mfma_f32_16x16x32_bf16 v[102:105], v[170:173], v[194:197], v[102:105]
	v_mfma_f32_16x16x32_bf16 v[98:101], v[178:181], v[194:197], v[98:101]
	v_mfma_f32_16x16x32_bf16 v[86:89], v[170:173], v[202:205], v[86:89]
	v_mfma_f32_16x16x32_bf16 v[82:85], v[178:181], v[202:205], v[82:85]
	v_mfma_f32_16x16x32_bf16 v[70:73], v[170:173], v[210:213], v[70:73]
	v_mfma_f32_16x16x32_bf16 v[66:69], v[178:181], v[210:213], v[66:69]
	s_barrier
; #define PG8_STAGEA(bufoff, gbase, voff) PG8_STAGE_X(bufoff, gbase, voff, AUXA)
; #define PG8_STAGEB(bufoff, gbase, voff) PG8_STAGE_X(bufoff, gbase, voff, AUXB)
; #define PG8_LDA(dst, b, h) do { _Pragma("unroll") for (int m = 0; m < 4; ++m) _Pragma("unroll") for (int k = 0; k < 2; ++k) dst[m][k] = *(const PG8_LAS bf16x8*)(lds + PG8_SA(b, h) + aoff + m * 2048 + k * 1024); } while (0)
; #define PG8_WAIT_V(n) asm volatile("s_waitcnt vmcnt(" #n ")" ::: "memory")
; #define PG8_WAIT_L(n) asm volatile("s_waitcnt lgkmcnt(" #n ")" ::: "memory")
;     ...
;         for (int t = t0; t < nt; t += 2) {
;             const bool last = (t == nt - 2);
;             const char* a1 = cA + (size_t)(t + 1) * kstepA;
;             const char* a2 = last ? nA : cA + (size_t)(t + 2) * kstepA; const char* b2 = last ? nB : cB + (size_t)(t + 2) * kstepB;
;             const char* a3 = a2 + kstepA; const char* b3 = b2 + kstepB;
;             if (last && has_next) S.a_ready(nxt);
;             if constexpr (SP2) {
;             PG8_LDB(B0, 0, 0); PG8_LDB(B1, 0, 1); PG8_SCHED; PG8_LDA(At, 0, 0); PG8_STAGEA(PG8_SA(1, 1), a1 + hstepA, voffA);
;     ...
;             const int relax = __builtin_amdgcn_readfirstlane((t == 0 && ui > 0) ? 1 : 0);
;             PG8_WAIT_VR(8, 24, relax); PG8_WAIT_L(0); PG8_BAR; PG8_MMA(0, 0, At, B0); PG8_MMA(0, 1, At, B1); PG8_BAR; PG8_SCHED;
;     ...
;             PG8_WAIT_V(8); PG8_WAIT_L(0); PG8_BAR; PG8_MMA(0, 0, At, B0); PG8_MMA(0, 1, At, B1); PG8_BAR; PG8_SCHED;
;     ...
;             PG8_LDA(At, 0, 1); PG8_STAGEB(PG8_SB(0, 0), b2, voffB); PG8_STAGEB(PG8_SB(0, 1), b2 + hstepB, voffB); PG8_STAGEA(PG8_SA(0, 0), a2, voffA);
;     ...
;             PG8_WAIT_VR(8, 24, relax); PG8_WAIT_L(0); PG8_BAR; PG8_MMA(1, 0, At, B0); PG8_MMA(1, 1, At, B1); PG8_BAR; PG8_SCHED;
;     ...
;             PG8_WAIT_V(8); PG8_WAIT_L(0); PG8_BAR; PG8_MMA(1, 0, At, B0); PG8_MMA(1, 1, At, B1); PG8_BAR; PG8_SCHED;
;     ...
;             PG8_LDB(B0, 1, 0); PG8_LDB(B1, 1, 1); PG8_SCHED; PG8_LDA(At, 1, 0); PG8_STAGEA(PG8_SA(0, 1), a2 + hstepA, voffA);
;             PG8_WAIT_V(8); PG8_WAIT_L(0); PG8_BAR; PG8_MMA(0, 0, At, B0); PG8_MMA(0, 1, At, B1); PG8_BAR; PG8_SCHED;
;             PG8_LDA(At, 1, 1); PG8_STAGEB(PG8_SB(1, 0), b3, voffB); PG8_STAGEB(PG8_SB(1, 1), b3 + hstepB, voffB); PG8_STAGEA(PG8_SA(1, 0), a3, voffA);
;             PG8_WAIT_V(8); PG8_WAIT_L(0); PG8_BAR; PG8_MMA(1, 0, At, B0); PG8_MMA(1, 1, At, B1); PG8_BAR; PG8_SCHED;
	s_add_i32 s6, s95, s50
	v_lshl_add_u64 v[144:145], v[144:145], 0, s[86:87]
	s_mov_b32 m0, s6
	ds_read_b128 v[182:185], v148 offset:49152
	ds_read_b128 v[186:189], v148 offset:50176
	ds_read_b128 v[190:193], v148 offset:51200
	ds_read_b128 v[194:197], v148 offset:52224
	ds_read_b128 v[198:201], v148 offset:53248
	ds_read_b128 v[202:205], v148 offset:54272
	ds_read_b128 v[206:209], v148 offset:55296
	ds_read_b128 v[210:213], v148 offset:56320
	global_load_lds_dwordx4 v[144:145], off
	s_add_i32 m0, s6, 0x2000
	s_add_u32 s6, s16, 0x100080
	v_lshl_add_u64 v[144:145], v[214:215], 0, s[86:87]
	s_addc_u32 s7, s17, 0
	s_add_i32 s16, vcc_lo, s50
	global_load_lds_dwordx4 v[144:145], off
	v_lshl_add_u64 v[144:145], s[6:7], 0, v[134:135]
	s_mov_b32 m0, s16
	s_nop 0
	global_load_lds_dwordx4 v[144:145], off
	v_lshl_add_u64 v[144:145], s[6:7], 0, v[130:131]
	s_add_i32 m0, s16, 0x2000
	s_nop 0
	global_load_lds_dwordx4 v[144:145], off
	v_lshl_add_u64 v[144:145], v[216:217], 0, s[86:87]
	s_mov_b32 m0, s83
	s_nop 0
	global_load_lds_dwordx4 v[144:145], off
	v_lshl_add_u64 v[144:145], v[218:219], 0, s[86:87]
	s_mov_b32 m0, s90
	s_nop 0
	global_load_lds_dwordx4 v[144:145], off
	s_waitcnt vmcnt(8)
	s_waitcnt lgkmcnt(0)
	s_barrier
	v_mfma_f32_16x16x32_bf16 v[62:65], v[150:153], v[182:185], v[62:65]
	v_mfma_f32_16x16x32_bf16 v[58:61], v[158:161], v[182:185], v[58:61]
	v_mfma_f32_16x16x32_bf16 v[46:49], v[150:153], v[190:193], v[46:49]
	v_mfma_f32_16x16x32_bf16 v[42:45], v[158:161], v[190:193], v[42:45]
	v_mfma_f32_16x16x32_bf16 v[30:33], v[150:153], v[198:201], v[30:33]
	v_mfma_f32_16x16x32_bf16 v[26:29], v[158:161], v[198:201], v[26:29]
	v_mfma_f32_16x16x32_bf16 v[12:15], v[150:153], v[206:209], v[12:15]
	v_mfma_f32_16x16x32_bf16 v[8:11], v[158:161], v[206:209], v[8:11]
	v_mfma_f32_16x16x32_bf16 v[62:65], v[154:157], v[186:189], v[62:65]
	v_mfma_f32_16x16x32_bf16 v[58:61], v[162:165], v[186:189], v[58:61]
	v_mfma_f32_16x16x32_bf16 v[46:49], v[154:157], v[194:197], v[46:49]
	v_mfma_f32_16x16x32_bf16 v[42:45], v[162:165], v[194:197], v[42:45]
	v_mfma_f32_16x16x32_bf16 v[30:33], v[154:157], v[202:205], v[30:33]
	v_mfma_f32_16x16x32_bf16 v[26:29], v[162:165], v[202:205], v[26:29]
	v_mfma_f32_16x16x32_bf16 v[12:15], v[154:157], v[210:213], v[12:15]
	v_mfma_f32_16x16x32_bf16 v[8:11], v[162:165], v[210:213], v[8:11]
	v_mfma_f32_16x16x32_bf16 v[54:57], v[166:169], v[182:185], v[54:57]
	v_mfma_f32_16x16x32_bf16 v[50:53], v[174:177], v[182:185], v[50:53]
	v_mfma_f32_16x16x32_bf16 v[38:41], v[166:169], v[190:193], v[38:41]
	v_mfma_f32_16x16x32_bf16 v[34:37], v[174:177], v[190:193], v[34:37]
	v_mfma_f32_16x16x32_bf16 v[22:25], v[166:169], v[198:201], v[22:25]
	v_mfma_f32_16x16x32_bf16 v[18:21], v[174:177], v[198:201], v[18:21]
	v_mfma_f32_16x16x32_bf16 v[4:7], v[166:169], v[206:209], v[4:7]
	v_mfma_f32_16x16x32_bf16 v[0:3], v[174:177], v[206:209], v[0:3]
	v_mfma_f32_16x16x32_bf16 v[54:57], v[170:173], v[186:189], v[54:57]
	v_mfma_f32_16x16x32_bf16 v[50:53], v[178:181], v[186:189], v[50:53]
	v_mfma_f32_16x16x32_bf16 v[38:41], v[170:173], v[194:197], v[38:41]
	v_mfma_f32_16x16x32_bf16 v[34:37], v[178:181], v[194:197], v[34:37]
	v_mfma_f32_16x16x32_bf16 v[22:25], v[170:173], v[202:205], v[22:25]
	v_mfma_f32_16x16x32_bf16 v[18:21], v[178:181], v[202:205], v[18:21]
	v_mfma_f32_16x16x32_bf16 v[4:7], v[170:173], v[210:213], v[4:7]
	v_mfma_f32_16x16x32_bf16 v[0:3], v[178:181], v[210:213], v[0:3]
	s_barrier
	s_add_i32 s39, s39, 2
	s_add_u32 s40, s40, 0x100
	s_addc_u32 s41, s41, 0
	s_add_u32 s12, s12, 0x100
	s_addc_u32 s13, s13, 0
.LBB0_712:
	s_add_u32 s6, s40, 0xfff00080
	s_addc_u32 s7, s41, -1
	s_add_i32 s95, 0, 0x10000
	s_cmp_eq_u32 s39, 60
	s_cselect_b32 s43, s0, s7
	s_cselect_b32 s42, s1, s6
	v_add_u32_e32 v144, s95, v146
	s_cselect_b32 s17, s23, s13
	s_cselect_b32 s16, s25, s12
	s_add_i32 vcc_lo, 0, 0x14000
	ds_read_b128 v[150:153], v144
	ds_read_b128 v[154:157], v144 offset:1024
	ds_read_b128 v[158:161], v144 offset:2048
	ds_read_b128 v[162:165], v144 offset:3072
	v_add_u32_e32 v144, vcc_lo, v146
	ds_read_b128 v[166:169], v144
	ds_read_b128 v[170:173], v144 offset:1024
	ds_read_b128 v[174:177], v144 offset:2048
	ds_read_b128 v[178:181], v144 offset:3072
	v_lshl_add_u64 v[144:145], s[40:41], 0, v[140:141]
	s_add_i32 m0, s69, 0xc000
	ds_read_b128 v[182:185], v148
	ds_read_b128 v[186:189], v148 offset:1024
	ds_read_b128 v[190:193], v148 offset:2048
	ds_read_b128 v[194:197], v148 offset:3072
	ds_read_b128 v[198:201], v148 offset:4096
	ds_read_b128 v[202:205], v148 offset:5120
	ds_read_b128 v[206:209], v148 offset:6144
	ds_read_b128 v[210:213], v148 offset:7168
	global_load_lds_dwordx4 v[144:145], off
	v_lshl_add_u64 v[144:145], s[40:41], 0, v[142:143]
	s_add_i32 m0, s69, 0xe000
	s_nop 0
	global_load_lds_dwordx4 v[144:145], off
	s_waitcnt vmcnt(8)
	s_waitcnt lgkmcnt(0)
	s_barrier
; #define PG8_STAGEA(bufoff, gbase, voff) PG8_STAGE_X(bufoff, gbase, voff, AUXA)
; #define PG8_STAGEB(bufoff, gbase, voff) PG8_STAGE_X(bufoff, gbase, voff, AUXB)
; #define PG8_LDA(dst, b, h) do { _Pragma("unroll") for (int m = 0; m < 4; ++m) _Pragma("unroll") for (int k = 0; k < 2; ++k) dst[m][k] = *(const PG8_LAS bf16x8*)(lds + PG8_SA(b, h) + aoff + m * 2048 + k * 1024); } while (0)
; #define PG8_LDB(dst, b, h) do { _Pragma("unroll") for (int n = 0; n < 2; ++n) _Pragma("unroll") for (int k = 0; k < 2; ++k) dst[n][k] = *(const PG8_LAS bf16x8*)(lds + PG8_SB(b, h) + boff + n * 2048 + k * 1024); } while (0)
; #define PG8_MMA(ai, bj, At, Bt) do { if (GEMM_PRIO_MODE == 0) __builtin_amdgcn_s_setprio(1); PG8_MMA_LOOPS \
;         acc[ai][bj][m][n] = __builtin_amdgcn_mfma_f32_16x16x32_bf16(Bt[n][k], At[m][k], acc[ai][bj][m][n], 0, 0, 0); if (GEMM_PRIO_MODE == 0) __builtin_amdgcn_s_setprio(0); } while (0)
; #define PG8_WAIT_V(n) asm volatile("s_waitcnt vmcnt(" #n ")" ::: "memory")
;     ...
;             PG8_LDB(B0, 0, 0); PG8_LDB(B1, 0, 1); PG8_SCHED; PG8_LDA(At, 0, 0); PG8_STAGEA(PG8_SA(1, 1), a1 + hstepA, voffA);
;     ...
;             const int relax = __builtin_amdgcn_readfirstlane((t == 0 && ui > 0) ? 1 : 0);
;             PG8_WAIT_VR(8, 24, relax); PG8_WAIT_L(0); PG8_BAR; PG8_MMA(0, 0, At, B0); PG8_MMA(0, 1, At, B1); PG8_BAR; PG8_SCHED;
;     ...
;             PG8_WAIT_V(8); PG8_WAIT_L(0); PG8_BAR; PG8_MMA(0, 0, At, B0); PG8_MMA(0, 1, At, B1); PG8_BAR; PG8_SCHED;
;     ...
;             PG8_LDA(At, 0, 1); PG8_STAGEB(PG8_SB(0, 0), b2, voffB); PG8_STAGEB(PG8_SB(0, 1), b2 + hstepB, voffB); PG8_STAGEA(PG8_SA(0, 0), a2, voffA);
;     ...
;             PG8_WAIT_VR(8, 24, relax); PG8_WAIT_L(0); PG8_BAR; PG8_MMA(1, 0, At, B0); PG8_MMA(1, 1, At, B1); PG8_BAR; PG8_SCHED;
;     ...
;             PG8_WAIT_V(8); PG8_WAIT_L(0); PG8_BAR; PG8_MMA(1, 0, At, B0); PG8_MMA(1, 1, At, B1); PG8_BAR; PG8_SCHED;
;     ...
;             PG8_LDB(B0, 1, 0); PG8_LDB(B1, 1, 1); PG8_SCHED; PG8_LDA(At, 1, 0); PG8_STAGEA(PG8_SA(0, 1), a2 + hstepA, voffA);
;             PG8_WAIT_V(8); PG8_WAIT_L(0); PG8_BAR; PG8_MMA(0, 0, At, B0); PG8_MMA(0, 1, At, B1); PG8_BAR; PG8_SCHED;
;             PG8_LDA(At, 1, 1); PG8_STAGEB(PG8_SB(1, 0), b3, voffB); PG8_STAGEB(PG8_SB(1, 1), b3 + hstepB, voffB); PG8_STAGEA(PG8_SA(1, 0), a3, voffA);
;             PG8_WAIT_V(8); PG8_WAIT_L(0); PG8_BAR; PG8_MMA(1, 0, At, B0); PG8_MMA(1, 1, At, B1); PG8_BAR; PG8_SCHED;
	v_mfma_f32_16x16x32_bf16 v[126:129], v[150:153], v[182:185], v[126:129]
	v_mfma_f32_16x16x32_bf16 v[122:125], v[158:161], v[182:185], v[122:125]
	v_mfma_f32_16x16x32_bf16 v[110:113], v[150:153], v[190:193], v[110:113]
	v_mfma_f32_16x16x32_bf16 v[106:109], v[158:161], v[190:193], v[106:109]
	v_mfma_f32_16x16x32_bf16 v[94:97], v[150:153], v[198:201], v[94:97]
	v_mfma_f32_16x16x32_bf16 v[90:93], v[158:161], v[198:201], v[90:93]
	v_mfma_f32_16x16x32_bf16 v[78:81], v[150:153], v[206:209], v[78:81]
	v_mfma_f32_16x16x32_bf16 v[74:77], v[158:161], v[206:209], v[74:77]
	v_mfma_f32_16x16x32_bf16 v[126:129], v[154:157], v[186:189], v[126:129]
	v_mfma_f32_16x16x32_bf16 v[122:125], v[162:165], v[186:189], v[122:125]
	v_mfma_f32_16x16x32_bf16 v[110:113], v[154:157], v[194:197], v[110:113]
	v_mfma_f32_16x16x32_bf16 v[106:109], v[162:165], v[194:197], v[106:109]
	v_mfma_f32_16x16x32_bf16 v[94:97], v[154:157], v[202:205], v[94:97]
	v_mfma_f32_16x16x32_bf16 v[90:93], v[162:165], v[202:205], v[90:93]
	v_mfma_f32_16x16x32_bf16 v[78:81], v[154:157], v[210:213], v[78:81]
	v_mfma_f32_16x16x32_bf16 v[74:77], v[162:165], v[210:213], v[74:77]
	v_mfma_f32_16x16x32_bf16 v[118:121], v[166:169], v[182:185], v[118:121]
	v_mfma_f32_16x16x32_bf16 v[114:117], v[174:177], v[182:185], v[114:117]
	v_mfma_f32_16x16x32_bf16 v[102:105], v[166:169], v[190:193], v[102:105]
	v_mfma_f32_16x16x32_bf16 v[98:101], v[174:177], v[190:193], v[98:101]
	v_mfma_f32_16x16x32_bf16 v[86:89], v[166:169], v[198:201], v[86:89]
	v_mfma_f32_16x16x32_bf16 v[82:85], v[174:177], v[198:201], v[82:85]
	v_mfma_f32_16x16x32_bf16 v[70:73], v[166:169], v[206:209], v[70:73]
	v_mfma_f32_16x16x32_bf16 v[66:69], v[174:177], v[206:209], v[66:69]
	v_mfma_f32_16x16x32_bf16 v[118:121], v[170:173], v[186:189], v[118:121]
	v_mfma_f32_16x16x32_bf16 v[114:117], v[178:181], v[186:189], v[114:117]
	v_mfma_f32_16x16x32_bf16 v[102:105], v[170:173], v[194:197], v[102:105]
	v_mfma_f32_16x16x32_bf16 v[98:101], v[178:181], v[194:197], v[98:101]
	v_mfma_f32_16x16x32_bf16 v[86:89], v[170:173], v[202:205], v[86:89]
	v_mfma_f32_16x16x32_bf16 v[82:85], v[178:181], v[202:205], v[82:85]
	v_mfma_f32_16x16x32_bf16 v[70:73], v[170:173], v[210:213], v[70:73]
	v_mfma_f32_16x16x32_bf16 v[66:69], v[178:181], v[210:213], v[66:69]
	s_barrier
	s_add_i32 s6, s95, s50
	v_lshl_add_u64 v[144:145], s[16:17], 0, v[134:135]
	s_mov_b32 m0, s6
	ds_read_b128 v[182:185], v148 offset:16384
	ds_read_b128 v[186:189], v148 offset:17408
	ds_read_b128 v[190:193], v148 offset:18432
	ds_read_b128 v[194:197], v148 offset:19456
	ds_read_b128 v[198:201], v148 offset:20480
	ds_read_b128 v[202:205], v148 offset:21504
	ds_read_b128 v[206:209], v148 offset:22528
	ds_read_b128 v[210:213], v148 offset:23552
	global_load_lds_dwordx4 v[144:145], off
	s_add_i32 m0, s6, 0x2000
	s_add_u32 s6, s16, 0x100000
	v_lshl_add_u64 v[214:215], s[16:17], 0, v[130:131]
	s_addc_u32 s7, s17, 0
	s_add_i32 s95, vcc_lo, s50
	global_load_lds_dwordx4 v[214:215], off
	v_lshl_add_u64 v[216:217], s[6:7], 0, v[134:135]
	s_mov_b32 m0, s95
	v_lshl_add_u64 v[218:219], s[42:43], 0, v[132:133]
	global_load_lds_dwordx4 v[216:217], off
	v_lshl_add_u64 v[216:217], s[6:7], 0, v[130:131]
	s_add_i32 m0, s95, 0x2000
	s_nop 0
	global_load_lds_dwordx4 v[216:217], off
	v_lshl_add_u64 v[216:217], s[42:43], 0, v[136:137]
	s_mov_b32 m0, s69
	s_nop 0
	global_load_lds_dwordx4 v[216:217], off
	s_mov_b32 m0, s72
	s_nop 0
	global_load_lds_dwordx4 v[218:219], off
	s_waitcnt vmcnt(8)
	s_waitcnt lgkmcnt(0)
	s_barrier
	v_mfma_f32_16x16x32_bf16 v[62:65], v[150:153], v[182:185], v[62:65]
	v_mfma_f32_16x16x32_bf16 v[58:61], v[158:161], v[182:185], v[58:61]
	v_mfma_f32_16x16x32_bf16 v[46:49], v[150:153], v[190:193], v[46:49]
	v_mfma_f32_16x16x32_bf16 v[42:45], v[158:161], v[190:193], v[42:45]
	v_mfma_f32_16x16x32_bf16 v[30:33], v[150:153], v[198:201], v[30:33]
	v_mfma_f32_16x16x32_bf16 v[26:29], v[158:161], v[198:201], v[26:29]
	v_mfma_f32_16x16x32_bf16 v[12:15], v[150:153], v[206:209], v[12:15]
	v_mfma_f32_16x16x32_bf16 v[8:11], v[158:161], v[206:209], v[8:11]
	v_mfma_f32_16x16x32_bf16 v[62:65], v[154:157], v[186:189], v[62:65]
	v_mfma_f32_16x16x32_bf16 v[58:61], v[162:165], v[186:189], v[58:61]
	v_mfma_f32_16x16x32_bf16 v[46:49], v[154:157], v[194:197], v[46:49]
	v_mfma_f32_16x16x32_bf16 v[42:45], v[162:165], v[194:197], v[42:45]
	v_mfma_f32_16x16x32_bf16 v[30:33], v[154:157], v[202:205], v[30:33]
	v_mfma_f32_16x16x32_bf16 v[26:29], v[162:165], v[202:205], v[26:29]
	v_mfma_f32_16x16x32_bf16 v[12:15], v[154:157], v[210:213], v[12:15]
	v_mfma_f32_16x16x32_bf16 v[8:11], v[162:165], v[210:213], v[8:11]
	v_mfma_f32_16x16x32_bf16 v[54:57], v[166:169], v[182:185], v[54:57]
	v_mfma_f32_16x16x32_bf16 v[50:53], v[174:177], v[182:185], v[50:53]
	v_mfma_f32_16x16x32_bf16 v[38:41], v[166:169], v[190:193], v[38:41]
	v_mfma_f32_16x16x32_bf16 v[34:37], v[174:177], v[190:193], v[34:37]
	v_mfma_f32_16x16x32_bf16 v[22:25], v[166:169], v[198:201], v[22:25]
	v_mfma_f32_16x16x32_bf16 v[18:21], v[174:177], v[198:201], v[18:21]
	v_mfma_f32_16x16x32_bf16 v[4:7], v[166:169], v[206:209], v[4:7]
	v_mfma_f32_16x16x32_bf16 v[0:3], v[174:177], v[206:209], v[0:3]
	v_mfma_f32_16x16x32_bf16 v[54:57], v[170:173], v[186:189], v[54:57]
	v_mfma_f32_16x16x32_bf16 v[50:53], v[178:181], v[186:189], v[50:53]
	v_mfma_f32_16x16x32_bf16 v[38:41], v[170:173], v[194:197], v[38:41]
	v_mfma_f32_16x16x32_bf16 v[34:37], v[178:181], v[194:197], v[34:37]
	v_mfma_f32_16x16x32_bf16 v[22:25], v[170:173], v[202:205], v[22:25]
	v_mfma_f32_16x16x32_bf16 v[18:21], v[178:181], v[202:205], v[18:21]
	v_mfma_f32_16x16x32_bf16 v[4:7], v[170:173], v[210:213], v[4:7]
	v_mfma_f32_16x16x32_bf16 v[0:3], v[178:181], v[210:213], v[0:3]
	s_barrier
; #define PG8_STAGEA(bufoff, gbase, voff) PG8_STAGE_X(bufoff, gbase, voff, AUXA)
; #define PG8_STAGEB(bufoff, gbase, voff) PG8_STAGE_X(bufoff, gbase, voff, AUXB)
; #define PG8_LDA(dst, b, h) do { _Pragma("unroll") for (int m = 0; m < 4; ++m) _Pragma("unroll") for (int k = 0; k < 2; ++k) dst[m][k] = *(const PG8_LAS bf16x8*)(lds + PG8_SA(b, h) + aoff + m * 2048 + k * 1024); } while (0)
; #define PG8_LDB(dst, b, h) do { _Pragma("unroll") for (int n = 0; n < 2; ++n) _Pragma("unroll") for (int k = 0; k < 2; ++k) dst[n][k] = *(const PG8_LAS bf16x8*)(lds + PG8_SB(b, h) + boff + n * 2048 + k * 1024); } while (0)
; #define PG8_MMA(ai, bj, At, Bt) do { if (GEMM_PRIO_MODE == 0) __builtin_amdgcn_s_setprio(1); PG8_MMA_LOOPS \
;         acc[ai][bj][m][n] = __builtin_amdgcn_mfma_f32_16x16x32_bf16(Bt[n][k], At[m][k], acc[ai][bj][m][n], 0, 0, 0); if (GEMM_PRIO_MODE == 0) __builtin_amdgcn_s_setprio(0); } while (0)
; #define PG8_WAIT_V(n) asm volatile("s_waitcnt vmcnt(" #n ")" ::: "memory")
; #define PG8_WAIT_VR(n, nr, flag) asm volatile("s_cmp_eq_u32 %0, 0\n\ts_cbranch_scc1 .Lpg8s%=\n\ts_waitcnt vmcnt(" #nr ")\n\ts_branch .Lpg8d%=\n.Lpg8s%=:\n\ts_waitcnt vmcnt(" #n ")\n.Lpg8d%=:" :: "s"(flag) : "memory", "scc")
; #define PG8_WAIT_L(n) asm volatile("s_waitcnt lgkmcnt(" #n ")" ::: "memory")
; #define PG8_BAR __builtin_amdgcn_s_barrier()
; #define PG8_SCHED __builtin_amdgcn_sched_barrier(0)
;     ...
;             PG8_LDA(At, 0, 1); PG8_STAGEB(PG8_SB(0, 0), b2, voffB); PG8_STAGEB(PG8_SB(0, 1), b2 + hstepB, voffB); PG8_STAGEA(PG8_SA(0, 0), a2, voffA);
;     ...
;             PG8_WAIT_VR(8, 24, relax); PG8_WAIT_L(0); PG8_BAR; PG8_MMA(1, 0, At, B0); PG8_MMA(1, 1, At, B1); PG8_BAR; PG8_SCHED;
;     ...
;             PG8_WAIT_V(8); PG8_WAIT_L(0); PG8_BAR; PG8_MMA(1, 0, At, B0); PG8_MMA(1, 1, At, B1); PG8_BAR; PG8_SCHED;
;     ...
;             PG8_LDB(B0, 1, 0); PG8_LDB(B1, 1, 1); PG8_SCHED; PG8_LDA(At, 1, 0); PG8_STAGEA(PG8_SA(0, 1), a2 + hstepA, voffA);
;             PG8_WAIT_V(8); PG8_WAIT_L(0); PG8_BAR; PG8_MMA(0, 0, At, B0); PG8_MMA(0, 1, At, B1); PG8_BAR; PG8_SCHED;
;             PG8_LDA(At, 1, 1); PG8_STAGEB(PG8_SB(1, 0), b3, voffB); PG8_STAGEB(PG8_SB(1, 1), b3 + hstepB, voffB); PG8_STAGEA(PG8_SA(1, 0), a3, voffA);
;             PG8_WAIT_V(8); PG8_WAIT_L(0); PG8_BAR; PG8_MMA(1, 0, At, B0); PG8_MMA(1, 1, At, B1); PG8_BAR; PG8_SCHED;
	s_add_i32 s95, 0, 0x18000
	v_add_u32_e32 v149, s95, v146
	s_add_i32 vcc_lo, 0, 0x1c000
	ds_read_b128 v[150:153], v149
	ds_read_b128 v[154:157], v149 offset:1024
	ds_read_b128 v[158:161], v149 offset:2048
	ds_read_b128 v[162:165], v149 offset:3072
	v_add_u32_e32 v149, vcc_lo, v146
	ds_read_b128 v[166:169], v149
	ds_read_b128 v[170:173], v149 offset:1024
	ds_read_b128 v[174:177], v149 offset:2048
	ds_read_b128 v[178:181], v149 offset:3072
	s_add_u32 s6, s42, 0x100000
	s_addc_u32 s7, s43, 0
	s_mov_b32 m0, s73
	v_lshl_add_u64 v[220:221], s[6:7], 0, v[136:137]
	ds_read_b128 v[182:185], v148 offset:32768
	ds_read_b128 v[186:189], v148 offset:33792
	ds_read_b128 v[190:193], v148 offset:34816
	ds_read_b128 v[194:197], v148 offset:35840
	ds_read_b128 v[198:201], v148 offset:36864
	ds_read_b128 v[202:205], v148 offset:37888
	ds_read_b128 v[206:209], v148 offset:38912
	ds_read_b128 v[210:213], v148 offset:39936
	global_load_lds_dwordx4 v[220:221], off
	v_lshl_add_u64 v[220:221], s[6:7], 0, v[132:133]
	s_mov_b32 m0, s82
	s_nop 0
	global_load_lds_dwordx4 v[220:221], off
	s_waitcnt vmcnt(8)
	s_waitcnt lgkmcnt(0)
	s_barrier
	v_mfma_f32_16x16x32_bf16 v[126:129], v[150:153], v[182:185], v[126:129]
	v_mfma_f32_16x16x32_bf16 v[122:125], v[158:161], v[182:185], v[122:125]
	v_mfma_f32_16x16x32_bf16 v[110:113], v[150:153], v[190:193], v[110:113]
	v_mfma_f32_16x16x32_bf16 v[106:109], v[158:161], v[190:193], v[106:109]
	v_mfma_f32_16x16x32_bf16 v[94:97], v[150:153], v[198:201], v[94:97]
	v_mfma_f32_16x16x32_bf16 v[90:93], v[158:161], v[198:201], v[90:93]
	v_mfma_f32_16x16x32_bf16 v[78:81], v[150:153], v[206:209], v[78:81]
	v_mfma_f32_16x16x32_bf16 v[74:77], v[158:161], v[206:209], v[74:77]
	v_mfma_f32_16x16x32_bf16 v[126:129], v[154:157], v[186:189], v[126:129]
	v_mfma_f32_16x16x32_bf16 v[122:125], v[162:165], v[186:189], v[122:125]
	v_mfma_f32_16x16x32_bf16 v[110:113], v[154:157], v[194:197], v[110:113]
	v_mfma_f32_16x16x32_bf16 v[106:109], v[162:165], v[194:197], v[106:109]
	v_mfma_f32_16x16x32_bf16 v[94:97], v[154:157], v[202:205], v[94:97]
	v_mfma_f32_16x16x32_bf16 v[90:93], v[162:165], v[202:205], v[90:93]
	v_mfma_f32_16x16x32_bf16 v[78:81], v[154:157], v[210:213], v[78:81]
	v_mfma_f32_16x16x32_bf16 v[74:77], v[162:165], v[210:213], v[74:77]
	v_mfma_f32_16x16x32_bf16 v[118:121], v[166:169], v[182:185], v[118:121]
	v_mfma_f32_16x16x32_bf16 v[114:117], v[174:177], v[182:185], v[114:117]
	v_mfma_f32_16x16x32_bf16 v[102:105], v[166:169], v[190:193], v[102:105]
	v_mfma_f32_16x16x32_bf16 v[98:101], v[174:177], v[190:193], v[98:101]
	v_mfma_f32_16x16x32_bf16 v[86:89], v[166:169], v[198:201], v[86:89]
	v_mfma_f32_16x16x32_bf16 v[82:85], v[174:177], v[198:201], v[82:85]
	v_mfma_f32_16x16x32_bf16 v[70:73], v[166:169], v[206:209], v[70:73]
	v_mfma_f32_16x16x32_bf16 v[66:69], v[174:177], v[206:209], v[66:69]
	v_mfma_f32_16x16x32_bf16 v[118:121], v[170:173], v[186:189], v[118:121]
	v_mfma_f32_16x16x32_bf16 v[114:117], v[178:181], v[186:189], v[114:117]
	v_mfma_f32_16x16x32_bf16 v[102:105], v[170:173], v[194:197], v[102:105]
	v_mfma_f32_16x16x32_bf16 v[98:101], v[178:181], v[194:197], v[98:101]
	v_mfma_f32_16x16x32_bf16 v[86:89], v[170:173], v[202:205], v[86:89]
	v_mfma_f32_16x16x32_bf16 v[82:85], v[178:181], v[202:205], v[82:85]
	v_mfma_f32_16x16x32_bf16 v[70:73], v[170:173], v[210:213], v[70:73]
	v_mfma_f32_16x16x32_bf16 v[66:69], v[178:181], v[210:213], v[66:69]
	s_barrier
; #define PG8_STAGEA(bufoff, gbase, voff) PG8_STAGE_X(bufoff, gbase, voff, AUXA)
; #define PG8_STAGEB(bufoff, gbase, voff) PG8_STAGE_X(bufoff, gbase, voff, AUXB)
; #define PG8_LDA(dst, b, h) do { _Pragma("unroll") for (int m = 0; m < 4; ++m) _Pragma("unroll") for (int k = 0; k < 2; ++k) dst[m][k] = *(const PG8_LAS bf16x8*)(lds + PG8_SA(b, h) + aoff + m * 2048 + k * 1024); } while (0)
; #define PG8_WAIT_V(n) asm volatile("s_waitcnt vmcnt(" #n ")" ::: "memory")
; #define PG8_BAR __builtin_amdgcn_s_barrier()
;     ...
;             PG8_LDB(B0, 1, 0); PG8_LDB(B1, 1, 1); PG8_SCHED; PG8_LDA(At, 1, 0); PG8_STAGEA(PG8_SA(0, 1), a2 + hstepA, voffA);
;             PG8_WAIT_V(8); PG8_WAIT_L(0); PG8_BAR; PG8_MMA(0, 0, At, B0); PG8_MMA(0, 1, At, B1); PG8_BAR; PG8_SCHED;
;             PG8_LDA(At, 1, 1); PG8_STAGEB(PG8_SB(1, 0), b3, voffB); PG8_STAGEB(PG8_SB(1, 1), b3 + hstepB, voffB); PG8_STAGEA(PG8_SA(1, 0), a3, voffA);
;             PG8_WAIT_V(8); PG8_WAIT_L(0); PG8_BAR; PG8_MMA(1, 0, At, B0); PG8_MMA(1, 1, At, B1); PG8_BAR; PG8_SCHED;
;             } else {
;             PG8_LDB(B0, 0, 0); PG8_SCHED; PG8_LDA(At, 0, 0); PG8_STAGEA(PG8_SA(1, 1), a1 + hstepA, voffA);
;             PG8_WAIT_L(8); PG8_BAR; PG8_WAIT_L(0); PG8_MMA(0, 0, At, B0); PG8_BAR; PG8_SCHED;
;             PG8_LDB(B1, 0, 1); PG8_STAGEB(PG8_SB(0, 0), b2, voffB);
;             PG8_BAR; PG8_WAIT_L(0); PG8_MMA(0, 1, At, B1); PG8_BAR;
;             PG8_LDA(At, 0, 1); PG8_STAGEA(PG8_SA(0, 0), a2, voffA);
;             PG8_BAR; PG8_WAIT_L(0); PG8_MMA(1, 0, At, B0); PG8_BAR; PG8_SCHED;
;             PG8_STAGEB(PG8_SB(0, 1), b2 + hstepB, voffB);
;             PG8_WAIT_V(6); PG8_BAR; PG8_MMA(1, 1, At, B1); PG8_BAR;
;             PG8_LDB(B0, 1, 0); PG8_SCHED; PG8_LDA(At, 1, 0); PG8_STAGEA(PG8_SA(0, 1), a2 + hstepA, voffA);
;             PG8_WAIT_L(8); PG8_BAR; PG8_WAIT_L(0); PG8_MMA(0, 0, At, B0); PG8_BAR; PG8_SCHED;
;             PG8_LDB(B1, 1, 1); PG8_STAGEB(PG8_SB(1, 0), b3, voffB);
;             PG8_BAR; PG8_WAIT_L(0); PG8_MMA(0, 1, At, B1); PG8_BAR;
;             PG8_LDA(At, 1, 1); PG8_STAGEA(PG8_SA(1, 0), a3, voffA);
;             PG8_BAR; PG8_WAIT_L(0); PG8_MMA(1, 0, At, B0); PG8_BAR; PG8_SCHED;
;             PG8_STAGEB(PG8_SB(1, 1), b3 + hstepB, voffB);
;             PG8_WAIT_V(6); PG8_BAR; PG8_MMA(1, 1, At, B1); PG8_BAR;
;             }
;         }
;         if constexpr (ALIGN_EPI) { if (wr == 0) PG8_BAR; }
	s_add_i32 s6, s95, s50
	v_lshl_add_u64 v[144:145], v[144:145], 0, s[86:87]
	s_mov_b32 m0, s6
	ds_read_b128 v[182:185], v148 offset:49152
	ds_read_b128 v[186:189], v148 offset:50176
	ds_read_b128 v[190:193], v148 offset:51200
	ds_read_b128 v[194:197], v148 offset:52224
	ds_read_b128 v[198:201], v148 offset:53248
	ds_read_b128 v[202:205], v148 offset:54272
	ds_read_b128 v[206:209], v148 offset:55296
	ds_read_b128 v[210:213], v148 offset:56320
	global_load_lds_dwordx4 v[144:145], off
	s_add_i32 m0, s6, 0x2000
	s_add_u32 s6, s16, 0x100080
	v_lshl_add_u64 v[144:145], v[214:215], 0, s[86:87]
	s_addc_u32 s7, s17, 0
	s_add_i32 s16, vcc_lo, s50
	global_load_lds_dwordx4 v[144:145], off
	v_lshl_add_u64 v[144:145], s[6:7], 0, v[134:135]
	s_mov_b32 m0, s16
	s_nop 0
	global_load_lds_dwordx4 v[144:145], off
	v_lshl_add_u64 v[144:145], s[6:7], 0, v[130:131]
	s_add_i32 m0, s16, 0x2000
	s_nop 0
	global_load_lds_dwordx4 v[144:145], off
	v_lshl_add_u64 v[144:145], v[216:217], 0, s[86:87]
	s_mov_b32 m0, s83
	s_nop 0
	global_load_lds_dwordx4 v[144:145], off
	v_lshl_add_u64 v[144:145], v[218:219], 0, s[86:87]
	s_mov_b32 m0, s90
	s_nop 0
	global_load_lds_dwordx4 v[144:145], off
	s_waitcnt vmcnt(8)
	s_waitcnt lgkmcnt(0)
	s_barrier
	v_mfma_f32_16x16x32_bf16 v[62:65], v[150:153], v[182:185], v[62:65]
	v_mfma_f32_16x16x32_bf16 v[58:61], v[158:161], v[182:185], v[58:61]
	v_mfma_f32_16x16x32_bf16 v[46:49], v[150:153], v[190:193], v[46:49]
	v_mfma_f32_16x16x32_bf16 v[42:45], v[158:161], v[190:193], v[42:45]
	v_mfma_f32_16x16x32_bf16 v[30:33], v[150:153], v[198:201], v[30:33]
	v_mfma_f32_16x16x32_bf16 v[26:29], v[158:161], v[198:201], v[26:29]
	v_mfma_f32_16x16x32_bf16 v[12:15], v[150:153], v[206:209], v[12:15]
	v_mfma_f32_16x16x32_bf16 v[8:11], v[158:161], v[206:209], v[8:11]
	v_mfma_f32_16x16x32_bf16 v[62:65], v[154:157], v[186:189], v[62:65]
	v_mfma_f32_16x16x32_bf16 v[58:61], v[162:165], v[186:189], v[58:61]
	v_mfma_f32_16x16x32_bf16 v[46:49], v[154:157], v[194:197], v[46:49]
	v_mfma_f32_16x16x32_bf16 v[42:45], v[162:165], v[194:197], v[42:45]
	v_mfma_f32_16x16x32_bf16 v[30:33], v[154:157], v[202:205], v[30:33]
	v_mfma_f32_16x16x32_bf16 v[26:29], v[162:165], v[202:205], v[26:29]
	v_mfma_f32_16x16x32_bf16 v[12:15], v[154:157], v[210:213], v[12:15]
	v_mfma_f32_16x16x32_bf16 v[8:11], v[162:165], v[210:213], v[8:11]
	v_mfma_f32_16x16x32_bf16 v[54:57], v[166:169], v[182:185], v[54:57]
	v_mfma_f32_16x16x32_bf16 v[50:53], v[174:177], v[182:185], v[50:53]
	v_mfma_f32_16x16x32_bf16 v[38:41], v[166:169], v[190:193], v[38:41]
	v_mfma_f32_16x16x32_bf16 v[34:37], v[174:177], v[190:193], v[34:37]
	v_mfma_f32_16x16x32_bf16 v[22:25], v[166:169], v[198:201], v[22:25]
	v_mfma_f32_16x16x32_bf16 v[18:21], v[174:177], v[198:201], v[18:21]
	v_mfma_f32_16x16x32_bf16 v[4:7], v[166:169], v[206:209], v[4:7]
	v_mfma_f32_16x16x32_bf16 v[0:3], v[174:177], v[206:209], v[0:3]
	v_mfma_f32_16x16x32_bf16 v[54:57], v[170:173], v[186:189], v[54:57]
	v_mfma_f32_16x16x32_bf16 v[50:53], v[178:181], v[186:189], v[50:53]
	v_mfma_f32_16x16x32_bf16 v[38:41], v[170:173], v[194:197], v[38:41]
	v_mfma_f32_16x16x32_bf16 v[34:37], v[178:181], v[194:197], v[34:37]
	v_mfma_f32_16x16x32_bf16 v[22:25], v[170:173], v[202:205], v[22:25]
	v_mfma_f32_16x16x32_bf16 v[18:21], v[178:181], v[202:205], v[18:21]
	v_mfma_f32_16x16x32_bf16 v[4:7], v[170:173], v[210:213], v[4:7]
	v_mfma_f32_16x16x32_bf16 v[0:3], v[178:181], v[210:213], v[0:3]
	s_barrier
	s_add_i32 s39, s39, 2
	s_add_u32 s40, s40, 0x100
	s_addc_u32 s41, s41, 0
	s_add_u32 s12, s12, 0x100
	s_addc_u32 s13, s13, 0
	s_cmp_gt_u32 s39, 61
	s_cbranch_scc0 .LBB0_712
	s_setprio 0
	s_and_b64 vcc, exec, s[18:19]
	s_cbranch_vccz .LBB0_715
	s_barrier

; #define PG8_STR(x) PG8_STR2(x)
;     ...
;         const char* nA = has_next ? (const char*)g.A + (size_t)nxt.pm * tstepA : cA; const char* nB = has_next ? (const char*)g.Bt + (size_t)nxt.pn * tstepB : cB;
;         int t0 = 0;
;         if constexpr (SP2 && GEMM_RELAX == 1) { if (ui > 0) {
;             const char* a1 = cA + kstepA; const char* a2 = cA + 2 * kstepA; const char* b2 = cB + 2 * kstepB; const char* a3 = a2 + kstepA; const char* b3 = b2 + kstepB;
;             PG8_LDB(B0, 0, 0); PG8_LDB(B1, 0, 1); PG8_SCHED; PG8_LDA(At, 0, 0); PG8_STAGEA(PG8_SA(1, 1), a1 + hstepA, voffA);
;             PG8_WAIT_V(24); PG8_WAIT_L(0); PG8_BAR; PG8_MMA(0, 0, At, B0); PG8_MMA(0, 1, At, B1); PG8_BAR; PG8_SCHED;
;             PG8_LDA(At, 0, 1); PG8_STAGEB(PG8_SB(0, 0), b2, voffB); PG8_STAGEB(PG8_SB(0, 1), b2 + hstepB, voffB); PG8_STAGEA(PG8_SA(0, 0), a2, voffA);
;             PG8_WAIT_V(24); PG8_WAIT_L(0); PG8_BAR; PG8_MMA(1, 0, At, B0); PG8_MMA(1, 1, At, B1); PG8_BAR; PG8_SCHED;
;             PG8_LDB(B0, 1, 0); PG8_LDB(B1, 1, 1); PG8_SCHED; PG8_LDA(At, 1, 0); PG8_STAGEA(PG8_SA(0, 1), a2 + hstepA, voffA);
;             PG8_WAIT_V(8); PG8_WAIT_L(0); PG8_BAR; PG8_MMA(0, 0, At, B0); PG8_MMA(0, 1, At, B1); PG8_BAR; PG8_SCHED;
;             PG8_LDA(At, 1, 1); PG8_STAGEB(PG8_SB(1, 0), b3, voffB); PG8_STAGEB(PG8_SB(1, 1), b3 + hstepB, voffB); PG8_STAGEA(PG8_SA(1, 0), a3, voffA);
;             PG8_WAIT_V(8); PG8_WAIT_L(0); PG8_BAR; PG8_MMA(1, 0, At, B0); PG8_MMA(1, 1, At, B1); PG8_BAR; PG8_SCHED;
;             t0 = 2; } }
;     ...
;         asm volatile(".p2align " PG8_STR(GEMM_LOOP_ALIGN) ::: "memory");
;     ...
;         for (int t = t0; t < nt; t += 2) {
;             const bool last = (t == nt - 2);
;             const char* a1 = cA + (size_t)(t + 1) * kstepA;
;             const char* a2 = last ? nA : cA + (size_t)(t + 2) * kstepA; const char* b2 = last ? nB : cB + (size_t)(t + 2) * kstepB;
;             const char* a3 = a2 + kstepA; const char* b3 = b2 + kstepB;
;             if (last && has_next) S.a_ready(nxt);
;             if constexpr (SP2) {
;             PG8_LDB(B0, 0, 0); PG8_LDB(B1, 0, 1); PG8_SCHED; PG8_LDA(At, 0, 0); PG8_STAGEA(PG8_SA(1, 1), a1 + hstepA, voffA);
;     ...
;             const int relax = __builtin_amdgcn_readfirstlane((t == 0 && ui > 0) ? 1 : 0);
;             PG8_WAIT_VR(8, 24, relax); PG8_WAIT_L(0); PG8_BAR; PG8_MMA(0, 0, At, B0); PG8_MMA(0, 1, At, B1); PG8_BAR; PG8_SCHED;
.LBB0_847:
	s_ashr_i32 s11, s10, 31
	s_lshl_b64 s[18:19], s[10:11], 23
	s_add_u32 s18, s62, s18
	s_addc_u32 s19, s63, s19
	s_and_b64 s[22:23], s[20:21], exec
	s_cselect_b32 s11, s19, s1
	s_cselect_b32 s73, s18, s0
	s_ashr_i32 s15, s14, 31
	s_lshl_b64 s[22:23], s[14:15], 23
	s_add_u32 s22, s12, s22
	s_addc_u32 s23, s13, s23
	s_and_b64 s[24:25], s[20:21], exec
	s_cselect_b32 s15, s23, s17
	s_cselect_b32 s78, s22, s16
	s_add_u32 s24, s0, 0xc000
	s_addc_u32 s25, s1, 0
	s_add_u32 s0, s16, 0x10000
	s_addc_u32 s1, s17, 0
	s_mov_b32 s82, -2
	s_waitcnt lgkmcnt(0)
	s_and_b64 vcc, exec, s[8:9]
	s_cbranch_vccnz .Lsprio_g4
	s_setprio 1
.Lsprio_g4:
	s_add_u32 s16, s24, 0x4000
	s_addc_u32 s17, s25, 0
	s_cmpk_eq_i32 s82, 0xfc
	s_cselect_b32 s36, s73, s16
	s_cselect_b32 s37, s11, s17
	s_cselect_b32 s16, s78, s0
	s_cselect_b32 s17, s15, s1
	s_add_u32 s26, s36, 0x8000
	s_addc_u32 s27, s37, 0
	s_add_i32 s83, 0, 0x10000
	s_add_i32 s94, 0, 0x14000
	v_add_u32_e32 v152, s83, v157
	v_add_u32_e32 v174, s94, v157
	ds_read_b128 v[130:133], v152
	ds_read_b128 v[134:137], v152 offset:1024
	ds_read_b128 v[148:151], v152 offset:2048
	ds_read_b128 v[152:155], v152 offset:3072
	ds_read_b128 v[162:165], v174
	ds_read_b128 v[166:169], v174 offset:1024
	ds_read_b128 v[170:173], v174 offset:2048
	ds_read_b128 v[174:177], v174 offset:3072
	v_lshl_add_u64 v[210:211], s[24:25], 0, v[144:145]
	s_add_i32 m0, s39, 0xc000
	ds_read_b128 v[178:181], v161
	ds_read_b128 v[182:185], v161 offset:1024
	ds_read_b128 v[186:189], v161 offset:2048
	ds_read_b128 v[190:193], v161 offset:3072
	ds_read_b128 v[194:197], v161 offset:4096
	ds_read_b128 v[198:201], v161 offset:5120
	ds_read_b128 v[202:205], v161 offset:6144
	ds_read_b128 v[206:209], v161 offset:7168
	global_load_lds_dwordx4 v[210:211], off
	v_lshl_add_u64 v[210:211], s[24:25], 0, v[146:147]
	s_add_i32 m0, s39, 0xe000
	s_nop 0
	global_load_lds_dwordx4 v[210:211], off
	s_waitcnt vmcnt(8)
	s_waitcnt lgkmcnt(0)
	s_barrier
	v_mfma_f32_16x16x32_bf16 v[126:129], v[130:133], v[178:181], 0
	v_mfma_f32_16x16x32_bf16 v[122:125], v[148:151], v[178:181], 0
	v_mfma_f32_16x16x32_bf16 v[110:113], v[130:133], v[186:189], 0
	v_mfma_f32_16x16x32_bf16 v[106:109], v[148:151], v[186:189], 0
	v_mfma_f32_16x16x32_bf16 v[94:97], v[130:133], v[194:197], 0
	v_mfma_f32_16x16x32_bf16 v[90:93], v[148:151], v[194:197], 0
	v_mfma_f32_16x16x32_bf16 v[78:81], v[130:133], v[202:205], 0
	v_mfma_f32_16x16x32_bf16 v[74:77], v[148:151], v[202:205], 0
	v_mfma_f32_16x16x32_bf16 v[126:129], v[134:137], v[182:185], v[126:129]
	v_mfma_f32_16x16x32_bf16 v[122:125], v[152:155], v[182:185], v[122:125]
	v_mfma_f32_16x16x32_bf16 v[110:113], v[134:137], v[190:193], v[110:113]
	v_mfma_f32_16x16x32_bf16 v[106:109], v[152:155], v[190:193], v[106:109]
	v_mfma_f32_16x16x32_bf16 v[94:97], v[134:137], v[198:201], v[94:97]
	v_mfma_f32_16x16x32_bf16 v[90:93], v[152:155], v[198:201], v[90:93]
	v_mfma_f32_16x16x32_bf16 v[78:81], v[134:137], v[206:209], v[78:81]
	v_mfma_f32_16x16x32_bf16 v[74:77], v[152:155], v[206:209], v[74:77]
	v_mfma_f32_16x16x32_bf16 v[118:121], v[162:165], v[178:181], 0
	v_mfma_f32_16x16x32_bf16 v[114:117], v[170:173], v[178:181], 0
	v_mfma_f32_16x16x32_bf16 v[102:105], v[162:165], v[186:189], 0
	v_mfma_f32_16x16x32_bf16 v[98:101], v[170:173], v[186:189], 0
	v_mfma_f32_16x16x32_bf16 v[86:89], v[162:165], v[194:197], 0
	v_mfma_f32_16x16x32_bf16 v[82:85], v[170:173], v[194:197], 0
	v_mfma_f32_16x16x32_bf16 v[70:73], v[162:165], v[202:205], 0
	v_mfma_f32_16x16x32_bf16 v[66:69], v[170:173], v[202:205], 0
	v_mfma_f32_16x16x32_bf16 v[118:121], v[166:169], v[182:185], v[118:121]
	v_mfma_f32_16x16x32_bf16 v[114:117], v[174:177], v[182:185], v[114:117]
	v_mfma_f32_16x16x32_bf16 v[102:105], v[166:169], v[190:193], v[102:105]
	v_mfma_f32_16x16x32_bf16 v[98:101], v[174:177], v[190:193], v[98:101]
	v_mfma_f32_16x16x32_bf16 v[86:89], v[166:169], v[198:201], v[86:89]
	v_mfma_f32_16x16x32_bf16 v[82:85], v[174:177], v[198:201], v[82:85]
	v_mfma_f32_16x16x32_bf16 v[70:73], v[166:169], v[206:209], v[70:73]
	v_mfma_f32_16x16x32_bf16 v[66:69], v[174:177], v[206:209], v[66:69]
	s_barrier
	s_add_i32 s83, s83, s38
	v_lshl_add_u64 v[210:211], s[16:17], 0, v[16:17]
	s_mov_b32 m0, s83
	ds_read_b128 v[178:181], v161 offset:16384
	ds_read_b128 v[182:185], v161 offset:17408
	ds_read_b128 v[186:189], v161 offset:18432
	ds_read_b128 v[190:193], v161 offset:19456
	ds_read_b128 v[194:197], v161 offset:20480
	ds_read_b128 v[198:201], v161 offset:21504
	ds_read_b128 v[202:205], v161 offset:22528
	ds_read_b128 v[206:209], v161 offset:23552
	global_load_lds_dwordx4 v[210:211], off
	s_add_i32 m0, s83, 0x2000
	s_add_u32 s90, s16, 0x4000
	v_lshl_add_u64 v[210:211], s[16:17], 0, v[138:139]
	s_addc_u32 s91, s17, 0
	s_add_i32 s83, s94, s38
	global_load_lds_dwordx4 v[210:211], off
	v_lshl_add_u64 v[210:211], s[90:91], 0, v[16:17]
	s_mov_b32 m0, s83
	s_nop 0
	global_load_lds_dwordx4 v[210:211], off
	v_lshl_add_u64 v[210:211], s[90:91], 0, v[138:139]
	s_add_i32 m0, s83, 0x2000
	s_nop 0
	global_load_lds_dwordx4 v[210:211], off
	v_lshl_add_u64 v[210:211], s[36:37], 0, v[142:143]
	s_mov_b32 m0, s39
	s_nop 0
	global_load_lds_dwordx4 v[210:211], off
	v_lshl_add_u64 v[210:211], s[36:37], 0, v[140:141]
	s_mov_b32 m0, s40
	s_nop 0
	global_load_lds_dwordx4 v[210:211], off
	s_waitcnt vmcnt(8)
	s_waitcnt lgkmcnt(0)
	s_barrier
; #define PG8_STAGEA(bufoff, gbase, voff) PG8_STAGE_X(bufoff, gbase, voff, AUXA)
; #define PG8_STAGEB(bufoff, gbase, voff) PG8_STAGE_X(bufoff, gbase, voff, AUXB)
; #define PG8_LDA(dst, b, h) do { _Pragma("unroll") for (int m = 0; m < 4; ++m) _Pragma("unroll") for (int k = 0; k < 2; ++k) dst[m][k] = *(const PG8_LAS bf16x8*)(lds + PG8_SA(b, h) + aoff + m * 2048 + k * 1024); } while (0)
; #define PG8_LDB(dst, b, h) do { _Pragma("unroll") for (int n = 0; n < 2; ++n) _Pragma("unroll") for (int k = 0; k < 2; ++k) dst[n][k] = *(const PG8_LAS bf16x8*)(lds + PG8_SB(b, h) + boff + n * 2048 + k * 1024); } while (0)
; #define PG8_MMA(ai, bj, At, Bt) do { if (GEMM_PRIO_MODE == 0) __builtin_amdgcn_s_setprio(1); PG8_MMA_LOOPS \
;         acc[ai][bj][m][n] = __builtin_amdgcn_mfma_f32_16x16x32_bf16(Bt[n][k], At[m][k], acc[ai][bj][m][n], 0, 0, 0); if (GEMM_PRIO_MODE == 0) __builtin_amdgcn_s_setprio(0); } while (0)
; #define PG8_WAIT_V(n) asm volatile("s_waitcnt vmcnt(" #n ")" ::: "memory")
; #define PG8_WAIT_VR(n, nr, flag) asm volatile("s_cmp_eq_u32 %0, 0\n\ts_cbranch_scc1 .Lpg8s%=\n\ts_waitcnt vmcnt(" #nr ")\n\ts_branch .Lpg8d%=\n.Lpg8s%=:\n\ts_waitcnt vmcnt(" #n ")\n.Lpg8d%=:" :: "s"(flag) : "memory", "scc")
; #define PG8_WAIT_L(n) asm volatile("s_waitcnt lgkmcnt(" #n ")" ::: "memory")
; #define PG8_BAR __builtin_amdgcn_s_barrier()
; #define PG8_SCHED __builtin_amdgcn_sched_barrier(0)
;     ...
;             PG8_LDA(At, 0, 1); PG8_STAGEB(PG8_SB(0, 0), b2, voffB); PG8_STAGEB(PG8_SB(0, 1), b2 + hstepB, voffB); PG8_STAGEA(PG8_SA(0, 0), a2, voffA);
;     ...
;             PG8_WAIT_VR(8, 24, relax); PG8_WAIT_L(0); PG8_BAR; PG8_MMA(1, 0, At, B0); PG8_MMA(1, 1, At, B1); PG8_BAR; PG8_SCHED;
;     ...
;             PG8_WAIT_V(8); PG8_WAIT_L(0); PG8_BAR; PG8_MMA(1, 0, At, B0); PG8_MMA(1, 1, At, B1); PG8_BAR; PG8_SCHED;
;     ...
;             PG8_LDB(B0, 1, 0); PG8_LDB(B1, 1, 1); PG8_SCHED; PG8_LDA(At, 1, 0); PG8_STAGEA(PG8_SA(0, 1), a2 + hstepA, voffA);
;             PG8_WAIT_V(8); PG8_WAIT_L(0); PG8_BAR; PG8_MMA(0, 0, At, B0); PG8_MMA(0, 1, At, B1); PG8_BAR; PG8_SCHED;
;             PG8_LDA(At, 1, 1); PG8_STAGEB(PG8_SB(1, 0), b3, voffB); PG8_STAGEB(PG8_SB(1, 1), b3 + hstepB, voffB); PG8_STAGEA(PG8_SA(1, 0), a3, voffA);
;             PG8_WAIT_V(8); PG8_WAIT_L(0); PG8_BAR; PG8_MMA(1, 0, At, B0); PG8_MMA(1, 1, At, B1); PG8_BAR; PG8_SCHED;
	v_mfma_f32_16x16x32_bf16 v[62:65], v[130:133], v[178:181], 0
	v_mfma_f32_16x16x32_bf16 v[58:61], v[148:151], v[178:181], 0
	v_mfma_f32_16x16x32_bf16 v[46:49], v[130:133], v[186:189], 0
	v_mfma_f32_16x16x32_bf16 v[42:45], v[148:151], v[186:189], 0
	v_mfma_f32_16x16x32_bf16 v[30:33], v[130:133], v[194:197], 0
	v_mfma_f32_16x16x32_bf16 v[26:29], v[148:151], v[194:197], 0
	v_mfma_f32_16x16x32_bf16 v[12:15], v[130:133], v[202:205], 0
	v_mfma_f32_16x16x32_bf16 v[8:11], v[148:151], v[202:205], 0
	v_mfma_f32_16x16x32_bf16 v[62:65], v[134:137], v[182:185], v[62:65]
	v_mfma_f32_16x16x32_bf16 v[58:61], v[152:155], v[182:185], v[58:61]
	v_mfma_f32_16x16x32_bf16 v[46:49], v[134:137], v[190:193], v[46:49]
	v_mfma_f32_16x16x32_bf16 v[42:45], v[152:155], v[190:193], v[42:45]
	v_mfma_f32_16x16x32_bf16 v[30:33], v[134:137], v[198:201], v[30:33]
	v_mfma_f32_16x16x32_bf16 v[26:29], v[152:155], v[198:201], v[26:29]
	v_mfma_f32_16x16x32_bf16 v[12:15], v[134:137], v[206:209], v[12:15]
	v_mfma_f32_16x16x32_bf16 v[8:11], v[152:155], v[206:209], v[8:11]
	v_mfma_f32_16x16x32_bf16 v[54:57], v[162:165], v[178:181], 0
	v_mfma_f32_16x16x32_bf16 v[50:53], v[170:173], v[178:181], 0
	v_mfma_f32_16x16x32_bf16 v[38:41], v[162:165], v[186:189], 0
	v_mfma_f32_16x16x32_bf16 v[34:37], v[170:173], v[186:189], 0
	v_mfma_f32_16x16x32_bf16 v[22:25], v[162:165], v[194:197], 0
	v_mfma_f32_16x16x32_bf16 v[18:21], v[170:173], v[194:197], 0
	v_mfma_f32_16x16x32_bf16 v[4:7], v[162:165], v[202:205], 0
	v_mfma_f32_16x16x32_bf16 v[0:3], v[170:173], v[202:205], 0
	v_mfma_f32_16x16x32_bf16 v[54:57], v[166:169], v[182:185], v[54:57]
	v_mfma_f32_16x16x32_bf16 v[50:53], v[174:177], v[182:185], v[50:53]
	v_mfma_f32_16x16x32_bf16 v[38:41], v[166:169], v[190:193], v[38:41]
	v_mfma_f32_16x16x32_bf16 v[34:37], v[174:177], v[190:193], v[34:37]
	v_mfma_f32_16x16x32_bf16 v[22:25], v[166:169], v[198:201], v[22:25]
	v_mfma_f32_16x16x32_bf16 v[18:21], v[174:177], v[198:201], v[18:21]
	v_mfma_f32_16x16x32_bf16 v[4:7], v[166:169], v[206:209], v[4:7]
	v_mfma_f32_16x16x32_bf16 v[0:3], v[174:177], v[206:209], v[0:3]
	s_barrier
	s_add_i32 s83, 0, 0x18000
	s_add_i32 s90, 0, 0x1c000
	v_add_u32_e32 v152, s83, v157
	v_add_u32_e32 v174, s90, v157
	ds_read_b128 v[130:133], v152
	ds_read_b128 v[134:137], v152 offset:1024
	ds_read_b128 v[148:151], v152 offset:2048
	ds_read_b128 v[152:155], v152 offset:3072
	ds_read_b128 v[162:165], v174
	ds_read_b128 v[166:169], v174 offset:1024
	ds_read_b128 v[170:173], v174 offset:2048
	ds_read_b128 v[174:177], v174 offset:3072
	s_add_u32 s36, s36, 0x4000
	s_addc_u32 s37, s37, 0
	s_mov_b32 m0, s41
	v_lshl_add_u64 v[210:211], s[36:37], 0, v[142:143]
	ds_read_b128 v[178:181], v161 offset:32768
	ds_read_b128 v[182:185], v161 offset:33792
	ds_read_b128 v[186:189], v161 offset:34816
	ds_read_b128 v[190:193], v161 offset:35840
	ds_read_b128 v[194:197], v161 offset:36864
	ds_read_b128 v[198:201], v161 offset:37888
	ds_read_b128 v[202:205], v161 offset:38912
	ds_read_b128 v[206:209], v161 offset:39936
	global_load_lds_dwordx4 v[210:211], off
	v_lshl_add_u64 v[210:211], s[36:37], 0, v[140:141]
	s_mov_b32 m0, s42
	s_nop 0
	global_load_lds_dwordx4 v[210:211], off
	s_waitcnt vmcnt(8)
	s_waitcnt lgkmcnt(0)
	s_barrier
	v_mfma_f32_16x16x32_bf16 v[126:129], v[130:133], v[178:181], v[126:129]
	v_mfma_f32_16x16x32_bf16 v[122:125], v[148:151], v[178:181], v[122:125]
	v_mfma_f32_16x16x32_bf16 v[110:113], v[130:133], v[186:189], v[110:113]
	v_mfma_f32_16x16x32_bf16 v[106:109], v[148:151], v[186:189], v[106:109]
	v_mfma_f32_16x16x32_bf16 v[94:97], v[130:133], v[194:197], v[94:97]
	v_mfma_f32_16x16x32_bf16 v[90:93], v[148:151], v[194:197], v[90:93]
	v_mfma_f32_16x16x32_bf16 v[78:81], v[130:133], v[202:205], v[78:81]
	v_mfma_f32_16x16x32_bf16 v[74:77], v[148:151], v[202:205], v[74:77]
	v_mfma_f32_16x16x32_bf16 v[126:129], v[134:137], v[182:185], v[126:129]
	v_mfma_f32_16x16x32_bf16 v[122:125], v[152:155], v[182:185], v[122:125]
	v_mfma_f32_16x16x32_bf16 v[110:113], v[134:137], v[190:193], v[110:113]
	v_mfma_f32_16x16x32_bf16 v[106:109], v[152:155], v[190:193], v[106:109]
	v_mfma_f32_16x16x32_bf16 v[94:97], v[134:137], v[198:201], v[94:97]
	v_mfma_f32_16x16x32_bf16 v[90:93], v[152:155], v[198:201], v[90:93]
	v_mfma_f32_16x16x32_bf16 v[78:81], v[134:137], v[206:209], v[78:81]
	v_mfma_f32_16x16x32_bf16 v[74:77], v[152:155], v[206:209], v[74:77]
	v_mfma_f32_16x16x32_bf16 v[118:121], v[162:165], v[178:181], v[118:121]
	v_mfma_f32_16x16x32_bf16 v[114:117], v[170:173], v[178:181], v[114:117]
	v_mfma_f32_16x16x32_bf16 v[102:105], v[162:165], v[186:189], v[102:105]
	v_mfma_f32_16x16x32_bf16 v[98:101], v[170:173], v[186:189], v[98:101]
	v_mfma_f32_16x16x32_bf16 v[86:89], v[162:165], v[194:197], v[86:89]
	v_mfma_f32_16x16x32_bf16 v[82:85], v[170:173], v[194:197], v[82:85]
	v_mfma_f32_16x16x32_bf16 v[70:73], v[162:165], v[202:205], v[70:73]
	v_mfma_f32_16x16x32_bf16 v[66:69], v[170:173], v[202:205], v[66:69]
	v_mfma_f32_16x16x32_bf16 v[118:121], v[166:169], v[182:185], v[118:121]
	v_mfma_f32_16x16x32_bf16 v[114:117], v[174:177], v[182:185], v[114:117]
	v_mfma_f32_16x16x32_bf16 v[102:105], v[166:169], v[190:193], v[102:105]
	v_mfma_f32_16x16x32_bf16 v[98:101], v[174:177], v[190:193], v[98:101]
	v_mfma_f32_16x16x32_bf16 v[86:89], v[166:169], v[198:201], v[86:89]
	v_mfma_f32_16x16x32_bf16 v[82:85], v[174:177], v[198:201], v[82:85]
	v_mfma_f32_16x16x32_bf16 v[70:73], v[166:169], v[206:209], v[70:73]
	v_mfma_f32_16x16x32_bf16 v[66:69], v[174:177], v[206:209], v[66:69]
	s_barrier
; #define PG8_STAGEA(bufoff, gbase, voff) PG8_STAGE_X(bufoff, gbase, voff, AUXA)
; #define PG8_STAGEB(bufoff, gbase, voff) PG8_STAGE_X(bufoff, gbase, voff, AUXB)
; #define PG8_LDA(dst, b, h) do { _Pragma("unroll") for (int m = 0; m < 4; ++m) _Pragma("unroll") for (int k = 0; k < 2; ++k) dst[m][k] = *(const PG8_LAS bf16x8*)(lds + PG8_SA(b, h) + aoff + m * 2048 + k * 1024); } while (0)
; #define PG8_WAIT_V(n) asm volatile("s_waitcnt vmcnt(" #n ")" ::: "memory")
; #define PG8_WAIT_L(n) asm volatile("s_waitcnt lgkmcnt(" #n ")" ::: "memory")
;     ...
;         for (int t = t0; t < nt; t += 2) {
;             const bool last = (t == nt - 2);
;             const char* a1 = cA + (size_t)(t + 1) * kstepA;
;             const char* a2 = last ? nA : cA + (size_t)(t + 2) * kstepA; const char* b2 = last ? nB : cB + (size_t)(t + 2) * kstepB;
;             const char* a3 = a2 + kstepA; const char* b3 = b2 + kstepB;
;             if (last && has_next) S.a_ready(nxt);
;             if constexpr (SP2) {
;             PG8_LDB(B0, 0, 0); PG8_LDB(B1, 0, 1); PG8_SCHED; PG8_LDA(At, 0, 0); PG8_STAGEA(PG8_SA(1, 1), a1 + hstepA, voffA);
;     ...
;             const int relax = __builtin_amdgcn_readfirstlane((t == 0 && ui > 0) ? 1 : 0);
;             PG8_WAIT_VR(8, 24, relax); PG8_WAIT_L(0); PG8_BAR; PG8_MMA(0, 0, At, B0); PG8_MMA(0, 1, At, B1); PG8_BAR; PG8_SCHED;
;     ...
;             PG8_WAIT_V(8); PG8_WAIT_L(0); PG8_BAR; PG8_MMA(0, 0, At, B0); PG8_MMA(0, 1, At, B1); PG8_BAR; PG8_SCHED;
;     ...
;             PG8_LDA(At, 0, 1); PG8_STAGEB(PG8_SB(0, 0), b2, voffB); PG8_STAGEB(PG8_SB(0, 1), b2 + hstepB, voffB); PG8_STAGEA(PG8_SA(0, 0), a2, voffA);
;     ...
;             PG8_WAIT_VR(8, 24, relax); PG8_WAIT_L(0); PG8_BAR; PG8_MMA(1, 0, At, B0); PG8_MMA(1, 1, At, B1); PG8_BAR; PG8_SCHED;
;     ...
;             PG8_WAIT_V(8); PG8_WAIT_L(0); PG8_BAR; PG8_MMA(1, 0, At, B0); PG8_MMA(1, 1, At, B1); PG8_BAR; PG8_SCHED;
;     ...
;             PG8_LDB(B0, 1, 0); PG8_LDB(B1, 1, 1); PG8_SCHED; PG8_LDA(At, 1, 0); PG8_STAGEA(PG8_SA(0, 1), a2 + hstepA, voffA);
;             PG8_WAIT_V(8); PG8_WAIT_L(0); PG8_BAR; PG8_MMA(0, 0, At, B0); PG8_MMA(0, 1, At, B1); PG8_BAR; PG8_SCHED;
;             PG8_LDA(At, 1, 1); PG8_STAGEB(PG8_SB(1, 0), b3, voffB); PG8_STAGEB(PG8_SB(1, 1), b3 + hstepB, voffB); PG8_STAGEA(PG8_SA(1, 0), a3, voffA);
;             PG8_WAIT_V(8); PG8_WAIT_L(0); PG8_BAR; PG8_MMA(1, 0, At, B0); PG8_MMA(1, 1, At, B1); PG8_BAR; PG8_SCHED;
	s_add_u32 s36, s16, 0x8000
	s_addc_u32 s37, s17, 0
	s_add_i32 s83, s83, s38
	v_lshl_add_u64 v[210:211], s[36:37], 0, v[16:17]
	s_mov_b32 m0, s83
	ds_read_b128 v[178:181], v161 offset:49152
	ds_read_b128 v[182:185], v161 offset:50176
	ds_read_b128 v[186:189], v161 offset:51200
	ds_read_b128 v[190:193], v161 offset:52224
	ds_read_b128 v[194:197], v161 offset:53248
	ds_read_b128 v[198:201], v161 offset:54272
	ds_read_b128 v[202:205], v161 offset:55296
	ds_read_b128 v[206:209], v161 offset:56320
	global_load_lds_dwordx4 v[210:211], off
	s_add_i32 m0, s83, 0x2000
	s_add_u32 s16, s16, 0xc000
	v_lshl_add_u64 v[210:211], s[36:37], 0, v[138:139]
	s_addc_u32 s17, s17, 0
	s_add_i32 s36, s90, s38
	global_load_lds_dwordx4 v[210:211], off
	v_lshl_add_u64 v[210:211], s[16:17], 0, v[16:17]
	s_mov_b32 m0, s36
	s_nop 0
	global_load_lds_dwordx4 v[210:211], off
	v_lshl_add_u64 v[210:211], s[16:17], 0, v[138:139]
	s_add_i32 m0, s36, 0x2000
	s_nop 0
	global_load_lds_dwordx4 v[210:211], off
	v_lshl_add_u64 v[210:211], s[26:27], 0, v[142:143]
	s_mov_b32 m0, s50
	s_nop 0
	global_load_lds_dwordx4 v[210:211], off
	v_lshl_add_u64 v[210:211], s[26:27], 0, v[140:141]
	s_mov_b32 m0, s51
	s_nop 0
	global_load_lds_dwordx4 v[210:211], off
	s_waitcnt vmcnt(8)
	s_waitcnt lgkmcnt(0)
	s_barrier
	v_mfma_f32_16x16x32_bf16 v[62:65], v[130:133], v[178:181], v[62:65]
	v_mfma_f32_16x16x32_bf16 v[58:61], v[148:151], v[178:181], v[58:61]
	v_mfma_f32_16x16x32_bf16 v[46:49], v[130:133], v[186:189], v[46:49]
	v_mfma_f32_16x16x32_bf16 v[42:45], v[148:151], v[186:189], v[42:45]
	v_mfma_f32_16x16x32_bf16 v[30:33], v[130:133], v[194:197], v[30:33]
	v_mfma_f32_16x16x32_bf16 v[26:29], v[148:151], v[194:197], v[26:29]
	v_mfma_f32_16x16x32_bf16 v[12:15], v[130:133], v[202:205], v[12:15]
	v_mfma_f32_16x16x32_bf16 v[8:11], v[148:151], v[202:205], v[8:11]
	v_mfma_f32_16x16x32_bf16 v[62:65], v[134:137], v[182:185], v[62:65]
	v_mfma_f32_16x16x32_bf16 v[58:61], v[152:155], v[182:185], v[58:61]
	v_mfma_f32_16x16x32_bf16 v[46:49], v[134:137], v[190:193], v[46:49]
	v_mfma_f32_16x16x32_bf16 v[42:45], v[152:155], v[190:193], v[42:45]
	v_mfma_f32_16x16x32_bf16 v[30:33], v[134:137], v[198:201], v[30:33]
	v_mfma_f32_16x16x32_bf16 v[26:29], v[152:155], v[198:201], v[26:29]
	v_mfma_f32_16x16x32_bf16 v[12:15], v[134:137], v[206:209], v[12:15]
	v_mfma_f32_16x16x32_bf16 v[8:11], v[152:155], v[206:209], v[8:11]
	v_mfma_f32_16x16x32_bf16 v[54:57], v[162:165], v[178:181], v[54:57]
	v_mfma_f32_16x16x32_bf16 v[50:53], v[170:173], v[178:181], v[50:53]
	v_mfma_f32_16x16x32_bf16 v[38:41], v[162:165], v[186:189], v[38:41]
	v_mfma_f32_16x16x32_bf16 v[34:37], v[170:173], v[186:189], v[34:37]
	v_mfma_f32_16x16x32_bf16 v[22:25], v[162:165], v[194:197], v[22:25]
	v_mfma_f32_16x16x32_bf16 v[18:21], v[170:173], v[194:197], v[18:21]
	v_mfma_f32_16x16x32_bf16 v[4:7], v[162:165], v[202:205], v[4:7]
	v_mfma_f32_16x16x32_bf16 v[0:3], v[170:173], v[202:205], v[0:3]
	v_mfma_f32_16x16x32_bf16 v[54:57], v[166:169], v[182:185], v[54:57]
	v_mfma_f32_16x16x32_bf16 v[50:53], v[174:177], v[182:185], v[50:53]
	v_mfma_f32_16x16x32_bf16 v[38:41], v[166:169], v[190:193], v[38:41]
	v_mfma_f32_16x16x32_bf16 v[34:37], v[174:177], v[190:193], v[34:37]
	v_mfma_f32_16x16x32_bf16 v[22:25], v[166:169], v[198:201], v[22:25]
	v_mfma_f32_16x16x32_bf16 v[18:21], v[174:177], v[198:201], v[18:21]
	v_mfma_f32_16x16x32_bf16 v[4:7], v[166:169], v[206:209], v[4:7]
	v_mfma_f32_16x16x32_bf16 v[0:3], v[174:177], v[206:209], v[0:3]
	s_barrier
	s_add_i32 s82, s82, 2
	s_add_u32 s24, s24, 0x10000
	s_addc_u32 s25, s25, 0
	s_add_u32 s0, s0, 0x10000
	s_addc_u32 s1, s1, 0
.LBB0_848:
	s_add_u32 s16, s24, 0x4000
	s_addc_u32 s17, s25, 0
	s_cmpk_eq_i32 s82, 0xfc
	s_cselect_b32 s36, s73, s16
	s_cselect_b32 s37, s11, s17
	s_cselect_b32 s16, s78, s0
	s_cselect_b32 s17, s15, s1
	s_add_u32 s26, s36, 0x8000
	s_addc_u32 s27, s37, 0
	s_add_i32 s83, 0, 0x10000
	s_add_i32 s94, 0, 0x14000
	v_add_u32_e32 v152, s83, v157
	v_add_u32_e32 v174, s94, v157
	ds_read_b128 v[130:133], v152
	ds_read_b128 v[134:137], v152 offset:1024
	ds_read_b128 v[148:151], v152 offset:2048
	ds_read_b128 v[152:155], v152 offset:3072
	ds_read_b128 v[162:165], v174
	ds_read_b128 v[166:169], v174 offset:1024
	ds_read_b128 v[170:173], v174 offset:2048
	ds_read_b128 v[174:177], v174 offset:3072
	v_lshl_add_u64 v[210:211], s[24:25], 0, v[144:145]
	s_add_i32 m0, s39, 0xc000
	ds_read_b128 v[178:181], v161
	ds_read_b128 v[182:185], v161 offset:1024
	ds_read_b128 v[186:189], v161 offset:2048
	ds_read_b128 v[190:193], v161 offset:3072
	ds_read_b128 v[194:197], v161 offset:4096
	ds_read_b128 v[198:201], v161 offset:5120
	ds_read_b128 v[202:205], v161 offset:6144
	ds_read_b128 v[206:209], v161 offset:7168
	global_load_lds_dwordx4 v[210:211], off
	v_lshl_add_u64 v[210:211], s[24:25], 0, v[146:147]
	s_add_i32 m0, s39, 0xe000
	s_nop 0
	global_load_lds_dwordx4 v[210:211], off
	s_waitcnt vmcnt(8)
	s_waitcnt lgkmcnt(0)
	s_barrier
; #define PG8_STAGEA(bufoff, gbase, voff) PG8_STAGE_X(bufoff, gbase, voff, AUXA)
; #define PG8_STAGEB(bufoff, gbase, voff) PG8_STAGE_X(bufoff, gbase, voff, AUXB)
; #define PG8_LDA(dst, b, h) do { _Pragma("unroll") for (int m = 0; m < 4; ++m) _Pragma("unroll") for (int k = 0; k < 2; ++k) dst[m][k] = *(const PG8_LAS bf16x8*)(lds + PG8_SA(b, h) + aoff + m * 2048 + k * 1024); } while (0)
; #define PG8_LDB(dst, b, h) do { _Pragma("unroll") for (int n = 0; n < 2; ++n) _Pragma("unroll") for (int k = 0; k < 2; ++k) dst[n][k] = *(const PG8_LAS bf16x8*)(lds + PG8_SB(b, h) + boff + n * 2048 + k * 1024); } while (0)
; #define PG8_MMA(ai, bj, At, Bt) do { if (GEMM_PRIO_MODE == 0) __builtin_amdgcn_s_setprio(1); PG8_MMA_LOOPS \
;         acc[ai][bj][m][n] = __builtin_amdgcn_mfma_f32_16x16x32_bf16(Bt[n][k], At[m][k], acc[ai][bj][m][n], 0, 0, 0); if (GEMM_PRIO_MODE == 0) __builtin_amdgcn_s_setprio(0); } while (0)
; #define PG8_WAIT_V(n) asm volatile("s_waitcnt vmcnt(" #n ")" ::: "memory")
;     ...
;             PG8_LDB(B0, 0, 0); PG8_LDB(B1, 0, 1); PG8_SCHED; PG8_LDA(At, 0, 0); PG8_STAGEA(PG8_SA(1, 1), a1 + hstepA, voffA);
;     ...
;             const int relax = __builtin_amdgcn_readfirstlane((t == 0 && ui > 0) ? 1 : 0);
;             PG8_WAIT_VR(8, 24, relax); PG8_WAIT_L(0); PG8_BAR; PG8_MMA(0, 0, At, B0); PG8_MMA(0, 1, At, B1); PG8_BAR; PG8_SCHED;
;     ...
;             PG8_WAIT_V(8); PG8_WAIT_L(0); PG8_BAR; PG8_MMA(0, 0, At, B0); PG8_MMA(0, 1, At, B1); PG8_BAR; PG8_SCHED;
;     ...
;             PG8_LDA(At, 0, 1); PG8_STAGEB(PG8_SB(0, 0), b2, voffB); PG8_STAGEB(PG8_SB(0, 1), b2 + hstepB, voffB); PG8_STAGEA(PG8_SA(0, 0), a2, voffA);
;     ...
;             PG8_WAIT_VR(8, 24, relax); PG8_WAIT_L(0); PG8_BAR; PG8_MMA(1, 0, At, B0); PG8_MMA(1, 1, At, B1); PG8_BAR; PG8_SCHED;
;     ...
;             PG8_WAIT_V(8); PG8_WAIT_L(0); PG8_BAR; PG8_MMA(1, 0, At, B0); PG8_MMA(1, 1, At, B1); PG8_BAR; PG8_SCHED;
;     ...
;             PG8_LDB(B0, 1, 0); PG8_LDB(B1, 1, 1); PG8_SCHED; PG8_LDA(At, 1, 0); PG8_STAGEA(PG8_SA(0, 1), a2 + hstepA, voffA);
;             PG8_WAIT_V(8); PG8_WAIT_L(0); PG8_BAR; PG8_MMA(0, 0, At, B0); PG8_MMA(0, 1, At, B1); PG8_BAR; PG8_SCHED;
;             PG8_LDA(At, 1, 1); PG8_STAGEB(PG8_SB(1, 0), b3, voffB); PG8_STAGEB(PG8_SB(1, 1), b3 + hstepB, voffB); PG8_STAGEA(PG8_SA(1, 0), a3, voffA);
;             PG8_WAIT_V(8); PG8_WAIT_L(0); PG8_BAR; PG8_MMA(1, 0, At, B0); PG8_MMA(1, 1, At, B1); PG8_BAR; PG8_SCHED;
	v_mfma_f32_16x16x32_bf16 v[126:129], v[130:133], v[178:181], v[126:129]
	v_mfma_f32_16x16x32_bf16 v[122:125], v[148:151], v[178:181], v[122:125]
	v_mfma_f32_16x16x32_bf16 v[110:113], v[130:133], v[186:189], v[110:113]
	v_mfma_f32_16x16x32_bf16 v[106:109], v[148:151], v[186:189], v[106:109]
	v_mfma_f32_16x16x32_bf16 v[94:97], v[130:133], v[194:197], v[94:97]
	v_mfma_f32_16x16x32_bf16 v[90:93], v[148:151], v[194:197], v[90:93]
	v_mfma_f32_16x16x32_bf16 v[78:81], v[130:133], v[202:205], v[78:81]
	v_mfma_f32_16x16x32_bf16 v[74:77], v[148:151], v[202:205], v[74:77]
	v_mfma_f32_16x16x32_bf16 v[126:129], v[134:137], v[182:185], v[126:129]
	v_mfma_f32_16x16x32_bf16 v[122:125], v[152:155], v[182:185], v[122:125]
	v_mfma_f32_16x16x32_bf16 v[110:113], v[134:137], v[190:193], v[110:113]
	v_mfma_f32_16x16x32_bf16 v[106:109], v[152:155], v[190:193], v[106:109]
	v_mfma_f32_16x16x32_bf16 v[94:97], v[134:137], v[198:201], v[94:97]
	v_mfma_f32_16x16x32_bf16 v[90:93], v[152:155], v[198:201], v[90:93]
	v_mfma_f32_16x16x32_bf16 v[78:81], v[134:137], v[206:209], v[78:81]
	v_mfma_f32_16x16x32_bf16 v[74:77], v[152:155], v[206:209], v[74:77]
	v_mfma_f32_16x16x32_bf16 v[118:121], v[162:165], v[178:181], v[118:121]
	v_mfma_f32_16x16x32_bf16 v[114:117], v[170:173], v[178:181], v[114:117]
	v_mfma_f32_16x16x32_bf16 v[102:105], v[162:165], v[186:189], v[102:105]
	v_mfma_f32_16x16x32_bf16 v[98:101], v[170:173], v[186:189], v[98:101]
	v_mfma_f32_16x16x32_bf16 v[86:89], v[162:165], v[194:197], v[86:89]
	v_mfma_f32_16x16x32_bf16 v[82:85], v[170:173], v[194:197], v[82:85]
	v_mfma_f32_16x16x32_bf16 v[70:73], v[162:165], v[202:205], v[70:73]
	v_mfma_f32_16x16x32_bf16 v[66:69], v[170:173], v[202:205], v[66:69]
	v_mfma_f32_16x16x32_bf16 v[118:121], v[166:169], v[182:185], v[118:121]
	v_mfma_f32_16x16x32_bf16 v[114:117], v[174:177], v[182:185], v[114:117]
	v_mfma_f32_16x16x32_bf16 v[102:105], v[166:169], v[190:193], v[102:105]
	v_mfma_f32_16x16x32_bf16 v[98:101], v[174:177], v[190:193], v[98:101]
	v_mfma_f32_16x16x32_bf16 v[86:89], v[166:169], v[198:201], v[86:89]
	v_mfma_f32_16x16x32_bf16 v[82:85], v[174:177], v[198:201], v[82:85]
	v_mfma_f32_16x16x32_bf16 v[70:73], v[166:169], v[206:209], v[70:73]
	v_mfma_f32_16x16x32_bf16 v[66:69], v[174:177], v[206:209], v[66:69]
	s_barrier
	s_add_i32 s83, s83, s38
	v_lshl_add_u64 v[210:211], s[16:17], 0, v[16:17]
	s_mov_b32 m0, s83
	ds_read_b128 v[178:181], v161 offset:16384
	ds_read_b128 v[182:185], v161 offset:17408
	ds_read_b128 v[186:189], v161 offset:18432
	ds_read_b128 v[190:193], v161 offset:19456
	ds_read_b128 v[194:197], v161 offset:20480
	ds_read_b128 v[198:201], v161 offset:21504
	ds_read_b128 v[202:205], v161 offset:22528
	ds_read_b128 v[206:209], v161 offset:23552
	global_load_lds_dwordx4 v[210:211], off
	s_add_i32 m0, s83, 0x2000
	s_add_u32 s90, s16, 0x4000
	v_lshl_add_u64 v[210:211], s[16:17], 0, v[138:139]
	s_addc_u32 s91, s17, 0
	s_add_i32 s83, s94, s38
	global_load_lds_dwordx4 v[210:211], off
	v_lshl_add_u64 v[210:211], s[90:91], 0, v[16:17]
	s_mov_b32 m0, s83
	s_nop 0
	global_load_lds_dwordx4 v[210:211], off
	v_lshl_add_u64 v[210:211], s[90:91], 0, v[138:139]
	s_add_i32 m0, s83, 0x2000
	s_nop 0
	global_load_lds_dwordx4 v[210:211], off
	v_lshl_add_u64 v[210:211], s[36:37], 0, v[142:143]
	s_mov_b32 m0, s39
	s_nop 0
	global_load_lds_dwordx4 v[210:211], off
	v_lshl_add_u64 v[210:211], s[36:37], 0, v[140:141]
	s_mov_b32 m0, s40
	s_nop 0
	global_load_lds_dwordx4 v[210:211], off
	s_waitcnt vmcnt(8)
	s_waitcnt lgkmcnt(0)
	s_barrier
	v_mfma_f32_16x16x32_bf16 v[62:65], v[130:133], v[178:181], v[62:65]
	v_mfma_f32_16x16x32_bf16 v[58:61], v[148:151], v[178:181], v[58:61]
	v_mfma_f32_16x16x32_bf16 v[46:49], v[130:133], v[186:189], v[46:49]
	v_mfma_f32_16x16x32_bf16 v[42:45], v[148:151], v[186:189], v[42:45]
	v_mfma_f32_16x16x32_bf16 v[30:33], v[130:133], v[194:197], v[30:33]
	v_mfma_f32_16x16x32_bf16 v[26:29], v[148:151], v[194:197], v[26:29]
	v_mfma_f32_16x16x32_bf16 v[12:15], v[130:133], v[202:205], v[12:15]
	v_mfma_f32_16x16x32_bf16 v[8:11], v[148:151], v[202:205], v[8:11]
	v_mfma_f32_16x16x32_bf16 v[62:65], v[134:137], v[182:185], v[62:65]
	v_mfma_f32_16x16x32_bf16 v[58:61], v[152:155], v[182:185], v[58:61]
	v_mfma_f32_16x16x32_bf16 v[46:49], v[134:137], v[190:193], v[46:49]
	v_mfma_f32_16x16x32_bf16 v[42:45], v[152:155], v[190:193], v[42:45]
	v_mfma_f32_16x16x32_bf16 v[30:33], v[134:137], v[198:201], v[30:33]
	v_mfma_f32_16x16x32_bf16 v[26:29], v[152:155], v[198:201], v[26:29]
	v_mfma_f32_16x16x32_bf16 v[12:15], v[134:137], v[206:209], v[12:15]
	v_mfma_f32_16x16x32_bf16 v[8:11], v[152:155], v[206:209], v[8:11]
	v_mfma_f32_16x16x32_bf16 v[54:57], v[162:165], v[178:181], v[54:57]
	v_mfma_f32_16x16x32_bf16 v[50:53], v[170:173], v[178:181], v[50:53]
	v_mfma_f32_16x16x32_bf16 v[38:41], v[162:165], v[186:189], v[38:41]
	v_mfma_f32_16x16x32_bf16 v[34:37], v[170:173], v[186:189], v[34:37]
	v_mfma_f32_16x16x32_bf16 v[22:25], v[162:165], v[194:197], v[22:25]
	v_mfma_f32_16x16x32_bf16 v[18:21], v[170:173], v[194:197], v[18:21]
	v_mfma_f32_16x16x32_bf16 v[4:7], v[162:165], v[202:205], v[4:7]
	v_mfma_f32_16x16x32_bf16 v[0:3], v[170:173], v[202:205], v[0:3]
	v_mfma_f32_16x16x32_bf16 v[54:57], v[166:169], v[182:185], v[54:57]
	v_mfma_f32_16x16x32_bf16 v[50:53], v[174:177], v[182:185], v[50:53]
	v_mfma_f32_16x16x32_bf16 v[38:41], v[166:169], v[190:193], v[38:41]
	v_mfma_f32_16x16x32_bf16 v[34:37], v[174:177], v[190:193], v[34:37]
	v_mfma_f32_16x16x32_bf16 v[22:25], v[166:169], v[198:201], v[22:25]
	v_mfma_f32_16x16x32_bf16 v[18:21], v[174:177], v[198:201], v[18:21]
	v_mfma_f32_16x16x32_bf16 v[4:7], v[166:169], v[206:209], v[4:7]
	v_mfma_f32_16x16x32_bf16 v[0:3], v[174:177], v[206:209], v[0:3]
	s_barrier
; #define PG8_STAGEA(bufoff, gbase, voff) PG8_STAGE_X(bufoff, gbase, voff, AUXA)
; #define PG8_STAGEB(bufoff, gbase, voff) PG8_STAGE_X(bufoff, gbase, voff, AUXB)
; #define PG8_LDA(dst, b, h) do { _Pragma("unroll") for (int m = 0; m < 4; ++m) _Pragma("unroll") for (int k = 0; k < 2; ++k) dst[m][k] = *(const PG8_LAS bf16x8*)(lds + PG8_SA(b, h) + aoff + m * 2048 + k * 1024); } while (0)
; #define PG8_LDB(dst, b, h) do { _Pragma("unroll") for (int n = 0; n < 2; ++n) _Pragma("unroll") for (int k = 0; k < 2; ++k) dst[n][k] = *(const PG8_LAS bf16x8*)(lds + PG8_SB(b, h) + boff + n * 2048 + k * 1024); } while (0)
; #define PG8_MMA(ai, bj, At, Bt) do { if (GEMM_PRIO_MODE == 0) __builtin_amdgcn_s_setprio(1); PG8_MMA_LOOPS \
;         acc[ai][bj][m][n] = __builtin_amdgcn_mfma_f32_16x16x32_bf16(Bt[n][k], At[m][k], acc[ai][bj][m][n], 0, 0, 0); if (GEMM_PRIO_MODE == 0) __builtin_amdgcn_s_setprio(0); } while (0)
; #define PG8_WAIT_V(n) asm volatile("s_waitcnt vmcnt(" #n ")" ::: "memory")
; #define PG8_WAIT_VR(n, nr, flag) asm volatile("s_cmp_eq_u32 %0, 0\n\ts_cbranch_scc1 .Lpg8s%=\n\ts_waitcnt vmcnt(" #nr ")\n\ts_branch .Lpg8d%=\n.Lpg8s%=:\n\ts_waitcnt vmcnt(" #n ")\n.Lpg8d%=:" :: "s"(flag) : "memory", "scc")
; #define PG8_WAIT_L(n) asm volatile("s_waitcnt lgkmcnt(" #n ")" ::: "memory")
; #define PG8_BAR __builtin_amdgcn_s_barrier()
; #define PG8_SCHED __builtin_amdgcn_sched_barrier(0)
;     ...
;             PG8_LDA(At, 0, 1); PG8_STAGEB(PG8_SB(0, 0), b2, voffB); PG8_STAGEB(PG8_SB(0, 1), b2 + hstepB, voffB); PG8_STAGEA(PG8_SA(0, 0), a2, voffA);
;     ...
;             PG8_WAIT_VR(8, 24, relax); PG8_WAIT_L(0); PG8_BAR; PG8_MMA(1, 0, At, B0); PG8_MMA(1, 1, At, B1); PG8_BAR; PG8_SCHED;
;     ...
;             PG8_WAIT_V(8); PG8_WAIT_L(0); PG8_BAR; PG8_MMA(1, 0, At, B0); PG8_MMA(1, 1, At, B1); PG8_BAR; PG8_SCHED;
;     ...
;             PG8_LDB(B0, 1, 0); PG8_LDB(B1, 1, 1); PG8_SCHED; PG8_LDA(At, 1, 0); PG8_STAGEA(PG8_SA(0, 1), a2 + hstepA, voffA);
;             PG8_WAIT_V(8); PG8_WAIT_L(0); PG8_BAR; PG8_MMA(0, 0, At, B0); PG8_MMA(0, 1, At, B1); PG8_BAR; PG8_SCHED;
;             PG8_LDA(At, 1, 1); PG8_STAGEB(PG8_SB(1, 0), b3, voffB); PG8_STAGEB(PG8_SB(1, 1), b3 + hstepB, voffB); PG8_STAGEA(PG8_SA(1, 0), a3, voffA);
;             PG8_WAIT_V(8); PG8_WAIT_L(0); PG8_BAR; PG8_MMA(1, 0, At, B0); PG8_MMA(1, 1, At, B1); PG8_BAR; PG8_SCHED;
	s_add_i32 s83, 0, 0x18000
	s_add_i32 s90, 0, 0x1c000
	v_add_u32_e32 v152, s83, v157
	v_add_u32_e32 v174, s90, v157
	ds_read_b128 v[130:133], v152
	ds_read_b128 v[134:137], v152 offset:1024
	ds_read_b128 v[148:151], v152 offset:2048
	ds_read_b128 v[152:155], v152 offset:3072
	ds_read_b128 v[162:165], v174
	ds_read_b128 v[166:169], v174 offset:1024
	ds_read_b128 v[170:173], v174 offset:2048
	ds_read_b128 v[174:177], v174 offset:3072
	s_add_u32 s36, s36, 0x4000
	s_addc_u32 s37, s37, 0
	s_mov_b32 m0, s41
	v_lshl_add_u64 v[210:211], s[36:37], 0, v[142:143]
	ds_read_b128 v[178:181], v161 offset:32768
	ds_read_b128 v[182:185], v161 offset:33792
	ds_read_b128 v[186:189], v161 offset:34816
	ds_read_b128 v[190:193], v161 offset:35840
	ds_read_b128 v[194:197], v161 offset:36864
	ds_read_b128 v[198:201], v161 offset:37888
	ds_read_b128 v[202:205], v161 offset:38912
	ds_read_b128 v[206:209], v161 offset:39936
	global_load_lds_dwordx4 v[210:211], off
	v_lshl_add_u64 v[210:211], s[36:37], 0, v[140:141]
	s_mov_b32 m0, s42
	s_nop 0
	global_load_lds_dwordx4 v[210:211], off
	s_waitcnt vmcnt(8)
	s_waitcnt lgkmcnt(0)
	s_barrier
	v_mfma_f32_16x16x32_bf16 v[126:129], v[130:133], v[178:181], v[126:129]
	v_mfma_f32_16x16x32_bf16 v[122:125], v[148:151], v[178:181], v[122:125]
	v_mfma_f32_16x16x32_bf16 v[110:113], v[130:133], v[186:189], v[110:113]
	v_mfma_f32_16x16x32_bf16 v[106:109], v[148:151], v[186:189], v[106:109]
	v_mfma_f32_16x16x32_bf16 v[94:97], v[130:133], v[194:197], v[94:97]
	v_mfma_f32_16x16x32_bf16 v[90:93], v[148:151], v[194:197], v[90:93]
	v_mfma_f32_16x16x32_bf16 v[78:81], v[130:133], v[202:205], v[78:81]
	v_mfma_f32_16x16x32_bf16 v[74:77], v[148:151], v[202:205], v[74:77]
	v_mfma_f32_16x16x32_bf16 v[126:129], v[134:137], v[182:185], v[126:129]
	v_mfma_f32_16x16x32_bf16 v[122:125], v[152:155], v[182:185], v[122:125]
	v_mfma_f32_16x16x32_bf16 v[110:113], v[134:137], v[190:193], v[110:113]
	v_mfma_f32_16x16x32_bf16 v[106:109], v[152:155], v[190:193], v[106:109]
	v_mfma_f32_16x16x32_bf16 v[94:97], v[134:137], v[198:201], v[94:97]
	v_mfma_f32_16x16x32_bf16 v[90:93], v[152:155], v[198:201], v[90:93]
	v_mfma_f32_16x16x32_bf16 v[78:81], v[134:137], v[206:209], v[78:81]
	v_mfma_f32_16x16x32_bf16 v[74:77], v[152:155], v[206:209], v[74:77]
	v_mfma_f32_16x16x32_bf16 v[118:121], v[162:165], v[178:181], v[118:121]
	v_mfma_f32_16x16x32_bf16 v[114:117], v[170:173], v[178:181], v[114:117]
	v_mfma_f32_16x16x32_bf16 v[102:105], v[162:165], v[186:189], v[102:105]
	v_mfma_f32_16x16x32_bf16 v[98:101], v[170:173], v[186:189], v[98:101]
	v_mfma_f32_16x16x32_bf16 v[86:89], v[162:165], v[194:197], v[86:89]
	v_mfma_f32_16x16x32_bf16 v[82:85], v[170:173], v[194:197], v[82:85]
	v_mfma_f32_16x16x32_bf16 v[70:73], v[162:165], v[202:205], v[70:73]
	v_mfma_f32_16x16x32_bf16 v[66:69], v[170:173], v[202:205], v[66:69]
	v_mfma_f32_16x16x32_bf16 v[118:121], v[166:169], v[182:185], v[118:121]
	v_mfma_f32_16x16x32_bf16 v[114:117], v[174:177], v[182:185], v[114:117]
	v_mfma_f32_16x16x32_bf16 v[102:105], v[166:169], v[190:193], v[102:105]
	v_mfma_f32_16x16x32_bf16 v[98:101], v[174:177], v[190:193], v[98:101]
	v_mfma_f32_16x16x32_bf16 v[86:89], v[166:169], v[198:201], v[86:89]
	v_mfma_f32_16x16x32_bf16 v[82:85], v[174:177], v[198:201], v[82:85]
	v_mfma_f32_16x16x32_bf16 v[70:73], v[166:169], v[206:209], v[70:73]
	v_mfma_f32_16x16x32_bf16 v[66:69], v[174:177], v[206:209], v[66:69]
	s_barrier
; #define PG8_STAGEA(bufoff, gbase, voff) PG8_STAGE_X(bufoff, gbase, voff, AUXA)
; #define PG8_STAGEB(bufoff, gbase, voff) PG8_STAGE_X(bufoff, gbase, voff, AUXB)
; #define PG8_LDA(dst, b, h) do { _Pragma("unroll") for (int m = 0; m < 4; ++m) _Pragma("unroll") for (int k = 0; k < 2; ++k) dst[m][k] = *(const PG8_LAS bf16x8*)(lds + PG8_SA(b, h) + aoff + m * 2048 + k * 1024); } while (0)
; #define PG8_WAIT_V(n) asm volatile("s_waitcnt vmcnt(" #n ")" ::: "memory")
; #define PG8_BAR __builtin_amdgcn_s_barrier()
;     ...
;             PG8_LDB(B0, 1, 0); PG8_LDB(B1, 1, 1); PG8_SCHED; PG8_LDA(At, 1, 0); PG8_STAGEA(PG8_SA(0, 1), a2 + hstepA, voffA);
;             PG8_WAIT_V(8); PG8_WAIT_L(0); PG8_BAR; PG8_MMA(0, 0, At, B0); PG8_MMA(0, 1, At, B1); PG8_BAR; PG8_SCHED;
;             PG8_LDA(At, 1, 1); PG8_STAGEB(PG8_SB(1, 0), b3, voffB); PG8_STAGEB(PG8_SB(1, 1), b3 + hstepB, voffB); PG8_STAGEA(PG8_SA(1, 0), a3, voffA);
;             PG8_WAIT_V(8); PG8_WAIT_L(0); PG8_BAR; PG8_MMA(1, 0, At, B0); PG8_MMA(1, 1, At, B1); PG8_BAR; PG8_SCHED;
;             } else {
;             PG8_LDB(B0, 0, 0); PG8_SCHED; PG8_LDA(At, 0, 0); PG8_STAGEA(PG8_SA(1, 1), a1 + hstepA, voffA);
;             PG8_WAIT_L(8); PG8_BAR; PG8_WAIT_L(0); PG8_MMA(0, 0, At, B0); PG8_BAR; PG8_SCHED;
;             PG8_LDB(B1, 0, 1); PG8_STAGEB(PG8_SB(0, 0), b2, voffB);
;             PG8_BAR; PG8_WAIT_L(0); PG8_MMA(0, 1, At, B1); PG8_BAR;
;             PG8_LDA(At, 0, 1); PG8_STAGEA(PG8_SA(0, 0), a2, voffA);
;             PG8_BAR; PG8_WAIT_L(0); PG8_MMA(1, 0, At, B0); PG8_BAR; PG8_SCHED;
;             PG8_STAGEB(PG8_SB(0, 1), b2 + hstepB, voffB);
;             PG8_WAIT_V(6); PG8_BAR; PG8_MMA(1, 1, At, B1); PG8_BAR;
;             PG8_LDB(B0, 1, 0); PG8_SCHED; PG8_LDA(At, 1, 0); PG8_STAGEA(PG8_SA(0, 1), a2 + hstepA, voffA);
;             PG8_WAIT_L(8); PG8_BAR; PG8_WAIT_L(0); PG8_MMA(0, 0, At, B0); PG8_BAR; PG8_SCHED;
;             PG8_LDB(B1, 1, 1); PG8_STAGEB(PG8_SB(1, 0), b3, voffB);
;             PG8_BAR; PG8_WAIT_L(0); PG8_MMA(0, 1, At, B1); PG8_BAR;
;             PG8_LDA(At, 1, 1); PG8_STAGEA(PG8_SA(1, 0), a3, voffA);
;             PG8_BAR; PG8_WAIT_L(0); PG8_MMA(1, 0, At, B0); PG8_BAR; PG8_SCHED;
;             PG8_STAGEB(PG8_SB(1, 1), b3 + hstepB, voffB);
;             PG8_WAIT_V(6); PG8_BAR; PG8_MMA(1, 1, At, B1); PG8_BAR;
;             }
;         }
;         if constexpr (ALIGN_EPI) { if (wr == 0) PG8_BAR; }
	s_add_u32 s36, s16, 0x8000
	s_addc_u32 s37, s17, 0
	s_add_i32 s83, s83, s38
	v_lshl_add_u64 v[210:211], s[36:37], 0, v[16:17]
	s_mov_b32 m0, s83
	ds_read_b128 v[178:181], v161 offset:49152
	ds_read_b128 v[182:185], v161 offset:50176
	ds_read_b128 v[186:189], v161 offset:51200
	ds_read_b128 v[190:193], v161 offset:52224
	ds_read_b128 v[194:197], v161 offset:53248
	ds_read_b128 v[198:201], v161 offset:54272
	ds_read_b128 v[202:205], v161 offset:55296
	ds_read_b128 v[206:209], v161 offset:56320
	global_load_lds_dwordx4 v[210:211], off
	s_add_i32 m0, s83, 0x2000
	s_add_u32 s16, s16, 0xc000
	v_lshl_add_u64 v[210:211], s[36:37], 0, v[138:139]
	s_addc_u32 s17, s17, 0
	s_add_i32 s36, s90, s38
	global_load_lds_dwordx4 v[210:211], off
	v_lshl_add_u64 v[210:211], s[16:17], 0, v[16:17]
	s_mov_b32 m0, s36
	s_nop 0
	global_load_lds_dwordx4 v[210:211], off
	v_lshl_add_u64 v[210:211], s[16:17], 0, v[138:139]
	s_add_i32 m0, s36, 0x2000
	s_nop 0
	global_load_lds_dwordx4 v[210:211], off
	v_lshl_add_u64 v[210:211], s[26:27], 0, v[142:143]
	s_mov_b32 m0, s50
	s_nop 0
	global_load_lds_dwordx4 v[210:211], off
	v_lshl_add_u64 v[210:211], s[26:27], 0, v[140:141]
	s_mov_b32 m0, s51
	s_nop 0
	global_load_lds_dwordx4 v[210:211], off
	s_waitcnt vmcnt(8)
	s_waitcnt lgkmcnt(0)
	s_barrier
	v_mfma_f32_16x16x32_bf16 v[62:65], v[130:133], v[178:181], v[62:65]
	v_mfma_f32_16x16x32_bf16 v[58:61], v[148:151], v[178:181], v[58:61]
	v_mfma_f32_16x16x32_bf16 v[46:49], v[130:133], v[186:189], v[46:49]
	v_mfma_f32_16x16x32_bf16 v[42:45], v[148:151], v[186:189], v[42:45]
	v_mfma_f32_16x16x32_bf16 v[30:33], v[130:133], v[194:197], v[30:33]
	v_mfma_f32_16x16x32_bf16 v[26:29], v[148:151], v[194:197], v[26:29]
	v_mfma_f32_16x16x32_bf16 v[12:15], v[130:133], v[202:205], v[12:15]
	v_mfma_f32_16x16x32_bf16 v[8:11], v[148:151], v[202:205], v[8:11]
	v_mfma_f32_16x16x32_bf16 v[62:65], v[134:137], v[182:185], v[62:65]
	v_mfma_f32_16x16x32_bf16 v[58:61], v[152:155], v[182:185], v[58:61]
	v_mfma_f32_16x16x32_bf16 v[46:49], v[134:137], v[190:193], v[46:49]
	v_mfma_f32_16x16x32_bf16 v[42:45], v[152:155], v[190:193], v[42:45]
	v_mfma_f32_16x16x32_bf16 v[30:33], v[134:137], v[198:201], v[30:33]
	v_mfma_f32_16x16x32_bf16 v[26:29], v[152:155], v[198:201], v[26:29]
	v_mfma_f32_16x16x32_bf16 v[12:15], v[134:137], v[206:209], v[12:15]
	v_mfma_f32_16x16x32_bf16 v[8:11], v[152:155], v[206:209], v[8:11]
	v_mfma_f32_16x16x32_bf16 v[54:57], v[162:165], v[178:181], v[54:57]
	v_mfma_f32_16x16x32_bf16 v[50:53], v[170:173], v[178:181], v[50:53]
	v_mfma_f32_16x16x32_bf16 v[38:41], v[162:165], v[186:189], v[38:41]
	v_mfma_f32_16x16x32_bf16 v[34:37], v[170:173], v[186:189], v[34:37]
	v_mfma_f32_16x16x32_bf16 v[22:25], v[162:165], v[194:197], v[22:25]
	v_mfma_f32_16x16x32_bf16 v[18:21], v[170:173], v[194:197], v[18:21]
	v_mfma_f32_16x16x32_bf16 v[4:7], v[162:165], v[202:205], v[4:7]
	v_mfma_f32_16x16x32_bf16 v[0:3], v[170:173], v[202:205], v[0:3]
	v_mfma_f32_16x16x32_bf16 v[54:57], v[166:169], v[182:185], v[54:57]
	v_mfma_f32_16x16x32_bf16 v[50:53], v[174:177], v[182:185], v[50:53]
	v_mfma_f32_16x16x32_bf16 v[38:41], v[166:169], v[190:193], v[38:41]
	v_mfma_f32_16x16x32_bf16 v[34:37], v[174:177], v[190:193], v[34:37]
	v_mfma_f32_16x16x32_bf16 v[22:25], v[166:169], v[198:201], v[22:25]
	v_mfma_f32_16x16x32_bf16 v[18:21], v[174:177], v[198:201], v[18:21]
	v_mfma_f32_16x16x32_bf16 v[4:7], v[166:169], v[206:209], v[4:7]
	v_mfma_f32_16x16x32_bf16 v[0:3], v[174:177], v[206:209], v[0:3]
	s_barrier
	s_add_i32 s82, s82, 2
	s_add_u32 s24, s24, 0x10000
	s_addc_u32 s25, s25, 0
	s_add_u32 s0, s0, 0x10000
	s_addc_u32 s1, s1, 0
	s_cmpk_gt_u32 s82, 0xfd
	s_cbranch_scc0 .LBB0_848
	s_setprio 0
	s_and_b64 vcc, exec, s[8:9]
	s_cbranch_vccz .LBB0_851
	s_barrier
